# v96 + per-phase s_setprio flips in the 8 GEMM K-loops replaced by s_nop 0
# baseline (speedup 1.0000x reference)
; #define PG8_STAGE(bufoff, gbase, voff) do { _Pragma("unroll") for (int _i = 0; _i < 2; ++_i) \
;         __builtin_amdgcn_global_load_lds((const unsigned*)((const char*)(gbase) + (voff)[_i]), (PG8_LAS unsigned*)(lds + (bufoff) + ldsw + _i * 8192), 16, 0, 0); } while (0)
; #define PG8_LDA(dst, b, h) do { _Pragma("unroll") for (int m = 0; m < 4; ++m) _Pragma("unroll") for (int k = 0; k < 2; ++k) dst[m][k] = *(const PG8_LAS bf16x8*)(lds + PG8_SA(b, h) + aoff + m * 2048 + k * 1024); } while (0)
; #define PG8_LDB(dst, b, h) do { _Pragma("unroll") for (int n = 0; n < 2; ++n) _Pragma("unroll") for (int k = 0; k < 2; ++k) dst[n][k] = *(const PG8_LAS bf16x8*)(lds + PG8_SB(b, h) + boff + n * 2048 + k * 1024); } while (0)
; #define PG8_MMA(ai, bj, At, Bt) do { __builtin_amdgcn_s_setprio(1); _Pragma("unroll") for (int m = 0; m < 4; ++m) _Pragma("unroll") for (int n = 0; n < 2; ++n) _Pragma("unroll") for (int k = 0; k < 2; ++k) \
;         acc[ai][bj][m][n] = __builtin_amdgcn_mfma_f32_16x16x32_bf16(Bt[n][k], At[m][k], acc[ai][bj][m][n], 0, 0, 0); __builtin_amdgcn_s_setprio(0); } while (0)
; #define PG8_WAIT_V(n) asm volatile("s_waitcnt vmcnt(" #n ")" ::: "memory")
; #define PG8_WAIT_L(n) asm volatile("s_waitcnt lgkmcnt(" #n ")" ::: "memory")
; #define PG8_BAR __builtin_amdgcn_s_barrier()
; #define PG8_SCHED __builtin_amdgcn_sched_barrier(0)
; template <class Epi, class Sched>
; __device__ __forceinline__ void gemm_phase(PG8_LAS unsigned char* lds, const Gemm g, const Sched& S, const Epi& E, const int tid) {
;     ...
;             PG8_LDB(B0, 0, 0); PG8_LDB(B1, 0, 1); PG8_SCHED; PG8_LDA(At, 0, 0); PG8_STAGE(PG8_SA(1, 1), a1 + hstepA, voffA);
;             PG8_WAIT_V(8); PG8_WAIT_L(0); PG8_BAR; PG8_MMA(0, 0, At, B0); PG8_MMA(0, 1, At, B1); PG8_BAR; PG8_SCHED;
;             PG8_LDA(At, 0, 1); PG8_STAGE(PG8_SB(0, 0), b2, voffB); PG8_STAGE(PG8_SB(0, 1), b2 + hstepB, voffB); PG8_STAGE(PG8_SA(0, 0), a2, voffA);
;             PG8_WAIT_V(8); PG8_WAIT_L(0); PG8_BAR; PG8_MMA(1, 0, At, B0); PG8_MMA(1, 1, At, B1); PG8_BAR; PG8_SCHED;
.LBB0_183:
	s_add_u32 s16, s42, 0xfffc0080
	s_addc_u32 s30, s43, -1
	s_add_i32 s33, 0, 0x10000
	s_cmp_eq_u32 s23, 12
	s_cselect_b32 s49, s17, s30
	s_cselect_b32 s48, s19, s16
	s_cselect_b32 s47, s15, s22
	s_cselect_b32 s46, s20, s21
	s_add_i32 s16, 0, 0x14000
	v_add_u32_e32 v44, s33, v202
	v_add_u32_e32 v156, s16, v202
	ds_read_b128 v[32:35], v44
	ds_read_b128 v[36:39], v44 offset:1024
	ds_read_b128 v[40:43], v44 offset:2048
	ds_read_b128 v[44:47], v44 offset:3072
	ds_read_b128 v[144:147], v156
	ds_read_b128 v[148:151], v156 offset:1024
	ds_read_b128 v[152:155], v156 offset:2048
	ds_read_b128 v[156:159], v156 offset:3072
	v_lshl_add_u64 v[210:211], s[42:43], 0, v[176:177]
	s_add_i32 m0, s58, 0xc000
	ds_read_b128 v[160:163], v204
	ds_read_b128 v[164:167], v204 offset:1024
	ds_read_b128 v[180:183], v204 offset:2048
	ds_read_b128 v[184:187], v204 offset:3072
	ds_read_b128 v[188:191], v204 offset:4096
	ds_read_b128 v[192:195], v204 offset:5120
	ds_read_b128 v[196:199], v204 offset:6144
	ds_read_b128 v[206:209], v204 offset:7168
	global_load_lds_dwordx4 v[210:211], off
	v_lshl_add_u64 v[210:211], s[42:43], 0, v[178:179]
	s_add_i32 m0, s58, 0xe000
	s_nop 0
	global_load_lds_dwordx4 v[210:211], off
	s_waitcnt vmcnt(8)
	s_waitcnt lgkmcnt(0)
	s_barrier
	s_nop 0
	s_waitcnt lgkmcnt(0)
	v_mfma_f32_16x16x32_bf16 v[140:143], v[32:35], v[160:163], v[140:143]
	v_mfma_f32_16x16x32_bf16 v[136:139], v[40:43], v[160:163], v[136:139]
	v_mfma_f32_16x16x32_bf16 v[124:127], v[32:35], v[180:183], v[124:127]
	v_mfma_f32_16x16x32_bf16 v[120:123], v[40:43], v[180:183], v[120:123]
	v_mfma_f32_16x16x32_bf16 v[108:111], v[32:35], v[188:191], v[108:111]
	v_mfma_f32_16x16x32_bf16 v[104:107], v[40:43], v[188:191], v[104:107]
	v_mfma_f32_16x16x32_bf16 v[92:95], v[32:35], v[196:199], v[92:95]
	v_mfma_f32_16x16x32_bf16 v[88:91], v[40:43], v[196:199], v[88:91]
	v_mfma_f32_16x16x32_bf16 v[140:143], v[36:39], v[164:167], v[140:143]
	v_mfma_f32_16x16x32_bf16 v[136:139], v[44:47], v[164:167], v[136:139]
	v_mfma_f32_16x16x32_bf16 v[124:127], v[36:39], v[184:187], v[124:127]
	v_mfma_f32_16x16x32_bf16 v[120:123], v[44:47], v[184:187], v[120:123]
	v_mfma_f32_16x16x32_bf16 v[108:111], v[36:39], v[192:195], v[108:111]
	v_mfma_f32_16x16x32_bf16 v[104:107], v[44:47], v[192:195], v[104:107]
	v_mfma_f32_16x16x32_bf16 v[92:95], v[36:39], v[206:209], v[92:95]
	v_mfma_f32_16x16x32_bf16 v[88:91], v[44:47], v[206:209], v[88:91]
	s_nop 0
	s_nop 0
	v_mfma_f32_16x16x32_bf16 v[132:135], v[144:147], v[160:163], v[132:135]
	v_mfma_f32_16x16x32_bf16 v[128:131], v[152:155], v[160:163], v[128:131]
	v_mfma_f32_16x16x32_bf16 v[116:119], v[144:147], v[180:183], v[116:119]
	v_mfma_f32_16x16x32_bf16 v[112:115], v[152:155], v[180:183], v[112:115]
	v_mfma_f32_16x16x32_bf16 v[100:103], v[144:147], v[188:191], v[100:103]
	v_mfma_f32_16x16x32_bf16 v[96:99], v[152:155], v[188:191], v[96:99]
	v_mfma_f32_16x16x32_bf16 v[84:87], v[144:147], v[196:199], v[84:87]
	v_mfma_f32_16x16x32_bf16 v[80:83], v[152:155], v[196:199], v[80:83]
	v_mfma_f32_16x16x32_bf16 v[132:135], v[148:151], v[164:167], v[132:135]
	v_mfma_f32_16x16x32_bf16 v[128:131], v[156:159], v[164:167], v[128:131]
	v_mfma_f32_16x16x32_bf16 v[116:119], v[148:151], v[184:187], v[116:119]
	v_mfma_f32_16x16x32_bf16 v[112:115], v[156:159], v[184:187], v[112:115]
	v_mfma_f32_16x16x32_bf16 v[100:103], v[148:151], v[192:195], v[100:103]
	v_mfma_f32_16x16x32_bf16 v[96:99], v[156:159], v[192:195], v[96:99]
	v_mfma_f32_16x16x32_bf16 v[84:87], v[148:151], v[206:209], v[84:87]
	v_mfma_f32_16x16x32_bf16 v[80:83], v[156:159], v[206:209], v[80:83]
	s_nop 0
	s_barrier
	s_add_i32 s30, s33, s57
	v_lshl_add_u64 v[210:211], s[46:47], 0, v[212:213]
	s_mov_b32 m0, s30
	ds_read_b128 v[160:163], v204 offset:16384
	ds_read_b128 v[164:167], v204 offset:17408
	ds_read_b128 v[180:183], v204 offset:18432
	ds_read_b128 v[184:187], v204 offset:19456
	ds_read_b128 v[188:191], v204 offset:20480
	ds_read_b128 v[192:195], v204 offset:21504
	ds_read_b128 v[196:199], v204 offset:22528
	ds_read_b128 v[206:209], v204 offset:23552
	global_load_lds_dwordx4 v[210:211], off
	s_add_i32 m0, s30, 0x2000
	s_add_u32 s52, s46, 0x40000
	v_lshl_add_u64 v[216:217], s[46:47], 0, v[172:173]
	s_addc_u32 s53, s47, 0
	s_add_i32 s16, s16, s57
	global_load_lds_dwordx4 v[216:217], off
	v_lshl_add_u64 v[218:219], s[52:53], 0, v[212:213]
	s_mov_b32 m0, s16
	v_lshl_add_u64 v[220:221], s[48:49], 0, v[170:171]
	global_load_lds_dwordx4 v[218:219], off
	v_lshl_add_u64 v[218:219], s[52:53], 0, v[172:173]
	s_add_i32 m0, s16, 0x2000
	s_nop 0
	global_load_lds_dwordx4 v[218:219], off
	v_lshl_add_u64 v[218:219], s[48:49], 0, v[168:169]
	s_mov_b32 m0, s58
	s_nop 0
	global_load_lds_dwordx4 v[218:219], off
	s_mov_b32 m0, s59
	s_nop 0
	global_load_lds_dwordx4 v[220:221], off
	s_waitcnt vmcnt(8)
	s_waitcnt lgkmcnt(0)
	s_barrier
; #define PG8_STAGE(bufoff, gbase, voff) do { _Pragma("unroll") for (int _i = 0; _i < 2; ++_i) \
;         __builtin_amdgcn_global_load_lds((const unsigned*)((const char*)(gbase) + (voff)[_i]), (PG8_LAS unsigned*)(lds + (bufoff) + ldsw + _i * 8192), 16, 0, 0); } while (0)
; #define PG8_LDA(dst, b, h) do { _Pragma("unroll") for (int m = 0; m < 4; ++m) _Pragma("unroll") for (int k = 0; k < 2; ++k) dst[m][k] = *(const PG8_LAS bf16x8*)(lds + PG8_SA(b, h) + aoff + m * 2048 + k * 1024); } while (0)
; #define PG8_LDB(dst, b, h) do { _Pragma("unroll") for (int n = 0; n < 2; ++n) _Pragma("unroll") for (int k = 0; k < 2; ++k) dst[n][k] = *(const PG8_LAS bf16x8*)(lds + PG8_SB(b, h) + boff + n * 2048 + k * 1024); } while (0)
; #define PG8_MMA(ai, bj, At, Bt) do { __builtin_amdgcn_s_setprio(1); _Pragma("unroll") for (int m = 0; m < 4; ++m) _Pragma("unroll") for (int n = 0; n < 2; ++n) _Pragma("unroll") for (int k = 0; k < 2; ++k) \
;         acc[ai][bj][m][n] = __builtin_amdgcn_mfma_f32_16x16x32_bf16(Bt[n][k], At[m][k], acc[ai][bj][m][n], 0, 0, 0); __builtin_amdgcn_s_setprio(0); } while (0)
; #define PG8_WAIT_V(n) asm volatile("s_waitcnt vmcnt(" #n ")" ::: "memory")
; #define PG8_WAIT_L(n) asm volatile("s_waitcnt lgkmcnt(" #n ")" ::: "memory")
; #define PG8_BAR __builtin_amdgcn_s_barrier()
; #define PG8_SCHED __builtin_amdgcn_sched_barrier(0)
; template <class Epi, class Sched>
; __device__ __forceinline__ void gemm_phase(PG8_LAS unsigned char* lds, const Gemm g, const Sched& S, const Epi& E, const int tid) {
;     ...
;             PG8_WAIT_V(8); PG8_WAIT_L(0); PG8_BAR; PG8_MMA(1, 0, At, B0); PG8_MMA(1, 1, At, B1); PG8_BAR; PG8_SCHED;
;             PG8_LDB(B0, 1, 0); PG8_LDB(B1, 1, 1); PG8_SCHED; PG8_LDA(At, 1, 0); PG8_STAGE(PG8_SA(0, 1), a2 + hstepA, voffA);
;             PG8_WAIT_V(8); PG8_WAIT_L(0); PG8_BAR; PG8_MMA(0, 0, At, B0); PG8_MMA(0, 1, At, B1); PG8_BAR; PG8_SCHED;
	s_nop 0
	s_waitcnt lgkmcnt(0)
	v_mfma_f32_16x16x32_bf16 v[76:79], v[32:35], v[160:163], v[76:79]
	v_mfma_f32_16x16x32_bf16 v[72:75], v[40:43], v[160:163], v[72:75]
	v_mfma_f32_16x16x32_bf16 v[60:63], v[32:35], v[180:183], v[60:63]
	v_mfma_f32_16x16x32_bf16 v[56:59], v[40:43], v[180:183], v[56:59]
	v_mfma_f32_16x16x32_bf16 v[28:31], v[32:35], v[188:191], v[28:31]
	v_mfma_f32_16x16x32_bf16 v[24:27], v[40:43], v[188:191], v[24:27]
	v_mfma_f32_16x16x32_bf16 v[12:15], v[32:35], v[196:199], v[12:15]
	v_mfma_f32_16x16x32_bf16 v[8:11], v[40:43], v[196:199], v[8:11]
	v_mfma_f32_16x16x32_bf16 v[76:79], v[36:39], v[164:167], v[76:79]
	v_mfma_f32_16x16x32_bf16 v[72:75], v[44:47], v[164:167], v[72:75]
	v_mfma_f32_16x16x32_bf16 v[60:63], v[36:39], v[184:187], v[60:63]
	v_mfma_f32_16x16x32_bf16 v[56:59], v[44:47], v[184:187], v[56:59]
	v_mfma_f32_16x16x32_bf16 v[28:31], v[36:39], v[192:195], v[28:31]
	v_mfma_f32_16x16x32_bf16 v[24:27], v[44:47], v[192:195], v[24:27]
	v_mfma_f32_16x16x32_bf16 v[12:15], v[36:39], v[206:209], v[12:15]
	v_mfma_f32_16x16x32_bf16 v[8:11], v[44:47], v[206:209], v[8:11]
	s_nop 0
	s_nop 0
	v_mfma_f32_16x16x32_bf16 v[20:23], v[144:147], v[188:191], v[20:23]
	v_mfma_f32_16x16x32_bf16 v[16:19], v[152:155], v[188:191], v[16:19]
	v_mfma_f32_16x16x32_bf16 v[4:7], v[144:147], v[196:199], v[4:7]
	v_mfma_f32_16x16x32_bf16 v[0:3], v[152:155], v[196:199], v[0:3]
	v_mfma_f32_16x16x32_bf16 v[32:35], v[144:147], v[160:163], v[68:71]
	v_mfma_f32_16x16x32_bf16 v[36:39], v[152:155], v[160:163], v[64:67]
	v_mfma_f32_16x16x32_bf16 v[40:43], v[144:147], v[180:183], v[52:55]
	v_mfma_f32_16x16x32_bf16 v[44:47], v[152:155], v[180:183], v[48:51]
	v_mfma_f32_16x16x32_bf16 v[20:23], v[148:151], v[192:195], v[20:23]
	v_mfma_f32_16x16x32_bf16 v[16:19], v[156:159], v[192:195], v[16:19]
	v_mfma_f32_16x16x32_bf16 v[4:7], v[148:151], v[206:209], v[4:7]
	v_mfma_f32_16x16x32_bf16 v[0:3], v[156:159], v[206:209], v[0:3]
	v_mfma_f32_16x16x32_bf16 v[32:35], v[148:151], v[164:167], v[32:35]
	v_mfma_f32_16x16x32_bf16 v[36:39], v[156:159], v[164:167], v[36:39]
	v_mfma_f32_16x16x32_bf16 v[40:43], v[148:151], v[184:187], v[40:43]
	v_mfma_f32_16x16x32_bf16 v[44:47], v[156:159], v[184:187], v[44:47]
	s_nop 0
	s_barrier
	s_add_i32 s16, 0, 0x18000
	s_add_i32 s30, 0, 0x1c000
	v_add_u32_e32 v68, s16, v202
	v_add_u32_e32 v156, s30, v202
	ds_read_b128 v[48:51], v68
	ds_read_b128 v[52:55], v68 offset:1024
	ds_read_b128 v[64:67], v68 offset:2048
	ds_read_b128 v[68:71], v68 offset:3072
	ds_read_b128 v[144:147], v156
	ds_read_b128 v[148:151], v156 offset:1024
	ds_read_b128 v[152:155], v156 offset:2048
	ds_read_b128 v[156:159], v156 offset:3072
	s_add_u32 s48, s48, 0x40000
	s_addc_u32 s49, s49, 0
	s_mov_b32 m0, s60
	v_lshl_add_u64 v[222:223], s[48:49], 0, v[168:169]
	ds_read_b128 v[160:163], v204 offset:32768
	ds_read_b128 v[164:167], v204 offset:33792
	ds_read_b128 v[180:183], v204 offset:34816
	ds_read_b128 v[184:187], v204 offset:35840
	ds_read_b128 v[188:191], v204 offset:36864
	ds_read_b128 v[192:195], v204 offset:37888
	ds_read_b128 v[196:199], v204 offset:38912
	ds_read_b128 v[206:209], v204 offset:39936
	global_load_lds_dwordx4 v[222:223], off
	v_lshl_add_u64 v[222:223], s[48:49], 0, v[170:171]
	s_mov_b32 m0, s61
	s_nop 0
	global_load_lds_dwordx4 v[222:223], off
	s_waitcnt vmcnt(8)
	s_waitcnt lgkmcnt(0)
	s_barrier
	s_nop 0
	s_waitcnt lgkmcnt(0)
	v_mfma_f32_16x16x32_bf16 v[140:143], v[48:51], v[160:163], v[140:143]
	v_mfma_f32_16x16x32_bf16 v[136:139], v[64:67], v[160:163], v[136:139]
	v_mfma_f32_16x16x32_bf16 v[124:127], v[48:51], v[180:183], v[124:127]
	v_mfma_f32_16x16x32_bf16 v[120:123], v[64:67], v[180:183], v[120:123]
	v_mfma_f32_16x16x32_bf16 v[108:111], v[48:51], v[188:191], v[108:111]
	v_mfma_f32_16x16x32_bf16 v[104:107], v[64:67], v[188:191], v[104:107]
	v_mfma_f32_16x16x32_bf16 v[92:95], v[48:51], v[196:199], v[92:95]
	v_mfma_f32_16x16x32_bf16 v[88:91], v[64:67], v[196:199], v[88:91]
	v_mfma_f32_16x16x32_bf16 v[140:143], v[52:55], v[164:167], v[140:143]
	v_mfma_f32_16x16x32_bf16 v[136:139], v[68:71], v[164:167], v[136:139]
	v_mfma_f32_16x16x32_bf16 v[124:127], v[52:55], v[184:187], v[124:127]
	v_mfma_f32_16x16x32_bf16 v[120:123], v[68:71], v[184:187], v[120:123]
	v_mfma_f32_16x16x32_bf16 v[108:111], v[52:55], v[192:195], v[108:111]
	v_mfma_f32_16x16x32_bf16 v[104:107], v[68:71], v[192:195], v[104:107]
	v_mfma_f32_16x16x32_bf16 v[92:95], v[52:55], v[206:209], v[92:95]
	v_mfma_f32_16x16x32_bf16 v[88:91], v[68:71], v[206:209], v[88:91]
	s_nop 0
	s_nop 0
	v_mfma_f32_16x16x32_bf16 v[132:135], v[144:147], v[160:163], v[132:135]
	v_mfma_f32_16x16x32_bf16 v[128:131], v[152:155], v[160:163], v[128:131]
	v_mfma_f32_16x16x32_bf16 v[116:119], v[144:147], v[180:183], v[116:119]
	v_mfma_f32_16x16x32_bf16 v[112:115], v[152:155], v[180:183], v[112:115]
	v_mfma_f32_16x16x32_bf16 v[100:103], v[144:147], v[188:191], v[100:103]
	v_mfma_f32_16x16x32_bf16 v[96:99], v[152:155], v[188:191], v[96:99]
	v_mfma_f32_16x16x32_bf16 v[84:87], v[144:147], v[196:199], v[84:87]
	v_mfma_f32_16x16x32_bf16 v[80:83], v[152:155], v[196:199], v[80:83]
	v_mfma_f32_16x16x32_bf16 v[132:135], v[148:151], v[164:167], v[132:135]
	v_mfma_f32_16x16x32_bf16 v[128:131], v[156:159], v[164:167], v[128:131]
	v_mfma_f32_16x16x32_bf16 v[116:119], v[148:151], v[184:187], v[116:119]
	v_mfma_f32_16x16x32_bf16 v[112:115], v[156:159], v[184:187], v[112:115]
	v_mfma_f32_16x16x32_bf16 v[100:103], v[148:151], v[192:195], v[100:103]
	v_mfma_f32_16x16x32_bf16 v[96:99], v[156:159], v[192:195], v[96:99]
	v_mfma_f32_16x16x32_bf16 v[84:87], v[148:151], v[206:209], v[84:87]
	v_mfma_f32_16x16x32_bf16 v[80:83], v[156:159], v[206:209], v[80:83]
	s_nop 0
	s_barrier
; #define PG8_STAGE(bufoff, gbase, voff) do { _Pragma("unroll") for (int _i = 0; _i < 2; ++_i) \
;         __builtin_amdgcn_global_load_lds((const unsigned*)((const char*)(gbase) + (voff)[_i]), (PG8_LAS unsigned*)(lds + (bufoff) + ldsw + _i * 8192), 16, 0, 0); } while (0)
; #define PG8_LDA(dst, b, h) do { _Pragma("unroll") for (int m = 0; m < 4; ++m) _Pragma("unroll") for (int k = 0; k < 2; ++k) dst[m][k] = *(const PG8_LAS bf16x8*)(lds + PG8_SA(b, h) + aoff + m * 2048 + k * 1024); } while (0)
; #define PG8_MMA(ai, bj, At, Bt) do { __builtin_amdgcn_s_setprio(1); _Pragma("unroll") for (int m = 0; m < 4; ++m) _Pragma("unroll") for (int n = 0; n < 2; ++n) _Pragma("unroll") for (int k = 0; k < 2; ++k) \
;         acc[ai][bj][m][n] = __builtin_amdgcn_mfma_f32_16x16x32_bf16(Bt[n][k], At[m][k], acc[ai][bj][m][n], 0, 0, 0); __builtin_amdgcn_s_setprio(0); } while (0)
; #define PG8_WAIT_V(n) asm volatile("s_waitcnt vmcnt(" #n ")" ::: "memory")
; #define PG8_WAIT_L(n) asm volatile("s_waitcnt lgkmcnt(" #n ")" ::: "memory")
; #define PG8_BAR __builtin_amdgcn_s_barrier()
; #define PG8_SCHED __builtin_amdgcn_sched_barrier(0)
; template <class Epi, class Sched>
; __device__ __forceinline__ void gemm_phase(PG8_LAS unsigned char* lds, const Gemm g, const Sched& S, const Epi& E, const int tid) {
;     ...
;             PG8_LDA(At, 1, 1); PG8_STAGE(PG8_SB(1, 0), b3, voffB); PG8_STAGE(PG8_SB(1, 1), b3 + hstepB, voffB); PG8_STAGE(PG8_SA(1, 0), a3, voffA);
;             PG8_WAIT_V(8); PG8_WAIT_L(0); PG8_BAR; PG8_MMA(1, 0, At, B0); PG8_MMA(1, 1, At, B1); PG8_BAR; PG8_SCHED;
;         }
	s_add_i32 s16, s16, s57
	v_lshl_add_u64 v[210:211], v[210:211], 0, s[10:11]
	s_mov_b32 m0, s16
	ds_read_b128 v[160:163], v204 offset:49152
	ds_read_b128 v[164:167], v204 offset:50176
	ds_read_b128 v[180:183], v204 offset:51200
	ds_read_b128 v[184:187], v204 offset:52224
	ds_read_b128 v[188:191], v204 offset:53248
	ds_read_b128 v[192:195], v204 offset:54272
	ds_read_b128 v[196:199], v204 offset:55296
	ds_read_b128 v[206:209], v204 offset:56320
	global_load_lds_dwordx4 v[210:211], off
	s_add_i32 m0, s16, 0x2000
	s_add_u32 s46, s46, 0x40080
	v_lshl_add_u64 v[210:211], v[216:217], 0, s[10:11]
	s_addc_u32 s47, s47, 0
	s_add_i32 s16, s30, s57
	global_load_lds_dwordx4 v[210:211], off
	v_lshl_add_u64 v[210:211], s[46:47], 0, v[212:213]
	s_mov_b32 m0, s16
	s_nop 0
	global_load_lds_dwordx4 v[210:211], off
	v_lshl_add_u64 v[210:211], s[46:47], 0, v[172:173]
	s_add_i32 m0, s16, 0x2000
	s_nop 0
	global_load_lds_dwordx4 v[210:211], off
	v_lshl_add_u64 v[210:211], v[218:219], 0, s[10:11]
	s_mov_b32 m0, s64
	s_nop 0
	global_load_lds_dwordx4 v[210:211], off
	v_lshl_add_u64 v[210:211], v[220:221], 0, s[10:11]
	s_mov_b32 m0, s65
	s_nop 0
	global_load_lds_dwordx4 v[210:211], off
	s_waitcnt vmcnt(8)
	s_waitcnt lgkmcnt(0)
	s_barrier
	s_nop 0
	s_waitcnt lgkmcnt(0)
	v_mfma_f32_16x16x32_bf16 v[76:79], v[48:51], v[160:163], v[76:79]
	v_mfma_f32_16x16x32_bf16 v[72:75], v[64:67], v[160:163], v[72:75]
	v_mfma_f32_16x16x32_bf16 v[60:63], v[48:51], v[180:183], v[60:63]
	v_mfma_f32_16x16x32_bf16 v[56:59], v[64:67], v[180:183], v[56:59]
	v_mfma_f32_16x16x32_bf16 v[28:31], v[48:51], v[188:191], v[28:31]
	v_mfma_f32_16x16x32_bf16 v[24:27], v[64:67], v[188:191], v[24:27]
	v_mfma_f32_16x16x32_bf16 v[12:15], v[48:51], v[196:199], v[12:15]
	v_mfma_f32_16x16x32_bf16 v[8:11], v[64:67], v[196:199], v[8:11]
	v_mfma_f32_16x16x32_bf16 v[76:79], v[52:55], v[164:167], v[76:79]
	v_mfma_f32_16x16x32_bf16 v[72:75], v[68:71], v[164:167], v[72:75]
	v_mfma_f32_16x16x32_bf16 v[60:63], v[52:55], v[184:187], v[60:63]
	v_mfma_f32_16x16x32_bf16 v[56:59], v[68:71], v[184:187], v[56:59]
	v_mfma_f32_16x16x32_bf16 v[28:31], v[52:55], v[192:195], v[28:31]
	v_mfma_f32_16x16x32_bf16 v[24:27], v[68:71], v[192:195], v[24:27]
	v_mfma_f32_16x16x32_bf16 v[12:15], v[52:55], v[206:209], v[12:15]
	v_mfma_f32_16x16x32_bf16 v[8:11], v[68:71], v[206:209], v[8:11]
	s_nop 0
	s_nop 0
	v_mfma_f32_16x16x32_bf16 v[32:35], v[144:147], v[160:163], v[32:35]
	v_mfma_f32_16x16x32_bf16 v[68:71], v[148:151], v[164:167], v[32:35]
	v_mfma_f32_16x16x32_bf16 v[32:35], v[152:155], v[160:163], v[36:39]
	v_mfma_f32_16x16x32_bf16 v[64:67], v[156:159], v[164:167], v[32:35]
	v_mfma_f32_16x16x32_bf16 v[32:35], v[144:147], v[180:183], v[40:43]
	v_mfma_f32_16x16x32_bf16 v[52:55], v[148:151], v[184:187], v[32:35]
	v_mfma_f32_16x16x32_bf16 v[32:35], v[152:155], v[180:183], v[44:47]
	v_mfma_f32_16x16x32_bf16 v[20:23], v[144:147], v[188:191], v[20:23]
	v_mfma_f32_16x16x32_bf16 v[16:19], v[152:155], v[188:191], v[16:19]
	v_mfma_f32_16x16x32_bf16 v[4:7], v[144:147], v[196:199], v[4:7]
	v_mfma_f32_16x16x32_bf16 v[0:3], v[152:155], v[196:199], v[0:3]
	v_mfma_f32_16x16x32_bf16 v[48:51], v[156:159], v[184:187], v[32:35]
	v_mfma_f32_16x16x32_bf16 v[20:23], v[148:151], v[192:195], v[20:23]
	v_mfma_f32_16x16x32_bf16 v[16:19], v[156:159], v[192:195], v[16:19]
	v_mfma_f32_16x16x32_bf16 v[4:7], v[148:151], v[206:209], v[4:7]
	v_mfma_f32_16x16x32_bf16 v[0:3], v[156:159], v[206:209], v[0:3]
	s_nop 0
	s_barrier
	s_add_i32 s23, s23, 2
	s_add_u32 s42, s42, 0x100
	s_addc_u32 s43, s43, 0
	s_add_u32 s21, s21, 0x100
	s_addc_u32 s22, s22, 0
	s_cmp_gt_u32 s23, 13
	s_cbranch_scc0 .LBB0_183
	s_and_b64 vcc, exec, s[12:13]
	s_cbranch_vccz .LBB0_186
	s_barrier

; #define PG8_STAGE(bufoff, gbase, voff) do { _Pragma("unroll") for (int _i = 0; _i < 2; ++_i) \
;         __builtin_amdgcn_global_load_lds((const unsigned*)((const char*)(gbase) + (voff)[_i]), (PG8_LAS unsigned*)(lds + (bufoff) + ldsw + _i * 8192), 16, 0, 0); } while (0)
; #define PG8_LDA(dst, b, h) do { _Pragma("unroll") for (int m = 0; m < 4; ++m) _Pragma("unroll") for (int k = 0; k < 2; ++k) dst[m][k] = *(const PG8_LAS bf16x8*)(lds + PG8_SA(b, h) + aoff + m * 2048 + k * 1024); } while (0)
; #define PG8_LDB(dst, b, h) do { _Pragma("unroll") for (int n = 0; n < 2; ++n) _Pragma("unroll") for (int k = 0; k < 2; ++k) dst[n][k] = *(const PG8_LAS bf16x8*)(lds + PG8_SB(b, h) + boff + n * 2048 + k * 1024); } while (0)
; #define PG8_MMA(ai, bj, At, Bt) do { __builtin_amdgcn_s_setprio(1); _Pragma("unroll") for (int m = 0; m < 4; ++m) _Pragma("unroll") for (int n = 0; n < 2; ++n) _Pragma("unroll") for (int k = 0; k < 2; ++k) \
;         acc[ai][bj][m][n] = __builtin_amdgcn_mfma_f32_16x16x32_bf16(Bt[n][k], At[m][k], acc[ai][bj][m][n], 0, 0, 0); __builtin_amdgcn_s_setprio(0); } while (0)
; #define PG8_WAIT_V(n) asm volatile("s_waitcnt vmcnt(" #n ")" ::: "memory")
; #define PG8_WAIT_L(n) asm volatile("s_waitcnt lgkmcnt(" #n ")" ::: "memory")
; #define PG8_BAR __builtin_amdgcn_s_barrier()
; #define PG8_SCHED __builtin_amdgcn_sched_barrier(0)
; template <class Epi, class Sched>
; __device__ __forceinline__ void gemm_phase(PG8_LAS unsigned char* lds, const Gemm g, const Sched& S, const Epi& E, const int tid) {
;     ...
;             PG8_LDB(B0, 0, 0); PG8_LDB(B1, 0, 1); PG8_SCHED; PG8_LDA(At, 0, 0); PG8_STAGE(PG8_SA(1, 1), a1 + hstepA, voffA);
;             PG8_WAIT_V(8); PG8_WAIT_L(0); PG8_BAR; PG8_MMA(0, 0, At, B0); PG8_MMA(0, 1, At, B1); PG8_BAR; PG8_SCHED;
;             PG8_LDA(At, 0, 1); PG8_STAGE(PG8_SB(0, 0), b2, voffB); PG8_STAGE(PG8_SB(0, 1), b2 + hstepB, voffB); PG8_STAGE(PG8_SA(0, 0), a2, voffA);
;             PG8_WAIT_V(8); PG8_WAIT_L(0); PG8_BAR; PG8_MMA(1, 0, At, B0); PG8_MMA(1, 1, At, B1); PG8_BAR; PG8_SCHED;
.LBB0_464:
	s_add_u32 s16, s42, 0xfff80080
	s_addc_u32 s30, s43, -1
	s_add_i32 s41, 0, 0x10000
	s_cmp_eq_u32 s33, 28
	s_cselect_b32 s47, s1, s30
	s_cselect_b32 s46, s8, s16
	s_cselect_b32 s45, s19, s25
	s_cselect_b32 s44, s22, s23
	s_add_i32 s16, 0, 0x14000
	v_add_u32_e32 v68, s41, v230
	v_add_u32_e32 v156, s16, v230
	ds_read_b128 v[56:59], v68
	ds_read_b128 v[60:63], v68 offset:1024
	ds_read_b128 v[64:67], v68 offset:2048
	ds_read_b128 v[68:71], v68 offset:3072
	ds_read_b128 v[144:147], v156
	ds_read_b128 v[148:151], v156 offset:1024
	ds_read_b128 v[152:155], v156 offset:2048
	ds_read_b128 v[156:159], v156 offset:3072
	v_lshl_add_u64 v[202:203], s[42:43], 0, v[178:179]
	s_add_i32 m0, s57, 0xc000
	ds_read_b128 v[160:163], v231
	ds_read_b128 v[164:167], v231 offset:1024
	ds_read_b128 v[168:171], v231 offset:2048
	ds_read_b128 v[182:185], v231 offset:3072
	ds_read_b128 v[186:189], v231 offset:4096
	ds_read_b128 v[190:193], v231 offset:5120
	ds_read_b128 v[194:197], v231 offset:6144
	ds_read_b128 v[198:201], v231 offset:7168
	global_load_lds_dwordx4 v[202:203], off
	v_lshl_add_u64 v[202:203], s[42:43], 0, v[180:181]
	s_add_i32 m0, s57, 0xe000
	s_nop 0
	global_load_lds_dwordx4 v[202:203], off
	s_waitcnt vmcnt(8)
	s_waitcnt lgkmcnt(0)
	s_barrier
	s_nop 0
	s_waitcnt lgkmcnt(0)
	v_mfma_f32_16x16x32_bf16 v[140:143], v[56:59], v[160:163], v[140:143]
	v_mfma_f32_16x16x32_bf16 v[136:139], v[64:67], v[160:163], v[136:139]
	v_mfma_f32_16x16x32_bf16 v[124:127], v[56:59], v[168:171], v[124:127]
	v_mfma_f32_16x16x32_bf16 v[120:123], v[64:67], v[168:171], v[120:123]
	v_mfma_f32_16x16x32_bf16 v[108:111], v[56:59], v[186:189], v[108:111]
	v_mfma_f32_16x16x32_bf16 v[104:107], v[64:67], v[186:189], v[104:107]
	v_mfma_f32_16x16x32_bf16 v[92:95], v[56:59], v[194:197], v[92:95]
	v_mfma_f32_16x16x32_bf16 v[88:91], v[64:67], v[194:197], v[88:91]
	v_mfma_f32_16x16x32_bf16 v[140:143], v[60:63], v[164:167], v[140:143]
	v_mfma_f32_16x16x32_bf16 v[136:139], v[68:71], v[164:167], v[136:139]
	v_mfma_f32_16x16x32_bf16 v[124:127], v[60:63], v[182:185], v[124:127]
	v_mfma_f32_16x16x32_bf16 v[120:123], v[68:71], v[182:185], v[120:123]
	v_mfma_f32_16x16x32_bf16 v[108:111], v[60:63], v[190:193], v[108:111]
	v_mfma_f32_16x16x32_bf16 v[104:107], v[68:71], v[190:193], v[104:107]
	v_mfma_f32_16x16x32_bf16 v[92:95], v[60:63], v[198:201], v[92:95]
	v_mfma_f32_16x16x32_bf16 v[88:91], v[68:71], v[198:201], v[88:91]
	s_nop 0
	s_nop 0
	v_mfma_f32_16x16x32_bf16 v[132:135], v[144:147], v[160:163], v[132:135]
	v_mfma_f32_16x16x32_bf16 v[128:131], v[152:155], v[160:163], v[128:131]
	v_mfma_f32_16x16x32_bf16 v[116:119], v[144:147], v[168:171], v[116:119]
	v_mfma_f32_16x16x32_bf16 v[112:115], v[152:155], v[168:171], v[112:115]
	v_mfma_f32_16x16x32_bf16 v[100:103], v[144:147], v[186:189], v[100:103]
	v_mfma_f32_16x16x32_bf16 v[96:99], v[152:155], v[186:189], v[96:99]
	v_mfma_f32_16x16x32_bf16 v[84:87], v[144:147], v[194:197], v[84:87]
	v_mfma_f32_16x16x32_bf16 v[80:83], v[152:155], v[194:197], v[80:83]
	v_mfma_f32_16x16x32_bf16 v[132:135], v[148:151], v[164:167], v[132:135]
	v_mfma_f32_16x16x32_bf16 v[128:131], v[156:159], v[164:167], v[128:131]
	v_mfma_f32_16x16x32_bf16 v[116:119], v[148:151], v[182:185], v[116:119]
	v_mfma_f32_16x16x32_bf16 v[112:115], v[156:159], v[182:185], v[112:115]
	v_mfma_f32_16x16x32_bf16 v[100:103], v[148:151], v[190:193], v[100:103]
	v_mfma_f32_16x16x32_bf16 v[96:99], v[156:159], v[190:193], v[96:99]
	v_mfma_f32_16x16x32_bf16 v[84:87], v[148:151], v[198:201], v[84:87]
	v_mfma_f32_16x16x32_bf16 v[80:83], v[156:159], v[198:201], v[80:83]
	s_nop 0
	s_barrier
	s_add_i32 s30, s41, s56
	v_lshl_add_u64 v[202:203], s[44:45], 0, v[212:213]
	s_mov_b32 m0, s30
	ds_read_b128 v[160:163], v231 offset:16384
	ds_read_b128 v[164:167], v231 offset:17408
	ds_read_b128 v[168:171], v231 offset:18432
	ds_read_b128 v[182:185], v231 offset:19456
	ds_read_b128 v[186:189], v231 offset:20480
	ds_read_b128 v[190:193], v231 offset:21504
	ds_read_b128 v[194:197], v231 offset:22528
	ds_read_b128 v[198:201], v231 offset:23552
	global_load_lds_dwordx4 v[202:203], off
	s_add_i32 m0, s30, 0x2000
	s_add_u32 s52, s44, 0x80000
	v_lshl_add_u64 v[204:205], s[44:45], 0, v[176:177]
	s_addc_u32 s53, s45, 0
	s_add_i32 s16, s16, s56
	global_load_lds_dwordx4 v[204:205], off
	v_lshl_add_u64 v[206:207], s[52:53], 0, v[212:213]
	s_mov_b32 m0, s16
	v_lshl_add_u64 v[208:209], s[46:47], 0, v[174:175]
	global_load_lds_dwordx4 v[206:207], off
	v_lshl_add_u64 v[206:207], s[52:53], 0, v[176:177]
	s_add_i32 m0, s16, 0x2000
	s_nop 0
	global_load_lds_dwordx4 v[206:207], off
	v_lshl_add_u64 v[206:207], s[46:47], 0, v[172:173]
	s_mov_b32 m0, s57
	s_nop 0
	global_load_lds_dwordx4 v[206:207], off
	s_mov_b32 m0, s58
	s_nop 0
	global_load_lds_dwordx4 v[208:209], off
	s_waitcnt vmcnt(8)
	s_waitcnt lgkmcnt(0)
	s_barrier
; #define PG8_STAGE(bufoff, gbase, voff) do { _Pragma("unroll") for (int _i = 0; _i < 2; ++_i) \
;         __builtin_amdgcn_global_load_lds((const unsigned*)((const char*)(gbase) + (voff)[_i]), (PG8_LAS unsigned*)(lds + (bufoff) + ldsw + _i * 8192), 16, 0, 0); } while (0)
; #define PG8_LDA(dst, b, h) do { _Pragma("unroll") for (int m = 0; m < 4; ++m) _Pragma("unroll") for (int k = 0; k < 2; ++k) dst[m][k] = *(const PG8_LAS bf16x8*)(lds + PG8_SA(b, h) + aoff + m * 2048 + k * 1024); } while (0)
; #define PG8_LDB(dst, b, h) do { _Pragma("unroll") for (int n = 0; n < 2; ++n) _Pragma("unroll") for (int k = 0; k < 2; ++k) dst[n][k] = *(const PG8_LAS bf16x8*)(lds + PG8_SB(b, h) + boff + n * 2048 + k * 1024); } while (0)
; #define PG8_MMA(ai, bj, At, Bt) do { __builtin_amdgcn_s_setprio(1); _Pragma("unroll") for (int m = 0; m < 4; ++m) _Pragma("unroll") for (int n = 0; n < 2; ++n) _Pragma("unroll") for (int k = 0; k < 2; ++k) \
;         acc[ai][bj][m][n] = __builtin_amdgcn_mfma_f32_16x16x32_bf16(Bt[n][k], At[m][k], acc[ai][bj][m][n], 0, 0, 0); __builtin_amdgcn_s_setprio(0); } while (0)
; #define PG8_WAIT_V(n) asm volatile("s_waitcnt vmcnt(" #n ")" ::: "memory")
; #define PG8_WAIT_L(n) asm volatile("s_waitcnt lgkmcnt(" #n ")" ::: "memory")
; #define PG8_BAR __builtin_amdgcn_s_barrier()
; #define PG8_SCHED __builtin_amdgcn_sched_barrier(0)
; template <class Epi, class Sched>
; __device__ __forceinline__ void gemm_phase(PG8_LAS unsigned char* lds, const Gemm g, const Sched& S, const Epi& E, const int tid) {
;     ...
;             PG8_WAIT_V(8); PG8_WAIT_L(0); PG8_BAR; PG8_MMA(1, 0, At, B0); PG8_MMA(1, 1, At, B1); PG8_BAR; PG8_SCHED;
;             PG8_LDB(B0, 1, 0); PG8_LDB(B1, 1, 1); PG8_SCHED; PG8_LDA(At, 1, 0); PG8_STAGE(PG8_SA(0, 1), a2 + hstepA, voffA);
;             PG8_WAIT_V(8); PG8_WAIT_L(0); PG8_BAR; PG8_MMA(0, 0, At, B0); PG8_MMA(0, 1, At, B1); PG8_BAR; PG8_SCHED;
	s_nop 0
	s_waitcnt lgkmcnt(0)
	v_mfma_f32_16x16x32_bf16 v[76:79], v[56:59], v[160:163], v[76:79]
	v_mfma_f32_16x16x32_bf16 v[72:75], v[64:67], v[160:163], v[72:75]
	v_mfma_f32_16x16x32_bf16 v[44:47], v[56:59], v[168:171], v[44:47]
	v_mfma_f32_16x16x32_bf16 v[40:43], v[64:67], v[168:171], v[40:43]
	v_mfma_f32_16x16x32_bf16 v[28:31], v[56:59], v[186:189], v[28:31]
	v_mfma_f32_16x16x32_bf16 v[24:27], v[64:67], v[186:189], v[24:27]
	v_mfma_f32_16x16x32_bf16 v[12:15], v[56:59], v[194:197], v[12:15]
	v_mfma_f32_16x16x32_bf16 v[8:11], v[64:67], v[194:197], v[8:11]
	v_mfma_f32_16x16x32_bf16 v[76:79], v[60:63], v[164:167], v[76:79]
	v_mfma_f32_16x16x32_bf16 v[72:75], v[68:71], v[164:167], v[72:75]
	v_mfma_f32_16x16x32_bf16 v[44:47], v[60:63], v[182:185], v[44:47]
	v_mfma_f32_16x16x32_bf16 v[40:43], v[68:71], v[182:185], v[40:43]
	v_mfma_f32_16x16x32_bf16 v[28:31], v[60:63], v[190:193], v[28:31]
	v_mfma_f32_16x16x32_bf16 v[24:27], v[68:71], v[190:193], v[24:27]
	v_mfma_f32_16x16x32_bf16 v[12:15], v[60:63], v[198:201], v[12:15]
	v_mfma_f32_16x16x32_bf16 v[8:11], v[68:71], v[198:201], v[8:11]
	s_nop 0
	s_nop 0
	v_mfma_f32_16x16x32_bf16 v[52:55], v[144:147], v[160:163], v[52:55]
	v_mfma_f32_16x16x32_bf16 v[48:51], v[152:155], v[160:163], v[48:51]
	v_mfma_f32_16x16x32_bf16 v[36:39], v[144:147], v[168:171], v[36:39]
	v_mfma_f32_16x16x32_bf16 v[32:35], v[152:155], v[168:171], v[32:35]
	v_mfma_f32_16x16x32_bf16 v[20:23], v[144:147], v[186:189], v[20:23]
	v_mfma_f32_16x16x32_bf16 v[16:19], v[152:155], v[186:189], v[16:19]
	v_mfma_f32_16x16x32_bf16 v[4:7], v[144:147], v[194:197], v[4:7]
	v_mfma_f32_16x16x32_bf16 v[0:3], v[152:155], v[194:197], v[0:3]
	v_mfma_f32_16x16x32_bf16 v[52:55], v[148:151], v[164:167], v[52:55]
	v_mfma_f32_16x16x32_bf16 v[48:51], v[156:159], v[164:167], v[48:51]
	v_mfma_f32_16x16x32_bf16 v[36:39], v[148:151], v[182:185], v[36:39]
	v_mfma_f32_16x16x32_bf16 v[32:35], v[156:159], v[182:185], v[32:35]
	v_mfma_f32_16x16x32_bf16 v[20:23], v[148:151], v[190:193], v[20:23]
	v_mfma_f32_16x16x32_bf16 v[16:19], v[156:159], v[190:193], v[16:19]
	v_mfma_f32_16x16x32_bf16 v[4:7], v[148:151], v[198:201], v[4:7]
	v_mfma_f32_16x16x32_bf16 v[0:3], v[156:159], v[198:201], v[0:3]
	s_nop 0
	s_barrier
	s_add_i32 s16, 0, 0x18000
	s_add_i32 s30, 0, 0x1c000
	v_add_u32_e32 v68, s16, v230
	v_add_u32_e32 v156, s30, v230
	ds_read_b128 v[56:59], v68
	ds_read_b128 v[60:63], v68 offset:1024
	ds_read_b128 v[64:67], v68 offset:2048
	ds_read_b128 v[68:71], v68 offset:3072
	ds_read_b128 v[144:147], v156
	ds_read_b128 v[148:151], v156 offset:1024
	ds_read_b128 v[152:155], v156 offset:2048
	ds_read_b128 v[156:159], v156 offset:3072
	s_add_u32 s46, s46, 0x80000
	s_addc_u32 s47, s47, 0
	s_mov_b32 m0, s59
	v_lshl_add_u64 v[210:211], s[46:47], 0, v[172:173]
	ds_read_b128 v[160:163], v231 offset:32768
	ds_read_b128 v[164:167], v231 offset:33792
	ds_read_b128 v[168:171], v231 offset:34816
	ds_read_b128 v[182:185], v231 offset:35840
	ds_read_b128 v[186:189], v231 offset:36864
	ds_read_b128 v[190:193], v231 offset:37888
	ds_read_b128 v[194:197], v231 offset:38912
	ds_read_b128 v[198:201], v231 offset:39936
	global_load_lds_dwordx4 v[210:211], off
	v_lshl_add_u64 v[210:211], s[46:47], 0, v[174:175]
	s_mov_b32 m0, s60
	s_nop 0
	global_load_lds_dwordx4 v[210:211], off
	s_waitcnt vmcnt(8)
	s_waitcnt lgkmcnt(0)
	s_barrier
	s_nop 0
	s_waitcnt lgkmcnt(0)
	v_mfma_f32_16x16x32_bf16 v[140:143], v[56:59], v[160:163], v[140:143]
	v_mfma_f32_16x16x32_bf16 v[136:139], v[64:67], v[160:163], v[136:139]
	v_mfma_f32_16x16x32_bf16 v[124:127], v[56:59], v[168:171], v[124:127]
	v_mfma_f32_16x16x32_bf16 v[120:123], v[64:67], v[168:171], v[120:123]
	v_mfma_f32_16x16x32_bf16 v[108:111], v[56:59], v[186:189], v[108:111]
	v_mfma_f32_16x16x32_bf16 v[104:107], v[64:67], v[186:189], v[104:107]
	v_mfma_f32_16x16x32_bf16 v[92:95], v[56:59], v[194:197], v[92:95]
	v_mfma_f32_16x16x32_bf16 v[88:91], v[64:67], v[194:197], v[88:91]
	v_mfma_f32_16x16x32_bf16 v[140:143], v[60:63], v[164:167], v[140:143]
	v_mfma_f32_16x16x32_bf16 v[136:139], v[68:71], v[164:167], v[136:139]
	v_mfma_f32_16x16x32_bf16 v[124:127], v[60:63], v[182:185], v[124:127]
	v_mfma_f32_16x16x32_bf16 v[120:123], v[68:71], v[182:185], v[120:123]
	v_mfma_f32_16x16x32_bf16 v[108:111], v[60:63], v[190:193], v[108:111]
	v_mfma_f32_16x16x32_bf16 v[104:107], v[68:71], v[190:193], v[104:107]
	v_mfma_f32_16x16x32_bf16 v[92:95], v[60:63], v[198:201], v[92:95]
	v_mfma_f32_16x16x32_bf16 v[88:91], v[68:71], v[198:201], v[88:91]
	s_nop 0
	s_nop 0
	v_mfma_f32_16x16x32_bf16 v[132:135], v[144:147], v[160:163], v[132:135]
	v_mfma_f32_16x16x32_bf16 v[128:131], v[152:155], v[160:163], v[128:131]
	v_mfma_f32_16x16x32_bf16 v[116:119], v[144:147], v[168:171], v[116:119]
	v_mfma_f32_16x16x32_bf16 v[112:115], v[152:155], v[168:171], v[112:115]
	v_mfma_f32_16x16x32_bf16 v[100:103], v[144:147], v[186:189], v[100:103]
	v_mfma_f32_16x16x32_bf16 v[96:99], v[152:155], v[186:189], v[96:99]
	v_mfma_f32_16x16x32_bf16 v[84:87], v[144:147], v[194:197], v[84:87]
	v_mfma_f32_16x16x32_bf16 v[80:83], v[152:155], v[194:197], v[80:83]
	v_mfma_f32_16x16x32_bf16 v[132:135], v[148:151], v[164:167], v[132:135]
	v_mfma_f32_16x16x32_bf16 v[128:131], v[156:159], v[164:167], v[128:131]
	v_mfma_f32_16x16x32_bf16 v[116:119], v[148:151], v[182:185], v[116:119]
	v_mfma_f32_16x16x32_bf16 v[112:115], v[156:159], v[182:185], v[112:115]
	v_mfma_f32_16x16x32_bf16 v[100:103], v[148:151], v[190:193], v[100:103]
	v_mfma_f32_16x16x32_bf16 v[96:99], v[156:159], v[190:193], v[96:99]
	v_mfma_f32_16x16x32_bf16 v[84:87], v[148:151], v[198:201], v[84:87]
	v_mfma_f32_16x16x32_bf16 v[80:83], v[156:159], v[198:201], v[80:83]
	s_nop 0
	s_barrier
; #define PG8_STAGE(bufoff, gbase, voff) do { _Pragma("unroll") for (int _i = 0; _i < 2; ++_i) \
;         __builtin_amdgcn_global_load_lds((const unsigned*)((const char*)(gbase) + (voff)[_i]), (PG8_LAS unsigned*)(lds + (bufoff) + ldsw + _i * 8192), 16, 0, 0); } while (0)
; #define PG8_LDA(dst, b, h) do { _Pragma("unroll") for (int m = 0; m < 4; ++m) _Pragma("unroll") for (int k = 0; k < 2; ++k) dst[m][k] = *(const PG8_LAS bf16x8*)(lds + PG8_SA(b, h) + aoff + m * 2048 + k * 1024); } while (0)
; #define PG8_MMA(ai, bj, At, Bt) do { __builtin_amdgcn_s_setprio(1); _Pragma("unroll") for (int m = 0; m < 4; ++m) _Pragma("unroll") for (int n = 0; n < 2; ++n) _Pragma("unroll") for (int k = 0; k < 2; ++k) \
;         acc[ai][bj][m][n] = __builtin_amdgcn_mfma_f32_16x16x32_bf16(Bt[n][k], At[m][k], acc[ai][bj][m][n], 0, 0, 0); __builtin_amdgcn_s_setprio(0); } while (0)
; #define PG8_WAIT_V(n) asm volatile("s_waitcnt vmcnt(" #n ")" ::: "memory")
; #define PG8_WAIT_L(n) asm volatile("s_waitcnt lgkmcnt(" #n ")" ::: "memory")
; #define PG8_BAR __builtin_amdgcn_s_barrier()
; #define PG8_SCHED __builtin_amdgcn_sched_barrier(0)
; template <class Epi, class Sched>
; __device__ __forceinline__ void gemm_phase(PG8_LAS unsigned char* lds, const Gemm g, const Sched& S, const Epi& E, const int tid) {
;     ...
;             PG8_LDA(At, 1, 1); PG8_STAGE(PG8_SB(1, 0), b3, voffB); PG8_STAGE(PG8_SB(1, 1), b3 + hstepB, voffB); PG8_STAGE(PG8_SA(1, 0), a3, voffA);
;             PG8_WAIT_V(8); PG8_WAIT_L(0); PG8_BAR; PG8_MMA(1, 0, At, B0); PG8_MMA(1, 1, At, B1); PG8_BAR; PG8_SCHED;
;         }
	s_add_i32 s16, s16, s56
	v_lshl_add_u64 v[202:203], v[202:203], 0, s[10:11]
	s_mov_b32 m0, s16
	ds_read_b128 v[160:163], v231 offset:49152
	ds_read_b128 v[164:167], v231 offset:50176
	ds_read_b128 v[168:171], v231 offset:51200
	ds_read_b128 v[182:185], v231 offset:52224
	ds_read_b128 v[186:189], v231 offset:53248
	ds_read_b128 v[190:193], v231 offset:54272
	ds_read_b128 v[194:197], v231 offset:55296
	ds_read_b128 v[198:201], v231 offset:56320
	global_load_lds_dwordx4 v[202:203], off
	s_add_i32 m0, s16, 0x2000
	s_add_u32 s44, s44, 0x80080
	v_lshl_add_u64 v[202:203], v[204:205], 0, s[10:11]
	s_addc_u32 s45, s45, 0
	s_add_i32 s16, s30, s56
	global_load_lds_dwordx4 v[202:203], off
	v_lshl_add_u64 v[202:203], s[44:45], 0, v[212:213]
	s_mov_b32 m0, s16
	s_nop 0
	global_load_lds_dwordx4 v[202:203], off
	v_lshl_add_u64 v[202:203], s[44:45], 0, v[176:177]
	s_add_i32 m0, s16, 0x2000
	s_nop 0
	global_load_lds_dwordx4 v[202:203], off
	v_lshl_add_u64 v[202:203], v[206:207], 0, s[10:11]
	s_mov_b32 m0, s71
	s_nop 0
	global_load_lds_dwordx4 v[202:203], off
	v_lshl_add_u64 v[202:203], v[208:209], 0, s[10:11]
	s_mov_b32 m0, s72
	s_nop 0
	global_load_lds_dwordx4 v[202:203], off
	s_waitcnt vmcnt(8)
	s_waitcnt lgkmcnt(0)
	s_barrier
	s_nop 0
	s_waitcnt lgkmcnt(0)
	v_mfma_f32_16x16x32_bf16 v[76:79], v[56:59], v[160:163], v[76:79]
	v_mfma_f32_16x16x32_bf16 v[72:75], v[64:67], v[160:163], v[72:75]
	v_mfma_f32_16x16x32_bf16 v[44:47], v[56:59], v[168:171], v[44:47]
	v_mfma_f32_16x16x32_bf16 v[40:43], v[64:67], v[168:171], v[40:43]
	v_mfma_f32_16x16x32_bf16 v[28:31], v[56:59], v[186:189], v[28:31]
	v_mfma_f32_16x16x32_bf16 v[24:27], v[64:67], v[186:189], v[24:27]
	v_mfma_f32_16x16x32_bf16 v[12:15], v[56:59], v[194:197], v[12:15]
	v_mfma_f32_16x16x32_bf16 v[8:11], v[64:67], v[194:197], v[8:11]
	v_mfma_f32_16x16x32_bf16 v[76:79], v[60:63], v[164:167], v[76:79]
	v_mfma_f32_16x16x32_bf16 v[72:75], v[68:71], v[164:167], v[72:75]
	v_mfma_f32_16x16x32_bf16 v[44:47], v[60:63], v[182:185], v[44:47]
	v_mfma_f32_16x16x32_bf16 v[40:43], v[68:71], v[182:185], v[40:43]
	v_mfma_f32_16x16x32_bf16 v[28:31], v[60:63], v[190:193], v[28:31]
	v_mfma_f32_16x16x32_bf16 v[24:27], v[68:71], v[190:193], v[24:27]
	v_mfma_f32_16x16x32_bf16 v[12:15], v[60:63], v[198:201], v[12:15]
	v_mfma_f32_16x16x32_bf16 v[8:11], v[68:71], v[198:201], v[8:11]
	s_nop 0
	s_nop 0
	v_mfma_f32_16x16x32_bf16 v[52:55], v[144:147], v[160:163], v[52:55]
	v_mfma_f32_16x16x32_bf16 v[48:51], v[152:155], v[160:163], v[48:51]
	v_mfma_f32_16x16x32_bf16 v[36:39], v[144:147], v[168:171], v[36:39]
	v_mfma_f32_16x16x32_bf16 v[32:35], v[152:155], v[168:171], v[32:35]
	v_mfma_f32_16x16x32_bf16 v[20:23], v[144:147], v[186:189], v[20:23]
	v_mfma_f32_16x16x32_bf16 v[16:19], v[152:155], v[186:189], v[16:19]
	v_mfma_f32_16x16x32_bf16 v[4:7], v[144:147], v[194:197], v[4:7]
	v_mfma_f32_16x16x32_bf16 v[0:3], v[152:155], v[194:197], v[0:3]
	v_mfma_f32_16x16x32_bf16 v[52:55], v[148:151], v[164:167], v[52:55]
	v_mfma_f32_16x16x32_bf16 v[48:51], v[156:159], v[164:167], v[48:51]
	v_mfma_f32_16x16x32_bf16 v[36:39], v[148:151], v[182:185], v[36:39]
	v_mfma_f32_16x16x32_bf16 v[32:35], v[156:159], v[182:185], v[32:35]
	v_mfma_f32_16x16x32_bf16 v[20:23], v[148:151], v[190:193], v[20:23]
	v_mfma_f32_16x16x32_bf16 v[16:19], v[156:159], v[190:193], v[16:19]
	v_mfma_f32_16x16x32_bf16 v[4:7], v[148:151], v[198:201], v[4:7]
	v_mfma_f32_16x16x32_bf16 v[0:3], v[156:159], v[198:201], v[0:3]
	s_nop 0
	s_barrier
	s_add_i32 s33, s33, 2
	s_add_u32 s42, s42, 0x100
	s_addc_u32 s43, s43, 0
	s_add_u32 s23, s23, 0x100
	s_addc_u32 s25, s25, 0
	s_cmp_gt_u32 s33, 29
	s_cbranch_scc0 .LBB0_464
	s_and_b64 vcc, exec, s[14:15]
	s_cbranch_vccz .LBB0_467
	s_barrier

; #define PG8_STAGE(bufoff, gbase, voff) do { _Pragma("unroll") for (int _i = 0; _i < 2; ++_i) \
;         __builtin_amdgcn_global_load_lds((const unsigned*)((const char*)(gbase) + (voff)[_i]), (PG8_LAS unsigned*)(lds + (bufoff) + ldsw + _i * 8192), 16, 0, 0); } while (0)
; #define PG8_LDA(dst, b, h) do { _Pragma("unroll") for (int m = 0; m < 4; ++m) _Pragma("unroll") for (int k = 0; k < 2; ++k) dst[m][k] = *(const PG8_LAS bf16x8*)(lds + PG8_SA(b, h) + aoff + m * 2048 + k * 1024); } while (0)
; #define PG8_LDB(dst, b, h) do { _Pragma("unroll") for (int n = 0; n < 2; ++n) _Pragma("unroll") for (int k = 0; k < 2; ++k) dst[n][k] = *(const PG8_LAS bf16x8*)(lds + PG8_SB(b, h) + boff + n * 2048 + k * 1024); } while (0)
; #define PG8_MMA(ai, bj, At, Bt) do { __builtin_amdgcn_s_setprio(1); _Pragma("unroll") for (int m = 0; m < 4; ++m) _Pragma("unroll") for (int n = 0; n < 2; ++n) _Pragma("unroll") for (int k = 0; k < 2; ++k) \
;         acc[ai][bj][m][n] = __builtin_amdgcn_mfma_f32_16x16x32_bf16(Bt[n][k], At[m][k], acc[ai][bj][m][n], 0, 0, 0); __builtin_amdgcn_s_setprio(0); } while (0)
; #define PG8_WAIT_V(n) asm volatile("s_waitcnt vmcnt(" #n ")" ::: "memory")
; #define PG8_WAIT_L(n) asm volatile("s_waitcnt lgkmcnt(" #n ")" ::: "memory")
; #define PG8_BAR __builtin_amdgcn_s_barrier()
; #define PG8_SCHED __builtin_amdgcn_sched_barrier(0)
; template <class Epi, class Sched>
; __device__ __forceinline__ void gemm_phase(PG8_LAS unsigned char* lds, const Gemm g, const Sched& S, const Epi& E, const int tid) {
;     ...
;             PG8_LDB(B0, 0, 0); PG8_LDB(B1, 0, 1); PG8_SCHED; PG8_LDA(At, 0, 0); PG8_STAGE(PG8_SA(1, 1), a1 + hstepA, voffA);
;             PG8_WAIT_V(8); PG8_WAIT_L(0); PG8_BAR; PG8_MMA(0, 0, At, B0); PG8_MMA(0, 1, At, B1); PG8_BAR; PG8_SCHED;
;             PG8_LDA(At, 0, 1); PG8_STAGE(PG8_SB(0, 0), b2, voffB); PG8_STAGE(PG8_SB(0, 1), b2 + hstepB, voffB); PG8_STAGE(PG8_SA(0, 0), a2, voffA);
;             PG8_WAIT_V(8); PG8_WAIT_L(0); PG8_BAR; PG8_MMA(1, 0, At, B0); PG8_MMA(1, 1, At, B1); PG8_BAR; PG8_SCHED;
.LBB0_569:
	s_add_u32 s16, s44, 0xfffc0080
	s_addc_u32 s30, s45, -1
	s_add_i32 s35, 0, 0x10000
	s_cmp_eq_u32 s33, 12
	s_cselect_b32 s73, s8, s30
	s_cselect_b32 s72, s17, s16
	s_cselect_b32 s49, s20, s23
	s_cselect_b32 s48, s21, s22
	s_add_i32 s16, 0, 0x14000
	v_add_u32_e32 v84, s35, v189
	v_add_u32_e32 v156, s16, v189
	ds_read_b128 v[68:71], v84
	ds_read_b128 v[76:79], v84 offset:1024
	ds_read_b128 v[80:83], v84 offset:2048
	ds_read_b128 v[84:87], v84 offset:3072
	ds_read_b128 v[144:147], v156
	ds_read_b128 v[148:151], v156 offset:1024
	ds_read_b128 v[152:155], v156 offset:2048
	ds_read_b128 v[156:159], v156 offset:3072
	v_lshl_add_u64 v[208:209], s[44:45], 0, v[170:171]
	s_add_i32 m0, s91, 0xc000
	ds_read_b128 v[160:163], v190
	ds_read_b128 v[174:177], v190 offset:1024
	ds_read_b128 v[178:181], v190 offset:2048
	ds_read_b128 v[182:185], v190 offset:3072
	ds_read_b128 v[192:195], v190 offset:4096
	ds_read_b128 v[196:199], v190 offset:5120
	ds_read_b128 v[200:203], v190 offset:6144
	ds_read_b128 v[204:207], v190 offset:7168
	global_load_lds_dwordx4 v[208:209], off
	v_lshl_add_u64 v[208:209], s[44:45], 0, v[172:173]
	s_add_i32 m0, s91, 0xe000
	s_nop 0
	global_load_lds_dwordx4 v[208:209], off
	s_waitcnt vmcnt(8)
	s_waitcnt lgkmcnt(0)
	s_barrier
	s_nop 0
	s_waitcnt lgkmcnt(0)
	v_mfma_f32_16x16x32_bf16 v[140:143], v[68:71], v[160:163], v[140:143]
	v_mfma_f32_16x16x32_bf16 v[136:139], v[80:83], v[160:163], v[136:139]
	v_mfma_f32_16x16x32_bf16 v[124:127], v[68:71], v[178:181], v[124:127]
	v_mfma_f32_16x16x32_bf16 v[120:123], v[80:83], v[178:181], v[120:123]
	v_mfma_f32_16x16x32_bf16 v[108:111], v[68:71], v[192:195], v[108:111]
	v_mfma_f32_16x16x32_bf16 v[104:107], v[80:83], v[192:195], v[104:107]
	v_mfma_f32_16x16x32_bf16 v[92:95], v[68:71], v[200:203], v[92:95]
	v_mfma_f32_16x16x32_bf16 v[88:91], v[80:83], v[200:203], v[88:91]
	v_mfma_f32_16x16x32_bf16 v[140:143], v[76:79], v[174:177], v[140:143]
	v_mfma_f32_16x16x32_bf16 v[136:139], v[84:87], v[174:177], v[136:139]
	v_mfma_f32_16x16x32_bf16 v[124:127], v[76:79], v[182:185], v[124:127]
	v_mfma_f32_16x16x32_bf16 v[120:123], v[84:87], v[182:185], v[120:123]
	v_mfma_f32_16x16x32_bf16 v[108:111], v[76:79], v[196:199], v[108:111]
	v_mfma_f32_16x16x32_bf16 v[104:107], v[84:87], v[196:199], v[104:107]
	v_mfma_f32_16x16x32_bf16 v[92:95], v[76:79], v[204:207], v[92:95]
	v_mfma_f32_16x16x32_bf16 v[88:91], v[84:87], v[204:207], v[88:91]
	s_nop 0
	s_nop 0
	v_mfma_f32_16x16x32_bf16 v[132:135], v[144:147], v[160:163], v[132:135]
	v_mfma_f32_16x16x32_bf16 v[128:131], v[152:155], v[160:163], v[128:131]
	v_mfma_f32_16x16x32_bf16 v[116:119], v[144:147], v[178:181], v[116:119]
	v_mfma_f32_16x16x32_bf16 v[112:115], v[152:155], v[178:181], v[112:115]
	v_mfma_f32_16x16x32_bf16 v[100:103], v[144:147], v[192:195], v[100:103]
	v_mfma_f32_16x16x32_bf16 v[96:99], v[152:155], v[192:195], v[96:99]
	v_mfma_f32_16x16x32_bf16 v[72:75], v[144:147], v[200:203], v[72:75]
	v_mfma_f32_16x16x32_bf16 v[64:67], v[152:155], v[200:203], v[64:67]
	v_mfma_f32_16x16x32_bf16 v[132:135], v[148:151], v[174:177], v[132:135]
	v_mfma_f32_16x16x32_bf16 v[128:131], v[156:159], v[174:177], v[128:131]
	v_mfma_f32_16x16x32_bf16 v[116:119], v[148:151], v[182:185], v[116:119]
	v_mfma_f32_16x16x32_bf16 v[112:115], v[156:159], v[182:185], v[112:115]
	v_mfma_f32_16x16x32_bf16 v[100:103], v[148:151], v[196:199], v[100:103]
	v_mfma_f32_16x16x32_bf16 v[96:99], v[156:159], v[196:199], v[96:99]
	v_mfma_f32_16x16x32_bf16 v[72:75], v[148:151], v[204:207], v[72:75]
	v_mfma_f32_16x16x32_bf16 v[64:67], v[156:159], v[204:207], v[64:67]
	s_nop 0
	s_barrier
	s_add_i32 s30, s35, s90
	v_lshl_add_u64 v[208:209], s[48:49], 0, v[212:213]
	s_mov_b32 m0, s30
	ds_read_b128 v[160:163], v190 offset:16384
	ds_read_b128 v[174:177], v190 offset:17408
	ds_read_b128 v[178:181], v190 offset:18432
	ds_read_b128 v[182:185], v190 offset:19456
	ds_read_b128 v[192:195], v190 offset:20480
	ds_read_b128 v[196:199], v190 offset:21504
	ds_read_b128 v[200:203], v190 offset:22528
	ds_read_b128 v[204:207], v190 offset:23552
	global_load_lds_dwordx4 v[208:209], off
	s_add_i32 m0, s30, 0x2000
	s_add_u32 s52, s48, 0x40000
	v_lshl_add_u64 v[210:211], s[48:49], 0, v[168:169]
	s_addc_u32 s53, s49, 0
	s_add_i32 s16, s16, s90
	global_load_lds_dwordx4 v[210:211], off
	v_lshl_add_u64 v[216:217], s[52:53], 0, v[212:213]
	s_mov_b32 m0, s16
	v_lshl_add_u64 v[218:219], s[72:73], 0, v[166:167]
	global_load_lds_dwordx4 v[216:217], off
	v_lshl_add_u64 v[216:217], s[52:53], 0, v[168:169]
	s_add_i32 m0, s16, 0x2000
	s_nop 0
	global_load_lds_dwordx4 v[216:217], off
	v_lshl_add_u64 v[216:217], s[72:73], 0, v[164:165]
	s_mov_b32 m0, s91
	s_nop 0
	global_load_lds_dwordx4 v[216:217], off
	s_mov_b32 m0, s92
	s_nop 0
	global_load_lds_dwordx4 v[218:219], off
	s_waitcnt vmcnt(8)
	s_waitcnt lgkmcnt(0)
	s_barrier
; #define PG8_STAGE(bufoff, gbase, voff) do { _Pragma("unroll") for (int _i = 0; _i < 2; ++_i) \
;         __builtin_amdgcn_global_load_lds((const unsigned*)((const char*)(gbase) + (voff)[_i]), (PG8_LAS unsigned*)(lds + (bufoff) + ldsw + _i * 8192), 16, 0, 0); } while (0)
; #define PG8_LDA(dst, b, h) do { _Pragma("unroll") for (int m = 0; m < 4; ++m) _Pragma("unroll") for (int k = 0; k < 2; ++k) dst[m][k] = *(const PG8_LAS bf16x8*)(lds + PG8_SA(b, h) + aoff + m * 2048 + k * 1024); } while (0)
; #define PG8_LDB(dst, b, h) do { _Pragma("unroll") for (int n = 0; n < 2; ++n) _Pragma("unroll") for (int k = 0; k < 2; ++k) dst[n][k] = *(const PG8_LAS bf16x8*)(lds + PG8_SB(b, h) + boff + n * 2048 + k * 1024); } while (0)
; #define PG8_MMA(ai, bj, At, Bt) do { __builtin_amdgcn_s_setprio(1); _Pragma("unroll") for (int m = 0; m < 4; ++m) _Pragma("unroll") for (int n = 0; n < 2; ++n) _Pragma("unroll") for (int k = 0; k < 2; ++k) \
;         acc[ai][bj][m][n] = __builtin_amdgcn_mfma_f32_16x16x32_bf16(Bt[n][k], At[m][k], acc[ai][bj][m][n], 0, 0, 0); __builtin_amdgcn_s_setprio(0); } while (0)
; #define PG8_WAIT_V(n) asm volatile("s_waitcnt vmcnt(" #n ")" ::: "memory")
; #define PG8_WAIT_L(n) asm volatile("s_waitcnt lgkmcnt(" #n ")" ::: "memory")
; #define PG8_BAR __builtin_amdgcn_s_barrier()
; #define PG8_SCHED __builtin_amdgcn_sched_barrier(0)
; template <class Epi, class Sched>
; __device__ __forceinline__ void gemm_phase(PG8_LAS unsigned char* lds, const Gemm g, const Sched& S, const Epi& E, const int tid) {
;     ...
;             PG8_WAIT_V(8); PG8_WAIT_L(0); PG8_BAR; PG8_MMA(1, 0, At, B0); PG8_MMA(1, 1, At, B1); PG8_BAR; PG8_SCHED;
;             PG8_LDB(B0, 1, 0); PG8_LDB(B1, 1, 1); PG8_SCHED; PG8_LDA(At, 1, 0); PG8_STAGE(PG8_SA(0, 1), a2 + hstepA, voffA);
;             PG8_WAIT_V(8); PG8_WAIT_L(0); PG8_BAR; PG8_MMA(0, 0, At, B0); PG8_MMA(0, 1, At, B1); PG8_BAR; PG8_SCHED;
	s_nop 0
	s_waitcnt lgkmcnt(0)
	v_mfma_f32_16x16x32_bf16 v[60:63], v[68:71], v[160:163], v[60:63]
	v_mfma_f32_16x16x32_bf16 v[56:59], v[80:83], v[160:163], v[56:59]
	v_mfma_f32_16x16x32_bf16 v[44:47], v[68:71], v[178:181], v[44:47]
	v_mfma_f32_16x16x32_bf16 v[40:43], v[80:83], v[178:181], v[40:43]
	v_mfma_f32_16x16x32_bf16 v[28:31], v[68:71], v[192:195], v[28:31]
	v_mfma_f32_16x16x32_bf16 v[24:27], v[80:83], v[192:195], v[24:27]
	v_mfma_f32_16x16x32_bf16 v[12:15], v[68:71], v[200:203], v[12:15]
	v_mfma_f32_16x16x32_bf16 v[8:11], v[80:83], v[200:203], v[8:11]
	v_mfma_f32_16x16x32_bf16 v[60:63], v[76:79], v[174:177], v[60:63]
	v_mfma_f32_16x16x32_bf16 v[56:59], v[84:87], v[174:177], v[56:59]
	v_mfma_f32_16x16x32_bf16 v[44:47], v[76:79], v[182:185], v[44:47]
	v_mfma_f32_16x16x32_bf16 v[40:43], v[84:87], v[182:185], v[40:43]
	v_mfma_f32_16x16x32_bf16 v[28:31], v[76:79], v[196:199], v[28:31]
	v_mfma_f32_16x16x32_bf16 v[24:27], v[84:87], v[196:199], v[24:27]
	v_mfma_f32_16x16x32_bf16 v[12:15], v[76:79], v[204:207], v[12:15]
	v_mfma_f32_16x16x32_bf16 v[8:11], v[84:87], v[204:207], v[8:11]
	s_nop 0
	s_nop 0
	v_mfma_f32_16x16x32_bf16 v[52:55], v[144:147], v[160:163], v[52:55]
	v_mfma_f32_16x16x32_bf16 v[48:51], v[152:155], v[160:163], v[48:51]
	v_mfma_f32_16x16x32_bf16 v[36:39], v[144:147], v[178:181], v[36:39]
	v_mfma_f32_16x16x32_bf16 v[32:35], v[152:155], v[178:181], v[32:35]
	v_mfma_f32_16x16x32_bf16 v[20:23], v[144:147], v[192:195], v[20:23]
	v_mfma_f32_16x16x32_bf16 v[16:19], v[152:155], v[192:195], v[16:19]
	v_mfma_f32_16x16x32_bf16 v[4:7], v[144:147], v[200:203], v[4:7]
	v_mfma_f32_16x16x32_bf16 v[0:3], v[152:155], v[200:203], v[0:3]
	v_mfma_f32_16x16x32_bf16 v[52:55], v[148:151], v[174:177], v[52:55]
	v_mfma_f32_16x16x32_bf16 v[48:51], v[156:159], v[174:177], v[48:51]
	v_mfma_f32_16x16x32_bf16 v[36:39], v[148:151], v[182:185], v[36:39]
	v_mfma_f32_16x16x32_bf16 v[32:35], v[156:159], v[182:185], v[32:35]
	v_mfma_f32_16x16x32_bf16 v[20:23], v[148:151], v[196:199], v[20:23]
	v_mfma_f32_16x16x32_bf16 v[16:19], v[156:159], v[196:199], v[16:19]
	v_mfma_f32_16x16x32_bf16 v[4:7], v[148:151], v[204:207], v[4:7]
	v_mfma_f32_16x16x32_bf16 v[0:3], v[156:159], v[204:207], v[0:3]
	s_nop 0
	s_barrier
	s_add_i32 s16, 0, 0x18000
	s_add_i32 s30, 0, 0x1c000
	v_add_u32_e32 v84, s16, v189
	v_add_u32_e32 v156, s30, v189
	ds_read_b128 v[68:71], v84
	ds_read_b128 v[76:79], v84 offset:1024
	ds_read_b128 v[80:83], v84 offset:2048
	ds_read_b128 v[84:87], v84 offset:3072
	ds_read_b128 v[144:147], v156
	ds_read_b128 v[148:151], v156 offset:1024
	ds_read_b128 v[152:155], v156 offset:2048
	ds_read_b128 v[156:159], v156 offset:3072
	s_add_u32 s52, s72, 0x40000
	s_addc_u32 s53, s73, 0
	s_mov_b32 m0, s93
	v_lshl_add_u64 v[220:221], s[52:53], 0, v[164:165]
	ds_read_b128 v[160:163], v190 offset:32768
	ds_read_b128 v[174:177], v190 offset:33792
	ds_read_b128 v[178:181], v190 offset:34816
	ds_read_b128 v[182:185], v190 offset:35840
	ds_read_b128 v[192:195], v190 offset:36864
	ds_read_b128 v[196:199], v190 offset:37888
	ds_read_b128 v[200:203], v190 offset:38912
	ds_read_b128 v[204:207], v190 offset:39936
	global_load_lds_dwordx4 v[220:221], off
	v_lshl_add_u64 v[220:221], s[52:53], 0, v[166:167]
	s_mov_b32 m0, s94
	s_nop 0
	global_load_lds_dwordx4 v[220:221], off
	s_waitcnt vmcnt(8)
	s_waitcnt lgkmcnt(0)
	s_barrier
	s_nop 0
	s_waitcnt lgkmcnt(0)
	v_mfma_f32_16x16x32_bf16 v[140:143], v[68:71], v[160:163], v[140:143]
	v_mfma_f32_16x16x32_bf16 v[136:139], v[80:83], v[160:163], v[136:139]
	v_mfma_f32_16x16x32_bf16 v[124:127], v[68:71], v[178:181], v[124:127]
	v_mfma_f32_16x16x32_bf16 v[120:123], v[80:83], v[178:181], v[120:123]
	v_mfma_f32_16x16x32_bf16 v[108:111], v[68:71], v[192:195], v[108:111]
	v_mfma_f32_16x16x32_bf16 v[104:107], v[80:83], v[192:195], v[104:107]
	v_mfma_f32_16x16x32_bf16 v[92:95], v[68:71], v[200:203], v[92:95]
	v_mfma_f32_16x16x32_bf16 v[88:91], v[80:83], v[200:203], v[88:91]
	v_mfma_f32_16x16x32_bf16 v[140:143], v[76:79], v[174:177], v[140:143]
	v_mfma_f32_16x16x32_bf16 v[136:139], v[84:87], v[174:177], v[136:139]
	v_mfma_f32_16x16x32_bf16 v[124:127], v[76:79], v[182:185], v[124:127]
	v_mfma_f32_16x16x32_bf16 v[120:123], v[84:87], v[182:185], v[120:123]
	v_mfma_f32_16x16x32_bf16 v[108:111], v[76:79], v[196:199], v[108:111]
	v_mfma_f32_16x16x32_bf16 v[104:107], v[84:87], v[196:199], v[104:107]
	v_mfma_f32_16x16x32_bf16 v[92:95], v[76:79], v[204:207], v[92:95]
	v_mfma_f32_16x16x32_bf16 v[88:91], v[84:87], v[204:207], v[88:91]
	s_nop 0
	s_nop 0
	v_mfma_f32_16x16x32_bf16 v[132:135], v[144:147], v[160:163], v[132:135]
	v_mfma_f32_16x16x32_bf16 v[128:131], v[152:155], v[160:163], v[128:131]
	v_mfma_f32_16x16x32_bf16 v[116:119], v[144:147], v[178:181], v[116:119]
	v_mfma_f32_16x16x32_bf16 v[112:115], v[152:155], v[178:181], v[112:115]
	v_mfma_f32_16x16x32_bf16 v[100:103], v[144:147], v[192:195], v[100:103]
	v_mfma_f32_16x16x32_bf16 v[96:99], v[152:155], v[192:195], v[96:99]
	v_mfma_f32_16x16x32_bf16 v[72:75], v[144:147], v[200:203], v[72:75]
	v_mfma_f32_16x16x32_bf16 v[64:67], v[152:155], v[200:203], v[64:67]
	v_mfma_f32_16x16x32_bf16 v[132:135], v[148:151], v[174:177], v[132:135]
	v_mfma_f32_16x16x32_bf16 v[128:131], v[156:159], v[174:177], v[128:131]
	v_mfma_f32_16x16x32_bf16 v[116:119], v[148:151], v[182:185], v[116:119]
	v_mfma_f32_16x16x32_bf16 v[112:115], v[156:159], v[182:185], v[112:115]
	v_mfma_f32_16x16x32_bf16 v[100:103], v[148:151], v[196:199], v[100:103]
	v_mfma_f32_16x16x32_bf16 v[96:99], v[156:159], v[196:199], v[96:99]
	v_mfma_f32_16x16x32_bf16 v[72:75], v[148:151], v[204:207], v[72:75]
	v_mfma_f32_16x16x32_bf16 v[64:67], v[156:159], v[204:207], v[64:67]
	s_nop 0
	s_barrier
; #define PG8_STAGE(bufoff, gbase, voff) do { _Pragma("unroll") for (int _i = 0; _i < 2; ++_i) \
;         __builtin_amdgcn_global_load_lds((const unsigned*)((const char*)(gbase) + (voff)[_i]), (PG8_LAS unsigned*)(lds + (bufoff) + ldsw + _i * 8192), 16, 0, 0); } while (0)
; #define PG8_LDA(dst, b, h) do { _Pragma("unroll") for (int m = 0; m < 4; ++m) _Pragma("unroll") for (int k = 0; k < 2; ++k) dst[m][k] = *(const PG8_LAS bf16x8*)(lds + PG8_SA(b, h) + aoff + m * 2048 + k * 1024); } while (0)
; #define PG8_MMA(ai, bj, At, Bt) do { __builtin_amdgcn_s_setprio(1); _Pragma("unroll") for (int m = 0; m < 4; ++m) _Pragma("unroll") for (int n = 0; n < 2; ++n) _Pragma("unroll") for (int k = 0; k < 2; ++k) \
;         acc[ai][bj][m][n] = __builtin_amdgcn_mfma_f32_16x16x32_bf16(Bt[n][k], At[m][k], acc[ai][bj][m][n], 0, 0, 0); __builtin_amdgcn_s_setprio(0); } while (0)
; #define PG8_WAIT_V(n) asm volatile("s_waitcnt vmcnt(" #n ")" ::: "memory")
; #define PG8_WAIT_L(n) asm volatile("s_waitcnt lgkmcnt(" #n ")" ::: "memory")
; #define PG8_BAR __builtin_amdgcn_s_barrier()
; #define PG8_SCHED __builtin_amdgcn_sched_barrier(0)
; template <class Epi, class Sched>
; __device__ __forceinline__ void gemm_phase(PG8_LAS unsigned char* lds, const Gemm g, const Sched& S, const Epi& E, const int tid) {
;     ...
;             PG8_LDA(At, 1, 1); PG8_STAGE(PG8_SB(1, 0), b3, voffB); PG8_STAGE(PG8_SB(1, 1), b3 + hstepB, voffB); PG8_STAGE(PG8_SA(1, 0), a3, voffA);
;             PG8_WAIT_V(8); PG8_WAIT_L(0); PG8_BAR; PG8_MMA(1, 0, At, B0); PG8_MMA(1, 1, At, B1); PG8_BAR; PG8_SCHED;
;         }
	s_add_i32 s16, s16, s90
	v_lshl_add_u64 v[208:209], v[208:209], 0, s[10:11]
	s_mov_b32 m0, s16
	ds_read_b128 v[160:163], v190 offset:49152
	ds_read_b128 v[174:177], v190 offset:50176
	ds_read_b128 v[178:181], v190 offset:51200
	ds_read_b128 v[182:185], v190 offset:52224
	ds_read_b128 v[192:195], v190 offset:53248
	ds_read_b128 v[196:199], v190 offset:54272
	ds_read_b128 v[200:203], v190 offset:55296
	ds_read_b128 v[204:207], v190 offset:56320
	global_load_lds_dwordx4 v[208:209], off
	s_add_i32 m0, s16, 0x2000
	s_add_u32 s48, s48, 0x40080
	v_lshl_add_u64 v[208:209], v[210:211], 0, s[10:11]
	s_addc_u32 s49, s49, 0
	s_add_i32 s16, s30, s90
	global_load_lds_dwordx4 v[208:209], off
	v_lshl_add_u64 v[208:209], s[48:49], 0, v[212:213]
	s_mov_b32 m0, s16
	s_nop 0
	global_load_lds_dwordx4 v[208:209], off
	v_lshl_add_u64 v[208:209], s[48:49], 0, v[168:169]
	s_add_i32 m0, s16, 0x2000
	s_nop 0
	global_load_lds_dwordx4 v[208:209], off
	v_lshl_add_u64 v[208:209], v[216:217], 0, s[10:11]
	s_mov_b32 m0, s69
	s_nop 0
	global_load_lds_dwordx4 v[208:209], off
	v_lshl_add_u64 v[208:209], v[218:219], 0, s[10:11]
	s_mov_b32 m0, s50
	s_nop 0
	global_load_lds_dwordx4 v[208:209], off
	s_waitcnt vmcnt(8)
	s_waitcnt lgkmcnt(0)
	s_barrier
	s_nop 0
	s_waitcnt lgkmcnt(0)
	v_mfma_f32_16x16x32_bf16 v[60:63], v[68:71], v[160:163], v[60:63]
	v_mfma_f32_16x16x32_bf16 v[56:59], v[80:83], v[160:163], v[56:59]
	v_mfma_f32_16x16x32_bf16 v[44:47], v[68:71], v[178:181], v[44:47]
	v_mfma_f32_16x16x32_bf16 v[40:43], v[80:83], v[178:181], v[40:43]
	v_mfma_f32_16x16x32_bf16 v[28:31], v[68:71], v[192:195], v[28:31]
	v_mfma_f32_16x16x32_bf16 v[24:27], v[80:83], v[192:195], v[24:27]
	v_mfma_f32_16x16x32_bf16 v[12:15], v[68:71], v[200:203], v[12:15]
	v_mfma_f32_16x16x32_bf16 v[8:11], v[80:83], v[200:203], v[8:11]
	v_mfma_f32_16x16x32_bf16 v[60:63], v[76:79], v[174:177], v[60:63]
	v_mfma_f32_16x16x32_bf16 v[56:59], v[84:87], v[174:177], v[56:59]
	v_mfma_f32_16x16x32_bf16 v[44:47], v[76:79], v[182:185], v[44:47]
	v_mfma_f32_16x16x32_bf16 v[40:43], v[84:87], v[182:185], v[40:43]
	v_mfma_f32_16x16x32_bf16 v[28:31], v[76:79], v[196:199], v[28:31]
	v_mfma_f32_16x16x32_bf16 v[24:27], v[84:87], v[196:199], v[24:27]
	v_mfma_f32_16x16x32_bf16 v[12:15], v[76:79], v[204:207], v[12:15]
	v_mfma_f32_16x16x32_bf16 v[8:11], v[84:87], v[204:207], v[8:11]
	s_nop 0
	s_nop 0
	v_mfma_f32_16x16x32_bf16 v[52:55], v[144:147], v[160:163], v[52:55]
	v_mfma_f32_16x16x32_bf16 v[48:51], v[152:155], v[160:163], v[48:51]
	v_mfma_f32_16x16x32_bf16 v[36:39], v[144:147], v[178:181], v[36:39]
	v_mfma_f32_16x16x32_bf16 v[32:35], v[152:155], v[178:181], v[32:35]
	v_mfma_f32_16x16x32_bf16 v[20:23], v[144:147], v[192:195], v[20:23]
	v_mfma_f32_16x16x32_bf16 v[16:19], v[152:155], v[192:195], v[16:19]
	v_mfma_f32_16x16x32_bf16 v[4:7], v[144:147], v[200:203], v[4:7]
	v_mfma_f32_16x16x32_bf16 v[0:3], v[152:155], v[200:203], v[0:3]
	v_mfma_f32_16x16x32_bf16 v[52:55], v[148:151], v[174:177], v[52:55]
	v_mfma_f32_16x16x32_bf16 v[48:51], v[156:159], v[174:177], v[48:51]
	v_mfma_f32_16x16x32_bf16 v[36:39], v[148:151], v[182:185], v[36:39]
	v_mfma_f32_16x16x32_bf16 v[32:35], v[156:159], v[182:185], v[32:35]
	v_mfma_f32_16x16x32_bf16 v[20:23], v[148:151], v[196:199], v[20:23]
	v_mfma_f32_16x16x32_bf16 v[16:19], v[156:159], v[196:199], v[16:19]
	v_mfma_f32_16x16x32_bf16 v[4:7], v[148:151], v[204:207], v[4:7]
	v_mfma_f32_16x16x32_bf16 v[0:3], v[156:159], v[204:207], v[0:3]
	s_nop 0
	s_barrier
	s_add_i32 s33, s33, 2
	s_add_u32 s44, s44, 0x100
	s_addc_u32 s45, s45, 0
	s_add_u32 s22, s22, 0x100
	s_addc_u32 s23, s23, 0
	s_cmp_gt_u32 s33, 13
	s_cbranch_scc0 .LBB0_569
	s_and_b64 vcc, exec, s[36:37]
	s_cbranch_vccz .LBB0_572
	s_barrier

; #define PG8_STAGE(bufoff, gbase, voff) do { _Pragma("unroll") for (int _i = 0; _i < 2; ++_i) \
;         __builtin_amdgcn_global_load_lds((const unsigned*)((const char*)(gbase) + (voff)[_i]), (PG8_LAS unsigned*)(lds + (bufoff) + ldsw + _i * 8192), 16, 0, 0); } while (0)
; #define PG8_LDA(dst, b, h) do { _Pragma("unroll") for (int m = 0; m < 4; ++m) _Pragma("unroll") for (int k = 0; k < 2; ++k) dst[m][k] = *(const PG8_LAS bf16x8*)(lds + PG8_SA(b, h) + aoff + m * 2048 + k * 1024); } while (0)
; #define PG8_LDB(dst, b, h) do { _Pragma("unroll") for (int n = 0; n < 2; ++n) _Pragma("unroll") for (int k = 0; k < 2; ++k) dst[n][k] = *(const PG8_LAS bf16x8*)(lds + PG8_SB(b, h) + boff + n * 2048 + k * 1024); } while (0)
; #define PG8_MMA(ai, bj, At, Bt) do { __builtin_amdgcn_s_setprio(1); _Pragma("unroll") for (int m = 0; m < 4; ++m) _Pragma("unroll") for (int n = 0; n < 2; ++n) _Pragma("unroll") for (int k = 0; k < 2; ++k) \
;         acc[ai][bj][m][n] = __builtin_amdgcn_mfma_f32_16x16x32_bf16(Bt[n][k], At[m][k], acc[ai][bj][m][n], 0, 0, 0); __builtin_amdgcn_s_setprio(0); } while (0)
; #define PG8_WAIT_V(n) asm volatile("s_waitcnt vmcnt(" #n ")" ::: "memory")
; #define PG8_WAIT_L(n) asm volatile("s_waitcnt lgkmcnt(" #n ")" ::: "memory")
; #define PG8_BAR __builtin_amdgcn_s_barrier()
; #define PG8_SCHED __builtin_amdgcn_sched_barrier(0)
; template <class Epi, class Sched>
; __device__ __forceinline__ void gemm_phase(PG8_LAS unsigned char* lds, const Gemm g, const Sched& S, const Epi& E, const int tid) {
;     ...
;             PG8_LDB(B0, 0, 0); PG8_LDB(B1, 0, 1); PG8_SCHED; PG8_LDA(At, 0, 0); PG8_STAGE(PG8_SA(1, 1), a1 + hstepA, voffA);
;             PG8_WAIT_V(8); PG8_WAIT_L(0); PG8_BAR; PG8_MMA(0, 0, At, B0); PG8_MMA(0, 1, At, B1); PG8_BAR; PG8_SCHED;
;             PG8_LDA(At, 0, 1); PG8_STAGE(PG8_SB(0, 0), b2, voffB); PG8_STAGE(PG8_SB(0, 1), b2 + hstepB, voffB); PG8_STAGE(PG8_SA(0, 0), a2, voffA);
;             PG8_WAIT_V(8); PG8_WAIT_L(0); PG8_BAR; PG8_MMA(1, 0, At, B0); PG8_MMA(1, 1, At, B1); PG8_BAR; PG8_SCHED;
.LBB0_1131:
	s_add_u32 s16, s42, 0xfffc0080
	s_addc_u32 s30, s43, -1
	s_add_i32 s41, 0, 0x10000
	s_cmp_eq_u32 s33, 12
	s_cselect_b32 s47, s1, s30
	s_cselect_b32 s46, s8, s16
	s_cselect_b32 s45, s19, s25
	s_cselect_b32 s44, s22, s23
	s_add_i32 s16, 0, 0x14000
	v_add_u32_e32 v68, s41, v230
	v_add_u32_e32 v156, s16, v230
	ds_read_b128 v[56:59], v68
	ds_read_b128 v[60:63], v68 offset:1024
	ds_read_b128 v[64:67], v68 offset:2048
	ds_read_b128 v[68:71], v68 offset:3072
	ds_read_b128 v[144:147], v156
	ds_read_b128 v[148:151], v156 offset:1024
	ds_read_b128 v[152:155], v156 offset:2048
	ds_read_b128 v[156:159], v156 offset:3072
	v_lshl_add_u64 v[202:203], s[42:43], 0, v[178:179]
	s_add_i32 m0, s57, 0xc000
	ds_read_b128 v[160:163], v231
	ds_read_b128 v[164:167], v231 offset:1024
	ds_read_b128 v[168:171], v231 offset:2048
	ds_read_b128 v[182:185], v231 offset:3072
	ds_read_b128 v[186:189], v231 offset:4096
	ds_read_b128 v[190:193], v231 offset:5120
	ds_read_b128 v[194:197], v231 offset:6144
	ds_read_b128 v[198:201], v231 offset:7168
	global_load_lds_dwordx4 v[202:203], off
	v_lshl_add_u64 v[202:203], s[42:43], 0, v[180:181]
	s_add_i32 m0, s57, 0xe000
	s_nop 0
	global_load_lds_dwordx4 v[202:203], off
	s_waitcnt vmcnt(8)
	s_waitcnt lgkmcnt(0)
	s_barrier
	s_nop 0
	s_waitcnt lgkmcnt(0)
	v_mfma_f32_16x16x32_bf16 v[140:143], v[56:59], v[160:163], v[140:143]
	v_mfma_f32_16x16x32_bf16 v[136:139], v[64:67], v[160:163], v[136:139]
	v_mfma_f32_16x16x32_bf16 v[124:127], v[56:59], v[168:171], v[124:127]
	v_mfma_f32_16x16x32_bf16 v[120:123], v[64:67], v[168:171], v[120:123]
	v_mfma_f32_16x16x32_bf16 v[108:111], v[56:59], v[186:189], v[108:111]
	v_mfma_f32_16x16x32_bf16 v[104:107], v[64:67], v[186:189], v[104:107]
	v_mfma_f32_16x16x32_bf16 v[92:95], v[56:59], v[194:197], v[92:95]
	v_mfma_f32_16x16x32_bf16 v[88:91], v[64:67], v[194:197], v[88:91]
	v_mfma_f32_16x16x32_bf16 v[140:143], v[60:63], v[164:167], v[140:143]
	v_mfma_f32_16x16x32_bf16 v[136:139], v[68:71], v[164:167], v[136:139]
	v_mfma_f32_16x16x32_bf16 v[124:127], v[60:63], v[182:185], v[124:127]
	v_mfma_f32_16x16x32_bf16 v[120:123], v[68:71], v[182:185], v[120:123]
	v_mfma_f32_16x16x32_bf16 v[108:111], v[60:63], v[190:193], v[108:111]
	v_mfma_f32_16x16x32_bf16 v[104:107], v[68:71], v[190:193], v[104:107]
	v_mfma_f32_16x16x32_bf16 v[92:95], v[60:63], v[198:201], v[92:95]
	v_mfma_f32_16x16x32_bf16 v[88:91], v[68:71], v[198:201], v[88:91]
	s_nop 0
	s_nop 0
	v_mfma_f32_16x16x32_bf16 v[132:135], v[144:147], v[160:163], v[132:135]
	v_mfma_f32_16x16x32_bf16 v[128:131], v[152:155], v[160:163], v[128:131]
	v_mfma_f32_16x16x32_bf16 v[116:119], v[144:147], v[168:171], v[116:119]
	v_mfma_f32_16x16x32_bf16 v[112:115], v[152:155], v[168:171], v[112:115]
	v_mfma_f32_16x16x32_bf16 v[100:103], v[144:147], v[186:189], v[100:103]
	v_mfma_f32_16x16x32_bf16 v[96:99], v[152:155], v[186:189], v[96:99]
	v_mfma_f32_16x16x32_bf16 v[84:87], v[144:147], v[194:197], v[84:87]
	v_mfma_f32_16x16x32_bf16 v[80:83], v[152:155], v[194:197], v[80:83]
	v_mfma_f32_16x16x32_bf16 v[132:135], v[148:151], v[164:167], v[132:135]
	v_mfma_f32_16x16x32_bf16 v[128:131], v[156:159], v[164:167], v[128:131]
	v_mfma_f32_16x16x32_bf16 v[116:119], v[148:151], v[182:185], v[116:119]
	v_mfma_f32_16x16x32_bf16 v[112:115], v[156:159], v[182:185], v[112:115]
	v_mfma_f32_16x16x32_bf16 v[100:103], v[148:151], v[190:193], v[100:103]
	v_mfma_f32_16x16x32_bf16 v[96:99], v[156:159], v[190:193], v[96:99]
	v_mfma_f32_16x16x32_bf16 v[84:87], v[148:151], v[198:201], v[84:87]
	v_mfma_f32_16x16x32_bf16 v[80:83], v[156:159], v[198:201], v[80:83]
	s_nop 0
	s_barrier
	s_add_i32 s30, s41, s56
	v_lshl_add_u64 v[202:203], s[44:45], 0, v[212:213]
	s_mov_b32 m0, s30
	ds_read_b128 v[160:163], v231 offset:16384
	ds_read_b128 v[164:167], v231 offset:17408
	ds_read_b128 v[168:171], v231 offset:18432
	ds_read_b128 v[182:185], v231 offset:19456
	ds_read_b128 v[186:189], v231 offset:20480
	ds_read_b128 v[190:193], v231 offset:21504
	ds_read_b128 v[194:197], v231 offset:22528
	ds_read_b128 v[198:201], v231 offset:23552
	global_load_lds_dwordx4 v[202:203], off
	s_add_i32 m0, s30, 0x2000
	s_add_u32 s52, s44, 0x40000
	v_lshl_add_u64 v[204:205], s[44:45], 0, v[176:177]
	s_addc_u32 s53, s45, 0
	s_add_i32 s16, s16, s56
	global_load_lds_dwordx4 v[204:205], off
	v_lshl_add_u64 v[206:207], s[52:53], 0, v[212:213]
	s_mov_b32 m0, s16
	v_lshl_add_u64 v[208:209], s[46:47], 0, v[174:175]
	global_load_lds_dwordx4 v[206:207], off
	v_lshl_add_u64 v[206:207], s[52:53], 0, v[176:177]
	s_add_i32 m0, s16, 0x2000
	s_nop 0
	global_load_lds_dwordx4 v[206:207], off
	v_lshl_add_u64 v[206:207], s[46:47], 0, v[172:173]
	s_mov_b32 m0, s57
	s_nop 0
	global_load_lds_dwordx4 v[206:207], off
	s_mov_b32 m0, s58
	s_nop 0
	global_load_lds_dwordx4 v[208:209], off
	s_waitcnt vmcnt(8)
	s_waitcnt lgkmcnt(0)
	s_barrier
; #define PG8_STAGE(bufoff, gbase, voff) do { _Pragma("unroll") for (int _i = 0; _i < 2; ++_i) \
;         __builtin_amdgcn_global_load_lds((const unsigned*)((const char*)(gbase) + (voff)[_i]), (PG8_LAS unsigned*)(lds + (bufoff) + ldsw + _i * 8192), 16, 0, 0); } while (0)
; #define PG8_LDA(dst, b, h) do { _Pragma("unroll") for (int m = 0; m < 4; ++m) _Pragma("unroll") for (int k = 0; k < 2; ++k) dst[m][k] = *(const PG8_LAS bf16x8*)(lds + PG8_SA(b, h) + aoff + m * 2048 + k * 1024); } while (0)
; #define PG8_LDB(dst, b, h) do { _Pragma("unroll") for (int n = 0; n < 2; ++n) _Pragma("unroll") for (int k = 0; k < 2; ++k) dst[n][k] = *(const PG8_LAS bf16x8*)(lds + PG8_SB(b, h) + boff + n * 2048 + k * 1024); } while (0)
; #define PG8_WAIT_V(n) asm volatile("s_waitcnt vmcnt(" #n ")" ::: "memory")
; template <class Epi, class Sched>
; __device__ __forceinline__ void gemm_phase(PG8_LAS unsigned char* lds, const Gemm g, const Sched& S, const Epi& E, const int tid) {
;     ...
;         for (int t = 0; t < ntc; t += 2) {
;             const bool last = (t == ntc - 2);
;             const char* a1 = cA + (size_t)(t + 1) * kstep;
;             const char* a2 = last ? nA : cA + (size_t)(t + 2) * kstep; const char* b2 = last ? nB : cB + (size_t)(t + 2) * kstep;
;             const char* a3 = a2 + kstep; const char* b3 = b2 + kstep;
;             PG8_LDB(B0, 0, 0); PG8_LDB(B1, 0, 1); PG8_SCHED; PG8_LDA(At, 0, 0); PG8_STAGE(PG8_SA(1, 1), a1 + hstepA, voffA);
;             PG8_WAIT_V(8); PG8_WAIT_L(0); PG8_BAR; PG8_MMA(0, 0, At, B0); PG8_MMA(0, 1, At, B1); PG8_BAR; PG8_SCHED;
;             PG8_LDA(At, 0, 1); PG8_STAGE(PG8_SB(0, 0), b2, voffB); PG8_STAGE(PG8_SB(0, 1), b2 + hstepB, voffB); PG8_STAGE(PG8_SA(0, 0), a2, voffA);
;             PG8_WAIT_V(8); PG8_WAIT_L(0); PG8_BAR; PG8_MMA(1, 0, At, B0); PG8_MMA(1, 1, At, B1); PG8_BAR; PG8_SCHED;
;             PG8_LDB(B0, 1, 0); PG8_LDB(B1, 1, 1); PG8_SCHED; PG8_LDA(At, 1, 0); PG8_STAGE(PG8_SA(0, 1), a2 + hstepA, voffA);
;             PG8_WAIT_V(8); PG8_WAIT_L(0); PG8_BAR; PG8_MMA(0, 0, At, B0); PG8_MMA(0, 1, At, B1); PG8_BAR; PG8_SCHED;
;             PG8_LDA(At, 1, 1); PG8_STAGE(PG8_SB(1, 0), b3, voffB); PG8_STAGE(PG8_SB(1, 1), b3 + hstepB, voffB); PG8_STAGE(PG8_SA(1, 0), a3, voffA);
;             PG8_WAIT_V(8); PG8_WAIT_L(0); PG8_BAR; PG8_MMA(1, 0, At, B0); PG8_MMA(1, 1, At, B1); PG8_BAR; PG8_SCHED;
	s_nop 0
	s_waitcnt lgkmcnt(0)
	v_mfma_f32_16x16x32_bf16 v[76:79], v[56:59], v[160:163], v[76:79]
	v_mfma_f32_16x16x32_bf16 v[72:75], v[64:67], v[160:163], v[72:75]
	v_mfma_f32_16x16x32_bf16 v[44:47], v[56:59], v[168:171], v[44:47]
	v_mfma_f32_16x16x32_bf16 v[40:43], v[64:67], v[168:171], v[40:43]
	v_mfma_f32_16x16x32_bf16 v[28:31], v[56:59], v[186:189], v[28:31]
	v_mfma_f32_16x16x32_bf16 v[24:27], v[64:67], v[186:189], v[24:27]
	v_mfma_f32_16x16x32_bf16 v[12:15], v[56:59], v[194:197], v[12:15]
	v_mfma_f32_16x16x32_bf16 v[8:11], v[64:67], v[194:197], v[8:11]
	v_mfma_f32_16x16x32_bf16 v[76:79], v[60:63], v[164:167], v[76:79]
	v_mfma_f32_16x16x32_bf16 v[72:75], v[68:71], v[164:167], v[72:75]
	v_mfma_f32_16x16x32_bf16 v[44:47], v[60:63], v[182:185], v[44:47]
	v_mfma_f32_16x16x32_bf16 v[40:43], v[68:71], v[182:185], v[40:43]
	v_mfma_f32_16x16x32_bf16 v[28:31], v[60:63], v[190:193], v[28:31]
	v_mfma_f32_16x16x32_bf16 v[24:27], v[68:71], v[190:193], v[24:27]
	v_mfma_f32_16x16x32_bf16 v[12:15], v[60:63], v[198:201], v[12:15]
	v_mfma_f32_16x16x32_bf16 v[8:11], v[68:71], v[198:201], v[8:11]
	s_nop 0
	s_nop 0
	v_mfma_f32_16x16x32_bf16 v[52:55], v[144:147], v[160:163], v[52:55]
	v_mfma_f32_16x16x32_bf16 v[48:51], v[152:155], v[160:163], v[48:51]
	v_mfma_f32_16x16x32_bf16 v[36:39], v[144:147], v[168:171], v[36:39]
	v_mfma_f32_16x16x32_bf16 v[32:35], v[152:155], v[168:171], v[32:35]
	v_mfma_f32_16x16x32_bf16 v[20:23], v[144:147], v[186:189], v[20:23]
	v_mfma_f32_16x16x32_bf16 v[16:19], v[152:155], v[186:189], v[16:19]
	v_mfma_f32_16x16x32_bf16 v[4:7], v[144:147], v[194:197], v[4:7]
	v_mfma_f32_16x16x32_bf16 v[0:3], v[152:155], v[194:197], v[0:3]
	v_mfma_f32_16x16x32_bf16 v[52:55], v[148:151], v[164:167], v[52:55]
	v_mfma_f32_16x16x32_bf16 v[48:51], v[156:159], v[164:167], v[48:51]
	v_mfma_f32_16x16x32_bf16 v[36:39], v[148:151], v[182:185], v[36:39]
	v_mfma_f32_16x16x32_bf16 v[32:35], v[156:159], v[182:185], v[32:35]
	v_mfma_f32_16x16x32_bf16 v[20:23], v[148:151], v[190:193], v[20:23]
	v_mfma_f32_16x16x32_bf16 v[16:19], v[156:159], v[190:193], v[16:19]
	v_mfma_f32_16x16x32_bf16 v[4:7], v[148:151], v[198:201], v[4:7]
	v_mfma_f32_16x16x32_bf16 v[0:3], v[156:159], v[198:201], v[0:3]
	s_nop 0
	s_barrier
	s_add_i32 s16, 0, 0x18000
	s_add_i32 s30, 0, 0x1c000
	v_add_u32_e32 v68, s16, v230
	v_add_u32_e32 v156, s30, v230
	ds_read_b128 v[56:59], v68
	ds_read_b128 v[60:63], v68 offset:1024
	ds_read_b128 v[64:67], v68 offset:2048
	ds_read_b128 v[68:71], v68 offset:3072
	ds_read_b128 v[144:147], v156
	ds_read_b128 v[148:151], v156 offset:1024
	ds_read_b128 v[152:155], v156 offset:2048
	ds_read_b128 v[156:159], v156 offset:3072
	s_add_u32 s46, s46, 0x40000
	s_addc_u32 s47, s47, 0
	s_mov_b32 m0, s59
	v_lshl_add_u64 v[210:211], s[46:47], 0, v[172:173]
	ds_read_b128 v[160:163], v231 offset:32768
	ds_read_b128 v[164:167], v231 offset:33792
	ds_read_b128 v[168:171], v231 offset:34816
	ds_read_b128 v[182:185], v231 offset:35840
	ds_read_b128 v[186:189], v231 offset:36864
	ds_read_b128 v[190:193], v231 offset:37888
	ds_read_b128 v[194:197], v231 offset:38912
	ds_read_b128 v[198:201], v231 offset:39936
	global_load_lds_dwordx4 v[210:211], off
	v_lshl_add_u64 v[210:211], s[46:47], 0, v[174:175]
	s_mov_b32 m0, s60
	s_nop 0
	global_load_lds_dwordx4 v[210:211], off
	s_waitcnt vmcnt(8)
	s_waitcnt lgkmcnt(0)
	s_barrier
	s_nop 0
	s_waitcnt lgkmcnt(0)
	v_mfma_f32_16x16x32_bf16 v[140:143], v[56:59], v[160:163], v[140:143]
	v_mfma_f32_16x16x32_bf16 v[136:139], v[64:67], v[160:163], v[136:139]
	v_mfma_f32_16x16x32_bf16 v[124:127], v[56:59], v[168:171], v[124:127]
	v_mfma_f32_16x16x32_bf16 v[120:123], v[64:67], v[168:171], v[120:123]
	v_mfma_f32_16x16x32_bf16 v[108:111], v[56:59], v[186:189], v[108:111]
	v_mfma_f32_16x16x32_bf16 v[104:107], v[64:67], v[186:189], v[104:107]
	v_mfma_f32_16x16x32_bf16 v[92:95], v[56:59], v[194:197], v[92:95]
	v_mfma_f32_16x16x32_bf16 v[88:91], v[64:67], v[194:197], v[88:91]
	v_mfma_f32_16x16x32_bf16 v[140:143], v[60:63], v[164:167], v[140:143]
	v_mfma_f32_16x16x32_bf16 v[136:139], v[68:71], v[164:167], v[136:139]
	v_mfma_f32_16x16x32_bf16 v[124:127], v[60:63], v[182:185], v[124:127]
	v_mfma_f32_16x16x32_bf16 v[120:123], v[68:71], v[182:185], v[120:123]
	v_mfma_f32_16x16x32_bf16 v[108:111], v[60:63], v[190:193], v[108:111]
	v_mfma_f32_16x16x32_bf16 v[104:107], v[68:71], v[190:193], v[104:107]
	v_mfma_f32_16x16x32_bf16 v[92:95], v[60:63], v[198:201], v[92:95]
	v_mfma_f32_16x16x32_bf16 v[88:91], v[68:71], v[198:201], v[88:91]
	s_nop 0
	s_nop 0
	v_mfma_f32_16x16x32_bf16 v[132:135], v[144:147], v[160:163], v[132:135]
	v_mfma_f32_16x16x32_bf16 v[128:131], v[152:155], v[160:163], v[128:131]
	v_mfma_f32_16x16x32_bf16 v[116:119], v[144:147], v[168:171], v[116:119]
	v_mfma_f32_16x16x32_bf16 v[112:115], v[152:155], v[168:171], v[112:115]
	v_mfma_f32_16x16x32_bf16 v[100:103], v[144:147], v[186:189], v[100:103]
	v_mfma_f32_16x16x32_bf16 v[96:99], v[152:155], v[186:189], v[96:99]
	v_mfma_f32_16x16x32_bf16 v[84:87], v[144:147], v[194:197], v[84:87]
	v_mfma_f32_16x16x32_bf16 v[80:83], v[152:155], v[194:197], v[80:83]
	v_mfma_f32_16x16x32_bf16 v[132:135], v[148:151], v[164:167], v[132:135]
	v_mfma_f32_16x16x32_bf16 v[128:131], v[156:159], v[164:167], v[128:131]
	v_mfma_f32_16x16x32_bf16 v[116:119], v[148:151], v[182:185], v[116:119]
	v_mfma_f32_16x16x32_bf16 v[112:115], v[156:159], v[182:185], v[112:115]
	v_mfma_f32_16x16x32_bf16 v[100:103], v[148:151], v[190:193], v[100:103]
	v_mfma_f32_16x16x32_bf16 v[96:99], v[156:159], v[190:193], v[96:99]
	v_mfma_f32_16x16x32_bf16 v[84:87], v[148:151], v[198:201], v[84:87]
	v_mfma_f32_16x16x32_bf16 v[80:83], v[156:159], v[198:201], v[80:83]
	s_nop 0
	s_barrier
; #define PG8_STAGE(bufoff, gbase, voff) do { _Pragma("unroll") for (int _i = 0; _i < 2; ++_i) \
;         __builtin_amdgcn_global_load_lds((const unsigned*)((const char*)(gbase) + (voff)[_i]), (PG8_LAS unsigned*)(lds + (bufoff) + ldsw + _i * 8192), 16, 0, 0); } while (0)
; #define PG8_LDA(dst, b, h) do { _Pragma("unroll") for (int m = 0; m < 4; ++m) _Pragma("unroll") for (int k = 0; k < 2; ++k) dst[m][k] = *(const PG8_LAS bf16x8*)(lds + PG8_SA(b, h) + aoff + m * 2048 + k * 1024); } while (0)
; #define PG8_LDB(dst, b, h) do { _Pragma("unroll") for (int n = 0; n < 2; ++n) _Pragma("unroll") for (int k = 0; k < 2; ++k) dst[n][k] = *(const PG8_LAS bf16x8*)(lds + PG8_SB(b, h) + boff + n * 2048 + k * 1024); } while (0)
; #define PG8_MMA(ai, bj, At, Bt) do { __builtin_amdgcn_s_setprio(1); _Pragma("unroll") for (int m = 0; m < 4; ++m) _Pragma("unroll") for (int n = 0; n < 2; ++n) _Pragma("unroll") for (int k = 0; k < 2; ++k) \
;         acc[ai][bj][m][n] = __builtin_amdgcn_mfma_f32_16x16x32_bf16(Bt[n][k], At[m][k], acc[ai][bj][m][n], 0, 0, 0); __builtin_amdgcn_s_setprio(0); } while (0)
; #define PG8_BAR __builtin_amdgcn_s_barrier()
; template <class Epi, class Sched>
; __device__ __forceinline__ void gemm_phase(PG8_LAS unsigned char* lds, const Gemm g, const Sched& S, const Epi& E, const int tid) {
;     ...
;             PG8_LDB(B0, 0, 0); PG8_LDB(B1, 0, 1); PG8_SCHED; PG8_LDA(At, 0, 0); PG8_STAGE(PG8_SA(1, 1), a1 + hstepA, voffA);
;             PG8_WAIT_V(8); PG8_WAIT_L(0); PG8_BAR; PG8_MMA(0, 0, At, B0); PG8_MMA(0, 1, At, B1); PG8_BAR; PG8_SCHED;
;             PG8_LDA(At, 0, 1); PG8_STAGE(PG8_SB(0, 0), b2, voffB); PG8_STAGE(PG8_SB(0, 1), b2 + hstepB, voffB); PG8_STAGE(PG8_SA(0, 0), a2, voffA);
;             PG8_WAIT_V(8); PG8_WAIT_L(0); PG8_BAR; PG8_MMA(1, 0, At, B0); PG8_MMA(1, 1, At, B1); PG8_BAR; PG8_SCHED;
;             PG8_LDB(B0, 1, 0); PG8_LDB(B1, 1, 1); PG8_SCHED; PG8_LDA(At, 1, 0); PG8_STAGE(PG8_SA(0, 1), a2 + hstepA, voffA);
;             PG8_WAIT_V(8); PG8_WAIT_L(0); PG8_BAR; PG8_MMA(0, 0, At, B0); PG8_MMA(0, 1, At, B1); PG8_BAR; PG8_SCHED;
;             PG8_LDA(At, 1, 1); PG8_STAGE(PG8_SB(1, 0), b3, voffB); PG8_STAGE(PG8_SB(1, 1), b3 + hstepB, voffB); PG8_STAGE(PG8_SA(1, 0), a3, voffA);
;             PG8_WAIT_V(8); PG8_WAIT_L(0); PG8_BAR; PG8_MMA(1, 0, At, B0); PG8_MMA(1, 1, At, B1); PG8_BAR; PG8_SCHED;
;         }
;         if (wr == 0) PG8_BAR;
	s_add_i32 s16, s16, s56
	v_lshl_add_u64 v[202:203], v[202:203], 0, s[10:11]
	s_mov_b32 m0, s16
	ds_read_b128 v[160:163], v231 offset:49152
	ds_read_b128 v[164:167], v231 offset:50176
	ds_read_b128 v[168:171], v231 offset:51200
	ds_read_b128 v[182:185], v231 offset:52224
	ds_read_b128 v[186:189], v231 offset:53248
	ds_read_b128 v[190:193], v231 offset:54272
	ds_read_b128 v[194:197], v231 offset:55296
	ds_read_b128 v[198:201], v231 offset:56320
	global_load_lds_dwordx4 v[202:203], off
	s_add_i32 m0, s16, 0x2000
	s_add_u32 s44, s44, 0x40080
	v_lshl_add_u64 v[202:203], v[204:205], 0, s[10:11]
	s_addc_u32 s45, s45, 0
	s_add_i32 s16, s30, s56
	global_load_lds_dwordx4 v[202:203], off
	v_lshl_add_u64 v[202:203], s[44:45], 0, v[212:213]
	s_mov_b32 m0, s16
	s_nop 0
	global_load_lds_dwordx4 v[202:203], off
	v_lshl_add_u64 v[202:203], s[44:45], 0, v[176:177]
	s_add_i32 m0, s16, 0x2000
	s_nop 0
	global_load_lds_dwordx4 v[202:203], off
	v_lshl_add_u64 v[202:203], v[206:207], 0, s[10:11]
	s_mov_b32 m0, s71
	s_nop 0
	global_load_lds_dwordx4 v[202:203], off
	v_lshl_add_u64 v[202:203], v[208:209], 0, s[10:11]
	s_mov_b32 m0, s72
	s_nop 0
	global_load_lds_dwordx4 v[202:203], off
	s_waitcnt vmcnt(8)
	s_waitcnt lgkmcnt(0)
	s_barrier
	s_nop 0
	s_waitcnt lgkmcnt(0)
	v_mfma_f32_16x16x32_bf16 v[76:79], v[56:59], v[160:163], v[76:79]
	v_mfma_f32_16x16x32_bf16 v[72:75], v[64:67], v[160:163], v[72:75]
	v_mfma_f32_16x16x32_bf16 v[44:47], v[56:59], v[168:171], v[44:47]
	v_mfma_f32_16x16x32_bf16 v[40:43], v[64:67], v[168:171], v[40:43]
	v_mfma_f32_16x16x32_bf16 v[28:31], v[56:59], v[186:189], v[28:31]
	v_mfma_f32_16x16x32_bf16 v[24:27], v[64:67], v[186:189], v[24:27]
	v_mfma_f32_16x16x32_bf16 v[12:15], v[56:59], v[194:197], v[12:15]
	v_mfma_f32_16x16x32_bf16 v[8:11], v[64:67], v[194:197], v[8:11]
	v_mfma_f32_16x16x32_bf16 v[76:79], v[60:63], v[164:167], v[76:79]
	v_mfma_f32_16x16x32_bf16 v[72:75], v[68:71], v[164:167], v[72:75]
	v_mfma_f32_16x16x32_bf16 v[44:47], v[60:63], v[182:185], v[44:47]
	v_mfma_f32_16x16x32_bf16 v[40:43], v[68:71], v[182:185], v[40:43]
	v_mfma_f32_16x16x32_bf16 v[28:31], v[60:63], v[190:193], v[28:31]
	v_mfma_f32_16x16x32_bf16 v[24:27], v[68:71], v[190:193], v[24:27]
	v_mfma_f32_16x16x32_bf16 v[12:15], v[60:63], v[198:201], v[12:15]
	v_mfma_f32_16x16x32_bf16 v[8:11], v[68:71], v[198:201], v[8:11]
	s_nop 0
	s_nop 0
	v_mfma_f32_16x16x32_bf16 v[52:55], v[144:147], v[160:163], v[52:55]
	v_mfma_f32_16x16x32_bf16 v[48:51], v[152:155], v[160:163], v[48:51]
	v_mfma_f32_16x16x32_bf16 v[36:39], v[144:147], v[168:171], v[36:39]
	v_mfma_f32_16x16x32_bf16 v[32:35], v[152:155], v[168:171], v[32:35]
	v_mfma_f32_16x16x32_bf16 v[20:23], v[144:147], v[186:189], v[20:23]
	v_mfma_f32_16x16x32_bf16 v[16:19], v[152:155], v[186:189], v[16:19]
	v_mfma_f32_16x16x32_bf16 v[4:7], v[144:147], v[194:197], v[4:7]
	v_mfma_f32_16x16x32_bf16 v[0:3], v[152:155], v[194:197], v[0:3]
	v_mfma_f32_16x16x32_bf16 v[52:55], v[148:151], v[164:167], v[52:55]
	v_mfma_f32_16x16x32_bf16 v[48:51], v[156:159], v[164:167], v[48:51]
	v_mfma_f32_16x16x32_bf16 v[36:39], v[148:151], v[182:185], v[36:39]
	v_mfma_f32_16x16x32_bf16 v[32:35], v[156:159], v[182:185], v[32:35]
	v_mfma_f32_16x16x32_bf16 v[20:23], v[148:151], v[190:193], v[20:23]
	v_mfma_f32_16x16x32_bf16 v[16:19], v[156:159], v[190:193], v[16:19]
	v_mfma_f32_16x16x32_bf16 v[4:7], v[148:151], v[198:201], v[4:7]
	v_mfma_f32_16x16x32_bf16 v[0:3], v[156:159], v[198:201], v[0:3]
	s_nop 0
	s_barrier
	s_add_i32 s33, s33, 2
	s_add_u32 s42, s42, 0x100
	s_addc_u32 s43, s43, 0
	s_add_u32 s23, s23, 0x100
	s_addc_u32 s25, s25, 0
	s_cmp_gt_u32 s33, 13
	s_cbranch_scc0 .LBB0_1131
	s_and_b64 vcc, exec, s[14:15]
	s_cbranch_vccz .LBB0_1134
	s_barrier

; #define PG8_STAGE(bufoff, gbase, voff) do { _Pragma("unroll") for (int _i = 0; _i < 2; ++_i) \
;         __builtin_amdgcn_global_load_lds((const unsigned*)((const char*)(gbase) + (voff)[_i]), (PG8_LAS unsigned*)(lds + (bufoff) + ldsw + _i * 8192), 16, 0, 0); } while (0)
; #define PG8_LDA(dst, b, h) do { _Pragma("unroll") for (int m = 0; m < 4; ++m) _Pragma("unroll") for (int k = 0; k < 2; ++k) dst[m][k] = *(const PG8_LAS bf16x8*)(lds + PG8_SA(b, h) + aoff + m * 2048 + k * 1024); } while (0)
; #define PG8_WAIT_V(n) asm volatile("s_waitcnt vmcnt(" #n ")" ::: "memory")
; template <class Epi, class Sched>
; __device__ __forceinline__ void gemm_phase(PG8_LAS unsigned char* lds, const Gemm g, const Sched& S, const Epi& E, const int tid) {
;     ...
;         const char* nA = has_next ? (const char*)g.A + (size_t)nxt.pm * tstepA + (size_t)nxt.pn * g.a_pn_off + S.koff(nxt) : cA; const char* nB = has_next ? (const char*)g.Bt + (size_t)nxt.pn * tstepB + S.koff(nxt) : cB;
;         const int ntc = S.nt(cur, nt);
;         for (int t = 0; t < ntc; t += 2) {
;             const bool last = (t == ntc - 2);
;             const char* a1 = cA + (size_t)(t + 1) * kstep;
;             const char* a2 = last ? nA : cA + (size_t)(t + 2) * kstep; const char* b2 = last ? nB : cB + (size_t)(t + 2) * kstep;
;             const char* a3 = a2 + kstep; const char* b3 = b2 + kstep;
;             PG8_LDB(B0, 0, 0); PG8_LDB(B1, 0, 1); PG8_SCHED; PG8_LDA(At, 0, 0); PG8_STAGE(PG8_SA(1, 1), a1 + hstepA, voffA);
;             PG8_WAIT_V(8); PG8_WAIT_L(0); PG8_BAR; PG8_MMA(0, 0, At, B0); PG8_MMA(0, 1, At, B1); PG8_BAR; PG8_SCHED;
;             PG8_LDA(At, 0, 1); PG8_STAGE(PG8_SB(0, 0), b2, voffB); PG8_STAGE(PG8_SB(0, 1), b2 + hstepB, voffB); PG8_STAGE(PG8_SA(0, 0), a2, voffA);
;             PG8_WAIT_V(8); PG8_WAIT_L(0); PG8_BAR; PG8_MMA(1, 0, At, B0); PG8_MMA(1, 1, At, B1); PG8_BAR; PG8_SCHED;
;             PG8_LDB(B0, 1, 0); PG8_LDB(B1, 1, 1); PG8_SCHED; PG8_LDA(At, 1, 0); PG8_STAGE(PG8_SA(0, 1), a2 + hstepA, voffA);
;             PG8_WAIT_V(8); PG8_WAIT_L(0); PG8_BAR; PG8_MMA(0, 0, At, B0); PG8_MMA(0, 1, At, B1); PG8_BAR; PG8_SCHED;
;             PG8_LDA(At, 1, 1); PG8_STAGE(PG8_SB(1, 0), b3, voffB); PG8_STAGE(PG8_SB(1, 1), b3 + hstepB, voffB); PG8_STAGE(PG8_SA(1, 0), a3, voffA);
;             PG8_WAIT_V(8); PG8_WAIT_L(0); PG8_BAR; PG8_MMA(1, 0, At, B0); PG8_MMA(1, 1, At, B1); PG8_BAR; PG8_SCHED;
.LBB0_1392:
	s_add_u32 s16, s72, s45
	s_addc_u32 s30, s73, 0
	s_add_u32 s54, s16, 0x100
	s_addc_u32 s55, s30, 0
	s_and_b64 s[52:53], s[74:75], exec
	s_cselect_b32 s79, s65, s55
	s_cselect_b32 s78, s64, s54
	s_add_u32 s45, s70, s45
	s_addc_u32 s52, s71, 0
	s_add_u32 s45, s45, 0x100
	s_addc_u32 s54, s52, 0
	s_add_i32 s84, 0, 0x10000
	s_and_b64 s[52:53], s[74:75], exec
	s_cselect_b32 s81, s8, s54
	s_cselect_b32 s80, s19, s45
	s_add_i32 s75, 0, 0x14000
	s_add_u32 s82, s16, 0x40080
	s_addc_u32 s83, s30, 0
	s_add_i32 s53, s84, s87
	s_add_i32 m0, s2, 0xc000
	s_add_i32 s92, s2, 0xe000
	s_add_i32 s30, s53, 0x2000
	s_add_u32 vcc_lo, s80, 0x10000
	v_add_u32_e32 v68, s84, v251
	v_add_u32_e32 v156, s75, v251
	s_addc_u32 vcc_hi, s81, 0
	s_add_i32 s54, s75, s87
	ds_read_b128 v[48:51], v68
	ds_read_b128 v[52:55], v68 offset:1024
	ds_read_b128 v[64:67], v68 offset:2048
	ds_read_b128 v[68:71], v68 offset:3072
	ds_read_b128 v[136:139], v156
	ds_read_b128 v[148:151], v156 offset:1024
	ds_read_b128 v[152:155], v156 offset:2048
	ds_read_b128 v[156:159], v156 offset:3072
	s_add_i32 s55, s54, 0x2000
	s_add_i32 s61, 0, 0x18000
	s_add_i32 s63, 0, 0x1c000
	s_add_u32 s76, s78, 0x40000
	s_addc_u32 s77, s79, 0
	s_add_i32 s45, s61, s87
	s_add_i32 s52, s45, 0x2000
	s_add_u32 s74, s80, 0x10080
	s_addc_u32 s75, s81, 0
	s_add_i32 s84, s63, s87
	s_add_i32 s16, s84, 0x2000
	v_lshl_add_u64 v[192:193], s[82:83], 0, v[220:221]
	ds_read_b128 v[160:163], v252
	ds_read_b128 v[164:167], v252 offset:1024
	ds_read_b128 v[168:171], v252 offset:2048
	ds_read_b128 v[172:175], v252 offset:3072
	ds_read_b128 v[176:179], v252 offset:4096
	ds_read_b128 v[180:183], v252 offset:5120
	ds_read_b128 v[184:187], v252 offset:6144
	ds_read_b128 v[188:191], v252 offset:7168
	global_load_lds_dwordx4 v[192:193], off
	v_lshl_add_u64 v[192:193], s[82:83], 0, v[222:223]
	s_mov_b32 m0, s92
	s_nop 0
	global_load_lds_dwordx4 v[192:193], off
	s_waitcnt vmcnt(8)
	s_waitcnt lgkmcnt(0)
	s_barrier
	s_nop 0
	s_waitcnt lgkmcnt(0)
	v_mfma_f32_16x16x32_bf16 v[144:147], v[48:51], v[160:163], v[144:147]
	v_mfma_f32_16x16x32_bf16 v[140:143], v[64:67], v[160:163], v[140:143]
	v_mfma_f32_16x16x32_bf16 v[124:127], v[48:51], v[168:171], v[124:127]
	v_mfma_f32_16x16x32_bf16 v[120:123], v[64:67], v[168:171], v[120:123]
	v_mfma_f32_16x16x32_bf16 v[108:111], v[48:51], v[176:179], v[108:111]
	v_mfma_f32_16x16x32_bf16 v[104:107], v[64:67], v[176:179], v[104:107]
	v_mfma_f32_16x16x32_bf16 v[92:95], v[48:51], v[184:187], v[92:95]
	v_mfma_f32_16x16x32_bf16 v[88:91], v[64:67], v[184:187], v[88:91]
	v_mfma_f32_16x16x32_bf16 v[144:147], v[52:55], v[164:167], v[144:147]
	v_mfma_f32_16x16x32_bf16 v[140:143], v[68:71], v[164:167], v[140:143]
	v_mfma_f32_16x16x32_bf16 v[124:127], v[52:55], v[172:175], v[124:127]
	v_mfma_f32_16x16x32_bf16 v[120:123], v[68:71], v[172:175], v[120:123]
	v_mfma_f32_16x16x32_bf16 v[108:111], v[52:55], v[180:183], v[108:111]
	v_mfma_f32_16x16x32_bf16 v[104:107], v[68:71], v[180:183], v[104:107]
	v_mfma_f32_16x16x32_bf16 v[92:95], v[52:55], v[188:191], v[92:95]
	v_mfma_f32_16x16x32_bf16 v[88:91], v[68:71], v[188:191], v[88:91]
	s_nop 0
	s_nop 0
	v_mfma_f32_16x16x32_bf16 v[132:135], v[136:139], v[160:163], v[132:135]
	v_mfma_f32_16x16x32_bf16 v[128:131], v[152:155], v[160:163], v[128:131]
	v_mfma_f32_16x16x32_bf16 v[116:119], v[136:139], v[168:171], v[116:119]
	v_mfma_f32_16x16x32_bf16 v[112:115], v[152:155], v[168:171], v[112:115]
	v_mfma_f32_16x16x32_bf16 v[100:103], v[136:139], v[176:179], v[100:103]
	v_mfma_f32_16x16x32_bf16 v[96:99], v[152:155], v[176:179], v[96:99]
	v_mfma_f32_16x16x32_bf16 v[84:87], v[136:139], v[184:187], v[84:87]
	v_mfma_f32_16x16x32_bf16 v[80:83], v[152:155], v[184:187], v[80:83]
	v_mfma_f32_16x16x32_bf16 v[132:135], v[148:151], v[164:167], v[132:135]
	v_mfma_f32_16x16x32_bf16 v[128:131], v[156:159], v[164:167], v[128:131]
	v_mfma_f32_16x16x32_bf16 v[116:119], v[148:151], v[172:175], v[116:119]
	v_mfma_f32_16x16x32_bf16 v[112:115], v[156:159], v[172:175], v[112:115]
	v_mfma_f32_16x16x32_bf16 v[100:103], v[148:151], v[180:183], v[100:103]
	v_mfma_f32_16x16x32_bf16 v[96:99], v[156:159], v[180:183], v[96:99]
	v_mfma_f32_16x16x32_bf16 v[84:87], v[148:151], v[188:191], v[84:87]
	v_mfma_f32_16x16x32_bf16 v[80:83], v[156:159], v[188:191], v[80:83]
	s_nop 0
	s_barrier
	s_mov_b32 m0, s53
	v_lshl_add_u64 v[192:193], s[80:81], 0, v[212:213]
	ds_read_b128 v[160:163], v252 offset:16384
	ds_read_b128 v[164:167], v252 offset:17408
	ds_read_b128 v[168:171], v252 offset:18432
	ds_read_b128 v[172:175], v252 offset:19456
	ds_read_b128 v[176:179], v252 offset:20480
	ds_read_b128 v[180:183], v252 offset:21504
	ds_read_b128 v[184:187], v252 offset:22528
	ds_read_b128 v[188:191], v252 offset:23552
	global_load_lds_dwordx4 v[192:193], off
	v_lshl_add_u64 v[194:195], s[80:81], 0, v[224:225]
	s_mov_b32 m0, s30
	v_lshl_add_u64 v[196:197], vcc, 0, v[212:213]
	global_load_lds_dwordx4 v[194:195], off
	s_mov_b32 m0, s54
	v_lshl_add_u64 v[198:199], s[78:79], 0, v[222:223]
	global_load_lds_dwordx4 v[196:197], off
	v_lshl_add_u64 v[196:197], vcc, 0, v[224:225]
	s_mov_b32 m0, s55
	s_nop 0
	global_load_lds_dwordx4 v[196:197], off
	v_lshl_add_u64 v[196:197], s[78:79], 0, v[220:221]
	s_mov_b32 m0, s2
	s_nop 0
	global_load_lds_dwordx4 v[196:197], off
	s_mov_b32 m0, s93
	s_nop 0
	global_load_lds_dwordx4 v[198:199], off
	s_waitcnt vmcnt(8)
	s_waitcnt lgkmcnt(0)
	s_barrier
; #define PG8_STAGE(bufoff, gbase, voff) do { _Pragma("unroll") for (int _i = 0; _i < 2; ++_i) \
;         __builtin_amdgcn_global_load_lds((const unsigned*)((const char*)(gbase) + (voff)[_i]), (PG8_LAS unsigned*)(lds + (bufoff) + ldsw + _i * 8192), 16, 0, 0); } while (0)
; #define PG8_LDA(dst, b, h) do { _Pragma("unroll") for (int m = 0; m < 4; ++m) _Pragma("unroll") for (int k = 0; k < 2; ++k) dst[m][k] = *(const PG8_LAS bf16x8*)(lds + PG8_SA(b, h) + aoff + m * 2048 + k * 1024); } while (0)
; #define PG8_LDB(dst, b, h) do { _Pragma("unroll") for (int n = 0; n < 2; ++n) _Pragma("unroll") for (int k = 0; k < 2; ++k) dst[n][k] = *(const PG8_LAS bf16x8*)(lds + PG8_SB(b, h) + boff + n * 2048 + k * 1024); } while (0)
; #define PG8_MMA(ai, bj, At, Bt) do { __builtin_amdgcn_s_setprio(1); _Pragma("unroll") for (int m = 0; m < 4; ++m) _Pragma("unroll") for (int n = 0; n < 2; ++n) _Pragma("unroll") for (int k = 0; k < 2; ++k) \
;         acc[ai][bj][m][n] = __builtin_amdgcn_mfma_f32_16x16x32_bf16(Bt[n][k], At[m][k], acc[ai][bj][m][n], 0, 0, 0); __builtin_amdgcn_s_setprio(0); } while (0)
; #define PG8_WAIT_V(n) asm volatile("s_waitcnt vmcnt(" #n ")" ::: "memory")
; #define PG8_WAIT_L(n) asm volatile("s_waitcnt lgkmcnt(" #n ")" ::: "memory")
; #define PG8_BAR __builtin_amdgcn_s_barrier()
; #define PG8_SCHED __builtin_amdgcn_sched_barrier(0)
; template <class Epi, class Sched>
; __device__ __forceinline__ void gemm_phase(PG8_LAS unsigned char* lds, const Gemm g, const Sched& S, const Epi& E, const int tid) {
;     ...
;             PG8_WAIT_V(8); PG8_WAIT_L(0); PG8_BAR; PG8_MMA(0, 0, At, B0); PG8_MMA(0, 1, At, B1); PG8_BAR; PG8_SCHED;
;             PG8_LDA(At, 0, 1); PG8_STAGE(PG8_SB(0, 0), b2, voffB); PG8_STAGE(PG8_SB(0, 1), b2 + hstepB, voffB); PG8_STAGE(PG8_SA(0, 0), a2, voffA);
;             PG8_WAIT_V(8); PG8_WAIT_L(0); PG8_BAR; PG8_MMA(1, 0, At, B0); PG8_MMA(1, 1, At, B1); PG8_BAR; PG8_SCHED;
;             PG8_LDB(B0, 1, 0); PG8_LDB(B1, 1, 1); PG8_SCHED; PG8_LDA(At, 1, 0); PG8_STAGE(PG8_SA(0, 1), a2 + hstepA, voffA);
;             PG8_WAIT_V(8); PG8_WAIT_L(0); PG8_BAR; PG8_MMA(0, 0, At, B0); PG8_MMA(0, 1, At, B1); PG8_BAR; PG8_SCHED;
	s_nop 0
	s_waitcnt lgkmcnt(0)
	v_mfma_f32_16x16x32_bf16 v[76:79], v[48:51], v[160:163], v[76:79]
	v_mfma_f32_16x16x32_bf16 v[72:75], v[64:67], v[160:163], v[72:75]
	v_mfma_f32_16x16x32_bf16 v[44:47], v[48:51], v[168:171], v[44:47]
	v_mfma_f32_16x16x32_bf16 v[40:43], v[64:67], v[168:171], v[40:43]
	v_mfma_f32_16x16x32_bf16 v[28:31], v[48:51], v[176:179], v[28:31]
	v_mfma_f32_16x16x32_bf16 v[24:27], v[64:67], v[176:179], v[24:27]
	v_mfma_f32_16x16x32_bf16 v[12:15], v[48:51], v[184:187], v[12:15]
	v_mfma_f32_16x16x32_bf16 v[8:11], v[64:67], v[184:187], v[8:11]
	v_mfma_f32_16x16x32_bf16 v[76:79], v[52:55], v[164:167], v[76:79]
	v_mfma_f32_16x16x32_bf16 v[72:75], v[68:71], v[164:167], v[72:75]
	v_mfma_f32_16x16x32_bf16 v[44:47], v[52:55], v[172:175], v[44:47]
	v_mfma_f32_16x16x32_bf16 v[40:43], v[68:71], v[172:175], v[40:43]
	v_mfma_f32_16x16x32_bf16 v[28:31], v[52:55], v[180:183], v[28:31]
	v_mfma_f32_16x16x32_bf16 v[24:27], v[68:71], v[180:183], v[24:27]
	v_mfma_f32_16x16x32_bf16 v[12:15], v[52:55], v[188:191], v[12:15]
	v_mfma_f32_16x16x32_bf16 v[8:11], v[68:71], v[188:191], v[8:11]
	s_nop 0
	s_nop 0
	v_mfma_f32_16x16x32_bf16 v[36:39], v[136:139], v[168:171], v[36:39]
	v_mfma_f32_16x16x32_bf16 v[32:35], v[152:155], v[168:171], v[32:35]
	v_mfma_f32_16x16x32_bf16 v[20:23], v[136:139], v[176:179], v[20:23]
	v_mfma_f32_16x16x32_bf16 v[16:19], v[152:155], v[176:179], v[16:19]
	v_mfma_f32_16x16x32_bf16 v[4:7], v[136:139], v[184:187], v[4:7]
	v_mfma_f32_16x16x32_bf16 v[0:3], v[152:155], v[184:187], v[0:3]
	v_mfma_f32_16x16x32_bf16 v[48:51], v[136:139], v[160:163], v[60:63]
	v_mfma_f32_16x16x32_bf16 v[52:55], v[152:155], v[160:163], v[56:59]
	v_mfma_f32_16x16x32_bf16 v[36:39], v[148:151], v[172:175], v[36:39]
	v_mfma_f32_16x16x32_bf16 v[32:35], v[156:159], v[172:175], v[32:35]
	v_mfma_f32_16x16x32_bf16 v[20:23], v[148:151], v[180:183], v[20:23]
	v_mfma_f32_16x16x32_bf16 v[16:19], v[156:159], v[180:183], v[16:19]
	v_mfma_f32_16x16x32_bf16 v[4:7], v[148:151], v[188:191], v[4:7]
	v_mfma_f32_16x16x32_bf16 v[0:3], v[156:159], v[188:191], v[0:3]
	v_mfma_f32_16x16x32_bf16 v[48:51], v[148:151], v[164:167], v[48:51]
	v_mfma_f32_16x16x32_bf16 v[52:55], v[156:159], v[164:167], v[52:55]
	s_nop 0
	s_barrier
	v_add_u32_e32 v68, s61, v251
	v_add_u32_e32 v156, s63, v251
	ds_read_b128 v[56:59], v68
	ds_read_b128 v[60:63], v68 offset:1024
	ds_read_b128 v[64:67], v68 offset:2048
	ds_read_b128 v[68:71], v68 offset:3072
	ds_read_b128 v[136:139], v156
	ds_read_b128 v[148:151], v156 offset:1024
	ds_read_b128 v[152:155], v156 offset:2048
	ds_read_b128 v[156:159], v156 offset:3072
	s_mov_b32 m0, s94
	v_lshl_add_u64 v[200:201], s[76:77], 0, v[220:221]
	ds_read_b128 v[160:163], v252 offset:32768
	ds_read_b128 v[164:167], v252 offset:33792
	ds_read_b128 v[168:171], v252 offset:34816
	ds_read_b128 v[172:175], v252 offset:35840
	ds_read_b128 v[176:179], v252 offset:36864
	ds_read_b128 v[180:183], v252 offset:37888
	ds_read_b128 v[184:187], v252 offset:38912
	ds_read_b128 v[188:191], v252 offset:39936
	global_load_lds_dwordx4 v[200:201], off
	v_lshl_add_u64 v[200:201], s[76:77], 0, v[222:223]
	s_mov_b32 m0, s95
	s_nop 0
	global_load_lds_dwordx4 v[200:201], off
	s_waitcnt vmcnt(8)
	s_waitcnt lgkmcnt(0)
	s_barrier
	s_nop 0
	s_waitcnt lgkmcnt(0)
	v_mfma_f32_16x16x32_bf16 v[144:147], v[56:59], v[160:163], v[144:147]
	v_mfma_f32_16x16x32_bf16 v[140:143], v[64:67], v[160:163], v[140:143]
	v_mfma_f32_16x16x32_bf16 v[124:127], v[56:59], v[168:171], v[124:127]
	v_mfma_f32_16x16x32_bf16 v[120:123], v[64:67], v[168:171], v[120:123]
	v_mfma_f32_16x16x32_bf16 v[108:111], v[56:59], v[176:179], v[108:111]
	v_mfma_f32_16x16x32_bf16 v[104:107], v[64:67], v[176:179], v[104:107]
	v_mfma_f32_16x16x32_bf16 v[92:95], v[56:59], v[184:187], v[92:95]
	v_mfma_f32_16x16x32_bf16 v[88:91], v[64:67], v[184:187], v[88:91]
	v_mfma_f32_16x16x32_bf16 v[144:147], v[60:63], v[164:167], v[144:147]
	v_mfma_f32_16x16x32_bf16 v[140:143], v[68:71], v[164:167], v[140:143]
	v_mfma_f32_16x16x32_bf16 v[124:127], v[60:63], v[172:175], v[124:127]
	v_mfma_f32_16x16x32_bf16 v[120:123], v[68:71], v[172:175], v[120:123]
	v_mfma_f32_16x16x32_bf16 v[108:111], v[60:63], v[180:183], v[108:111]
	v_mfma_f32_16x16x32_bf16 v[104:107], v[68:71], v[180:183], v[104:107]
	v_mfma_f32_16x16x32_bf16 v[92:95], v[60:63], v[188:191], v[92:95]
	v_mfma_f32_16x16x32_bf16 v[88:91], v[68:71], v[188:191], v[88:91]
	s_nop 0
	s_nop 0
	v_mfma_f32_16x16x32_bf16 v[132:135], v[136:139], v[160:163], v[132:135]
	v_mfma_f32_16x16x32_bf16 v[128:131], v[152:155], v[160:163], v[128:131]
	v_mfma_f32_16x16x32_bf16 v[116:119], v[136:139], v[168:171], v[116:119]
	v_mfma_f32_16x16x32_bf16 v[112:115], v[152:155], v[168:171], v[112:115]
	v_mfma_f32_16x16x32_bf16 v[100:103], v[136:139], v[176:179], v[100:103]
	v_mfma_f32_16x16x32_bf16 v[96:99], v[152:155], v[176:179], v[96:99]
	v_mfma_f32_16x16x32_bf16 v[84:87], v[136:139], v[184:187], v[84:87]
	v_mfma_f32_16x16x32_bf16 v[80:83], v[152:155], v[184:187], v[80:83]
	v_mfma_f32_16x16x32_bf16 v[132:135], v[148:151], v[164:167], v[132:135]
	v_mfma_f32_16x16x32_bf16 v[128:131], v[156:159], v[164:167], v[128:131]
	v_mfma_f32_16x16x32_bf16 v[116:119], v[148:151], v[172:175], v[116:119]
	v_mfma_f32_16x16x32_bf16 v[112:115], v[156:159], v[172:175], v[112:115]
	v_mfma_f32_16x16x32_bf16 v[100:103], v[148:151], v[180:183], v[100:103]
	v_mfma_f32_16x16x32_bf16 v[96:99], v[156:159], v[180:183], v[96:99]
	v_mfma_f32_16x16x32_bf16 v[84:87], v[148:151], v[188:191], v[84:87]
	v_mfma_f32_16x16x32_bf16 v[80:83], v[156:159], v[188:191], v[80:83]
	s_nop 0
	s_barrier
; #define PG8_STAGE(bufoff, gbase, voff) do { _Pragma("unroll") for (int _i = 0; _i < 2; ++_i) \
;         __builtin_amdgcn_global_load_lds((const unsigned*)((const char*)(gbase) + (voff)[_i]), (PG8_LAS unsigned*)(lds + (bufoff) + ldsw + _i * 8192), 16, 0, 0); } while (0)
; #define PG8_LDA(dst, b, h) do { _Pragma("unroll") for (int m = 0; m < 4; ++m) _Pragma("unroll") for (int k = 0; k < 2; ++k) dst[m][k] = *(const PG8_LAS bf16x8*)(lds + PG8_SA(b, h) + aoff + m * 2048 + k * 1024); } while (0)
; #define PG8_MMA(ai, bj, At, Bt) do { __builtin_amdgcn_s_setprio(1); _Pragma("unroll") for (int m = 0; m < 4; ++m) _Pragma("unroll") for (int n = 0; n < 2; ++n) _Pragma("unroll") for (int k = 0; k < 2; ++k) \
;         acc[ai][bj][m][n] = __builtin_amdgcn_mfma_f32_16x16x32_bf16(Bt[n][k], At[m][k], acc[ai][bj][m][n], 0, 0, 0); __builtin_amdgcn_s_setprio(0); } while (0)
; #define PG8_WAIT_V(n) asm volatile("s_waitcnt vmcnt(" #n ")" ::: "memory")
; #define PG8_WAIT_L(n) asm volatile("s_waitcnt lgkmcnt(" #n ")" ::: "memory")
; #define PG8_BAR __builtin_amdgcn_s_barrier()
; #define PG8_SCHED __builtin_amdgcn_sched_barrier(0)
; template <class Epi, class Sched>
; __device__ __forceinline__ void gemm_phase(PG8_LAS unsigned char* lds, const Gemm g, const Sched& S, const Epi& E, const int tid) {
;     ...
;             PG8_LDA(At, 1, 1); PG8_STAGE(PG8_SB(1, 0), b3, voffB); PG8_STAGE(PG8_SB(1, 1), b3 + hstepB, voffB); PG8_STAGE(PG8_SA(1, 0), a3, voffA);
;             PG8_WAIT_V(8); PG8_WAIT_L(0); PG8_BAR; PG8_MMA(1, 0, At, B0); PG8_MMA(1, 1, At, B1); PG8_BAR; PG8_SCHED;
;         }
;         if (wr == 0) PG8_BAR;
	s_mov_b32 m0, s45
	v_lshl_add_u64 v[192:193], v[192:193], 0, s[10:11]
	ds_read_b128 v[160:163], v252 offset:49152
	ds_read_b128 v[164:167], v252 offset:50176
	ds_read_b128 v[168:171], v252 offset:51200
	ds_read_b128 v[172:175], v252 offset:52224
	ds_read_b128 v[176:179], v252 offset:53248
	ds_read_b128 v[180:183], v252 offset:54272
	ds_read_b128 v[184:187], v252 offset:55296
	ds_read_b128 v[188:191], v252 offset:56320
	global_load_lds_dwordx4 v[192:193], off
	v_lshl_add_u64 v[192:193], v[194:195], 0, s[10:11]
	s_mov_b32 m0, s52
	s_nop 0
	global_load_lds_dwordx4 v[192:193], off
	v_lshl_add_u64 v[192:193], s[74:75], 0, v[212:213]
	s_mov_b32 m0, s84
	s_nop 0
	global_load_lds_dwordx4 v[192:193], off
	v_lshl_add_u64 v[192:193], s[74:75], 0, v[224:225]
	s_mov_b32 m0, s16
	s_nop 0
	global_load_lds_dwordx4 v[192:193], off
	v_lshl_add_u64 v[192:193], v[196:197], 0, s[10:11]
	s_mov_b32 m0, s17
	s_nop 0
	global_load_lds_dwordx4 v[192:193], off
	v_lshl_add_u64 v[192:193], v[198:199], 0, s[10:11]
	s_mov_b32 m0, s20
	s_nop 0
	global_load_lds_dwordx4 v[192:193], off
	s_waitcnt vmcnt(8)
	s_waitcnt lgkmcnt(0)
	s_barrier
	s_nop 0
	s_waitcnt lgkmcnt(0)
	v_mfma_f32_16x16x32_bf16 v[76:79], v[56:59], v[160:163], v[76:79]
	v_mfma_f32_16x16x32_bf16 v[72:75], v[64:67], v[160:163], v[72:75]
	v_mfma_f32_16x16x32_bf16 v[44:47], v[56:59], v[168:171], v[44:47]
	v_mfma_f32_16x16x32_bf16 v[40:43], v[64:67], v[168:171], v[40:43]
	v_mfma_f32_16x16x32_bf16 v[28:31], v[56:59], v[176:179], v[28:31]
	v_mfma_f32_16x16x32_bf16 v[24:27], v[64:67], v[176:179], v[24:27]
	v_mfma_f32_16x16x32_bf16 v[12:15], v[56:59], v[184:187], v[12:15]
	v_mfma_f32_16x16x32_bf16 v[8:11], v[64:67], v[184:187], v[8:11]
	v_mfma_f32_16x16x32_bf16 v[76:79], v[60:63], v[164:167], v[76:79]
	v_mfma_f32_16x16x32_bf16 v[72:75], v[68:71], v[164:167], v[72:75]
	v_mfma_f32_16x16x32_bf16 v[44:47], v[60:63], v[172:175], v[44:47]
	v_mfma_f32_16x16x32_bf16 v[40:43], v[68:71], v[172:175], v[40:43]
	v_mfma_f32_16x16x32_bf16 v[28:31], v[60:63], v[180:183], v[28:31]
	v_mfma_f32_16x16x32_bf16 v[24:27], v[68:71], v[180:183], v[24:27]
	v_mfma_f32_16x16x32_bf16 v[12:15], v[60:63], v[188:191], v[12:15]
	v_mfma_f32_16x16x32_bf16 v[8:11], v[68:71], v[188:191], v[8:11]
	s_nop 0
	s_nop 0
	v_mfma_f32_16x16x32_bf16 v[48:51], v[136:139], v[160:163], v[48:51]
	v_mfma_f32_16x16x32_bf16 v[60:63], v[148:151], v[164:167], v[48:51]
	v_mfma_f32_16x16x32_bf16 v[48:51], v[152:155], v[160:163], v[52:55]
	v_mfma_f32_16x16x32_bf16 v[36:39], v[136:139], v[168:171], v[36:39]
	v_mfma_f32_16x16x32_bf16 v[32:35], v[152:155], v[168:171], v[32:35]
	v_mfma_f32_16x16x32_bf16 v[20:23], v[136:139], v[176:179], v[20:23]
	v_mfma_f32_16x16x32_bf16 v[16:19], v[152:155], v[176:179], v[16:19]
	v_mfma_f32_16x16x32_bf16 v[4:7], v[136:139], v[184:187], v[4:7]
	v_mfma_f32_16x16x32_bf16 v[0:3], v[152:155], v[184:187], v[0:3]
	v_mfma_f32_16x16x32_bf16 v[56:59], v[156:159], v[164:167], v[48:51]
	v_mfma_f32_16x16x32_bf16 v[36:39], v[148:151], v[172:175], v[36:39]
	v_mfma_f32_16x16x32_bf16 v[32:35], v[156:159], v[172:175], v[32:35]
	v_mfma_f32_16x16x32_bf16 v[20:23], v[148:151], v[180:183], v[20:23]
	v_mfma_f32_16x16x32_bf16 v[16:19], v[156:159], v[180:183], v[16:19]
	v_mfma_f32_16x16x32_bf16 v[4:7], v[148:151], v[188:191], v[4:7]
	v_mfma_f32_16x16x32_bf16 v[0:3], v[156:159], v[188:191], v[0:3]
	s_nop 0
	s_barrier
	s_movk_i32 s45, 0x100
	s_andn2_b64 vcc, exec, s[42:43]
	s_mov_b64 s[74:75], -1
	s_mov_b64 s[42:43], 0
	s_cbranch_vccz .LBB0_1392
	s_and_b64 vcc, exec, s[48:49]
	s_cbranch_vccz .LBB0_1395
	s_barrier

; #define PG8_STAGE(bufoff, gbase, voff) do { _Pragma("unroll") for (int _i = 0; _i < 2; ++_i) \
;         __builtin_amdgcn_global_load_lds((const unsigned*)((const char*)(gbase) + (voff)[_i]), (PG8_LAS unsigned*)(lds + (bufoff) + ldsw + _i * 8192), 16, 0, 0); } while (0)
; #define PG8_LDA(dst, b, h) do { _Pragma("unroll") for (int m = 0; m < 4; ++m) _Pragma("unroll") for (int k = 0; k < 2; ++k) dst[m][k] = *(const PG8_LAS bf16x8*)(lds + PG8_SA(b, h) + aoff + m * 2048 + k * 1024); } while (0)
; #define PG8_LDB(dst, b, h) do { _Pragma("unroll") for (int n = 0; n < 2; ++n) _Pragma("unroll") for (int k = 0; k < 2; ++k) dst[n][k] = *(const PG8_LAS bf16x8*)(lds + PG8_SB(b, h) + boff + n * 2048 + k * 1024); } while (0)
; #define PG8_MMA(ai, bj, At, Bt) do { __builtin_amdgcn_s_setprio(1); _Pragma("unroll") for (int m = 0; m < 4; ++m) _Pragma("unroll") for (int n = 0; n < 2; ++n) _Pragma("unroll") for (int k = 0; k < 2; ++k) \
;         acc[ai][bj][m][n] = __builtin_amdgcn_mfma_f32_16x16x32_bf16(Bt[n][k], At[m][k], acc[ai][bj][m][n], 0, 0, 0); __builtin_amdgcn_s_setprio(0); } while (0)
; #define PG8_WAIT_V(n) asm volatile("s_waitcnt vmcnt(" #n ")" ::: "memory")
; #define PG8_WAIT_L(n) asm volatile("s_waitcnt lgkmcnt(" #n ")" ::: "memory")
; #define PG8_BAR __builtin_amdgcn_s_barrier()
; #define PG8_SCHED __builtin_amdgcn_sched_barrier(0)
; template <class Epi, class Sched>
; __device__ __forceinline__ void gemm_phase(PG8_LAS unsigned char* lds, const Gemm g, const Sched& S, const Epi& E, const int tid) {
;     ...
;         const char* nA = has_next ? (const char*)g.A + (size_t)nxt.pm * tstepA + (size_t)nxt.pn * g.a_pn_off + S.koff(nxt) : cA; const char* nB = has_next ? (const char*)g.Bt + (size_t)nxt.pn * tstepB + S.koff(nxt) : cB;
;         const int ntc = S.nt(cur, nt);
;         for (int t = 0; t < ntc; t += 2) {
;             const bool last = (t == ntc - 2);
;             const char* a1 = cA + (size_t)(t + 1) * kstep;
;             const char* a2 = last ? nA : cA + (size_t)(t + 2) * kstep; const char* b2 = last ? nB : cB + (size_t)(t + 2) * kstep;
;             const char* a3 = a2 + kstep; const char* b3 = b2 + kstep;
;             PG8_LDB(B0, 0, 0); PG8_LDB(B1, 0, 1); PG8_SCHED; PG8_LDA(At, 0, 0); PG8_STAGE(PG8_SA(1, 1), a1 + hstepA, voffA);
;             PG8_WAIT_V(8); PG8_WAIT_L(0); PG8_BAR; PG8_MMA(0, 0, At, B0); PG8_MMA(0, 1, At, B1); PG8_BAR; PG8_SCHED;
.LBB0_1693:
	s_add_u32 s16, s44, 0xfffc0080
	s_addc_u32 s30, s45, -1
	s_add_i32 s52, 0, 0x10000
	s_cmp_eq_u32 s73, 12
	s_cselect_b32 s49, s35, s30
	s_cselect_b32 s48, s69, s16
	s_cselect_b32 s47, s25, s72
	s_cselect_b32 s46, s70, s71
	s_add_i32 s16, 0, 0x14000
	v_add_u32_e32 v140, s52, v204
	v_add_u32_e32 v156, s16, v204
	ds_read_b128 v[128:131], v140
	ds_read_b128 v[132:135], v140 offset:1024
	ds_read_b128 v[136:139], v140 offset:2048
	ds_read_b128 v[140:143], v140 offset:3072
	ds_read_b128 v[144:147], v156
	ds_read_b128 v[148:151], v156 offset:1024
	ds_read_b128 v[152:155], v156 offset:2048
	ds_read_b128 v[156:159], v156 offset:3072
	v_lshl_add_u64 v[196:197], s[44:45], 0, v[176:177]
	s_add_i32 m0, s59, 0xc000
	ds_read_b128 v[160:163], v206
	ds_read_b128 v[164:167], v206 offset:1024
	ds_read_b128 v[180:183], v206 offset:2048
	ds_read_b128 v[184:187], v206 offset:3072
	ds_read_b128 v[188:191], v206 offset:4096
	ds_read_b128 v[192:195], v206 offset:5120
	ds_read_b128 v[208:211], v206 offset:6144
	ds_read_b128 v[216:219], v206 offset:7168
	global_load_lds_dwordx4 v[196:197], off
	v_lshl_add_u64 v[196:197], s[44:45], 0, v[178:179]
	s_add_i32 m0, s59, 0xe000
	s_nop 0
	global_load_lds_dwordx4 v[196:197], off
	s_waitcnt vmcnt(8)
	s_waitcnt lgkmcnt(0)
	s_barrier
	s_nop 0
	s_waitcnt lgkmcnt(0)
	v_mfma_f32_16x16x32_bf16 v[124:127], v[128:131], v[160:163], v[124:127]
	v_mfma_f32_16x16x32_bf16 v[120:123], v[136:139], v[160:163], v[120:123]
	v_mfma_f32_16x16x32_bf16 v[108:111], v[128:131], v[180:183], v[108:111]
	v_mfma_f32_16x16x32_bf16 v[104:107], v[136:139], v[180:183], v[104:107]
	v_mfma_f32_16x16x32_bf16 v[92:95], v[128:131], v[188:191], v[92:95]
	v_mfma_f32_16x16x32_bf16 v[88:91], v[136:139], v[188:191], v[88:91]
	v_mfma_f32_16x16x32_bf16 v[76:79], v[128:131], v[208:211], v[76:79]
	v_mfma_f32_16x16x32_bf16 v[72:75], v[136:139], v[208:211], v[72:75]
	v_mfma_f32_16x16x32_bf16 v[124:127], v[132:135], v[164:167], v[124:127]
	v_mfma_f32_16x16x32_bf16 v[120:123], v[140:143], v[164:167], v[120:123]
	v_mfma_f32_16x16x32_bf16 v[108:111], v[132:135], v[184:187], v[108:111]
	v_mfma_f32_16x16x32_bf16 v[104:107], v[140:143], v[184:187], v[104:107]
	v_mfma_f32_16x16x32_bf16 v[92:95], v[132:135], v[192:195], v[92:95]
	v_mfma_f32_16x16x32_bf16 v[88:91], v[140:143], v[192:195], v[88:91]
	v_mfma_f32_16x16x32_bf16 v[76:79], v[132:135], v[216:219], v[76:79]
	v_mfma_f32_16x16x32_bf16 v[72:75], v[140:143], v[216:219], v[72:75]
	s_nop 0
	s_nop 0
	v_mfma_f32_16x16x32_bf16 v[116:119], v[144:147], v[160:163], v[116:119]
	v_mfma_f32_16x16x32_bf16 v[112:115], v[152:155], v[160:163], v[112:115]
	v_mfma_f32_16x16x32_bf16 v[100:103], v[144:147], v[180:183], v[100:103]
	v_mfma_f32_16x16x32_bf16 v[96:99], v[152:155], v[180:183], v[96:99]
	v_mfma_f32_16x16x32_bf16 v[84:87], v[144:147], v[188:191], v[84:87]
	v_mfma_f32_16x16x32_bf16 v[80:83], v[152:155], v[188:191], v[80:83]
	v_mfma_f32_16x16x32_bf16 v[68:71], v[144:147], v[208:211], v[68:71]
	v_mfma_f32_16x16x32_bf16 v[64:67], v[152:155], v[208:211], v[64:67]
	v_mfma_f32_16x16x32_bf16 v[116:119], v[148:151], v[164:167], v[116:119]
	v_mfma_f32_16x16x32_bf16 v[112:115], v[156:159], v[164:167], v[112:115]
	v_mfma_f32_16x16x32_bf16 v[100:103], v[148:151], v[184:187], v[100:103]
	v_mfma_f32_16x16x32_bf16 v[96:99], v[156:159], v[184:187], v[96:99]
	v_mfma_f32_16x16x32_bf16 v[84:87], v[148:151], v[192:195], v[84:87]
	v_mfma_f32_16x16x32_bf16 v[80:83], v[156:159], v[192:195], v[80:83]
	v_mfma_f32_16x16x32_bf16 v[68:71], v[148:151], v[216:219], v[68:71]
	v_mfma_f32_16x16x32_bf16 v[64:67], v[156:159], v[216:219], v[64:67]
	s_nop 0
	s_barrier
	s_add_i32 s30, s52, s57
	v_lshl_add_u64 v[196:197], s[46:47], 0, v[212:213]
	s_mov_b32 m0, s30
	ds_read_b128 v[160:163], v206 offset:16384
	ds_read_b128 v[164:167], v206 offset:17408
	ds_read_b128 v[180:183], v206 offset:18432
	ds_read_b128 v[184:187], v206 offset:19456
	ds_read_b128 v[188:191], v206 offset:20480
	ds_read_b128 v[192:195], v206 offset:21504
	ds_read_b128 v[208:211], v206 offset:22528
	ds_read_b128 v[216:219], v206 offset:23552
	global_load_lds_dwordx4 v[196:197], off
	s_add_i32 m0, s30, 0x2000
	s_add_u32 s52, s46, 0x40000
	v_lshl_add_u64 v[202:203], s[46:47], 0, v[168:169]
	s_addc_u32 s53, s47, 0
	s_add_i32 s16, s16, s57
	global_load_lds_dwordx4 v[202:203], off
	v_lshl_add_u64 v[220:221], s[52:53], 0, v[212:213]
	s_mov_b32 m0, s16
	v_lshl_add_u64 v[222:223], s[48:49], 0, v[170:171]
	global_load_lds_dwordx4 v[220:221], off
	v_lshl_add_u64 v[220:221], s[52:53], 0, v[168:169]
	s_add_i32 m0, s16, 0x2000
	s_nop 0
	global_load_lds_dwordx4 v[220:221], off
	v_lshl_add_u64 v[220:221], s[48:49], 0, v[172:173]
	s_mov_b32 m0, s59
	s_nop 0
	global_load_lds_dwordx4 v[220:221], off
	s_mov_b32 m0, s60
	s_nop 0
	global_load_lds_dwordx4 v[222:223], off
	s_waitcnt vmcnt(8)
	s_waitcnt lgkmcnt(0)
	s_barrier
; #define PG8_STAGE(bufoff, gbase, voff) do { _Pragma("unroll") for (int _i = 0; _i < 2; ++_i) \
;         __builtin_amdgcn_global_load_lds((const unsigned*)((const char*)(gbase) + (voff)[_i]), (PG8_LAS unsigned*)(lds + (bufoff) + ldsw + _i * 8192), 16, 0, 0); } while (0)
; #define PG8_LDA(dst, b, h) do { _Pragma("unroll") for (int m = 0; m < 4; ++m) _Pragma("unroll") for (int k = 0; k < 2; ++k) dst[m][k] = *(const PG8_LAS bf16x8*)(lds + PG8_SA(b, h) + aoff + m * 2048 + k * 1024); } while (0)
; #define PG8_LDB(dst, b, h) do { _Pragma("unroll") for (int n = 0; n < 2; ++n) _Pragma("unroll") for (int k = 0; k < 2; ++k) dst[n][k] = *(const PG8_LAS bf16x8*)(lds + PG8_SB(b, h) + boff + n * 2048 + k * 1024); } while (0)
; #define PG8_MMA(ai, bj, At, Bt) do { __builtin_amdgcn_s_setprio(1); _Pragma("unroll") for (int m = 0; m < 4; ++m) _Pragma("unroll") for (int n = 0; n < 2; ++n) _Pragma("unroll") for (int k = 0; k < 2; ++k) \
;         acc[ai][bj][m][n] = __builtin_amdgcn_mfma_f32_16x16x32_bf16(Bt[n][k], At[m][k], acc[ai][bj][m][n], 0, 0, 0); __builtin_amdgcn_s_setprio(0); } while (0)
; #define PG8_WAIT_V(n) asm volatile("s_waitcnt vmcnt(" #n ")" ::: "memory")
; #define PG8_WAIT_L(n) asm volatile("s_waitcnt lgkmcnt(" #n ")" ::: "memory")
; #define PG8_BAR __builtin_amdgcn_s_barrier()
; #define PG8_SCHED __builtin_amdgcn_sched_barrier(0)
; template <class Epi, class Sched>
; __device__ __forceinline__ void gemm_phase(PG8_LAS unsigned char* lds, const Gemm g, const Sched& S, const Epi& E, const int tid) {
;     ...
;             PG8_LDA(At, 0, 1); PG8_STAGE(PG8_SB(0, 0), b2, voffB); PG8_STAGE(PG8_SB(0, 1), b2 + hstepB, voffB); PG8_STAGE(PG8_SA(0, 0), a2, voffA);
;             PG8_WAIT_V(8); PG8_WAIT_L(0); PG8_BAR; PG8_MMA(1, 0, At, B0); PG8_MMA(1, 1, At, B1); PG8_BAR; PG8_SCHED;
;             PG8_LDB(B0, 1, 0); PG8_LDB(B1, 1, 1); PG8_SCHED; PG8_LDA(At, 1, 0); PG8_STAGE(PG8_SA(0, 1), a2 + hstepA, voffA);
;             PG8_WAIT_V(8); PG8_WAIT_L(0); PG8_BAR; PG8_MMA(0, 0, At, B0); PG8_MMA(0, 1, At, B1); PG8_BAR; PG8_SCHED;
	s_nop 0
	s_waitcnt lgkmcnt(0)
	v_mfma_f32_16x16x32_bf16 v[60:63], v[128:131], v[160:163], v[60:63]
	v_mfma_f32_16x16x32_bf16 v[56:59], v[136:139], v[160:163], v[56:59]
	v_mfma_f32_16x16x32_bf16 v[44:47], v[128:131], v[180:183], v[44:47]
	v_mfma_f32_16x16x32_bf16 v[40:43], v[136:139], v[180:183], v[40:43]
	v_mfma_f32_16x16x32_bf16 v[28:31], v[128:131], v[188:191], v[28:31]
	v_mfma_f32_16x16x32_bf16 v[24:27], v[136:139], v[188:191], v[24:27]
	v_mfma_f32_16x16x32_bf16 v[12:15], v[128:131], v[208:211], v[12:15]
	v_mfma_f32_16x16x32_bf16 v[8:11], v[136:139], v[208:211], v[8:11]
	v_mfma_f32_16x16x32_bf16 v[60:63], v[132:135], v[164:167], v[60:63]
	v_mfma_f32_16x16x32_bf16 v[56:59], v[140:143], v[164:167], v[56:59]
	v_mfma_f32_16x16x32_bf16 v[44:47], v[132:135], v[184:187], v[44:47]
	v_mfma_f32_16x16x32_bf16 v[40:43], v[140:143], v[184:187], v[40:43]
	v_mfma_f32_16x16x32_bf16 v[28:31], v[132:135], v[192:195], v[28:31]
	v_mfma_f32_16x16x32_bf16 v[24:27], v[140:143], v[192:195], v[24:27]
	v_mfma_f32_16x16x32_bf16 v[12:15], v[132:135], v[216:219], v[12:15]
	v_mfma_f32_16x16x32_bf16 v[8:11], v[140:143], v[216:219], v[8:11]
	s_nop 0
	s_nop 0
	v_mfma_f32_16x16x32_bf16 v[52:55], v[144:147], v[160:163], v[52:55]
	v_mfma_f32_16x16x32_bf16 v[48:51], v[152:155], v[160:163], v[48:51]
	v_mfma_f32_16x16x32_bf16 v[36:39], v[144:147], v[180:183], v[36:39]
	v_mfma_f32_16x16x32_bf16 v[32:35], v[152:155], v[180:183], v[32:35]
	v_mfma_f32_16x16x32_bf16 v[20:23], v[144:147], v[188:191], v[20:23]
	v_mfma_f32_16x16x32_bf16 v[16:19], v[152:155], v[188:191], v[16:19]
	v_mfma_f32_16x16x32_bf16 v[4:7], v[144:147], v[208:211], v[4:7]
	v_mfma_f32_16x16x32_bf16 v[0:3], v[152:155], v[208:211], v[0:3]
	v_mfma_f32_16x16x32_bf16 v[52:55], v[148:151], v[164:167], v[52:55]
	v_mfma_f32_16x16x32_bf16 v[48:51], v[156:159], v[164:167], v[48:51]
	v_mfma_f32_16x16x32_bf16 v[36:39], v[148:151], v[184:187], v[36:39]
	v_mfma_f32_16x16x32_bf16 v[32:35], v[156:159], v[184:187], v[32:35]
	v_mfma_f32_16x16x32_bf16 v[20:23], v[148:151], v[192:195], v[20:23]
	v_mfma_f32_16x16x32_bf16 v[16:19], v[156:159], v[192:195], v[16:19]
	v_mfma_f32_16x16x32_bf16 v[4:7], v[148:151], v[216:219], v[4:7]
	v_mfma_f32_16x16x32_bf16 v[0:3], v[156:159], v[216:219], v[0:3]
	s_nop 0
	s_barrier
	s_add_i32 s16, 0, 0x18000
	s_add_i32 s30, 0, 0x1c000
	v_add_u32_e32 v140, s16, v204
	v_add_u32_e32 v156, s30, v204
	ds_read_b128 v[128:131], v140
	ds_read_b128 v[132:135], v140 offset:1024
	ds_read_b128 v[136:139], v140 offset:2048
	ds_read_b128 v[140:143], v140 offset:3072
	ds_read_b128 v[144:147], v156
	ds_read_b128 v[148:151], v156 offset:1024
	ds_read_b128 v[152:155], v156 offset:2048
	ds_read_b128 v[156:159], v156 offset:3072
	s_add_u32 s48, s48, 0x40000
	s_addc_u32 s49, s49, 0
	s_mov_b32 m0, s61
	v_lshl_add_u64 v[224:225], s[48:49], 0, v[172:173]
	ds_read_b128 v[160:163], v206 offset:32768
	ds_read_b128 v[164:167], v206 offset:33792
	ds_read_b128 v[180:183], v206 offset:34816
	ds_read_b128 v[184:187], v206 offset:35840
	ds_read_b128 v[188:191], v206 offset:36864
	ds_read_b128 v[192:195], v206 offset:37888
	ds_read_b128 v[208:211], v206 offset:38912
	ds_read_b128 v[216:219], v206 offset:39936
	global_load_lds_dwordx4 v[224:225], off
	v_lshl_add_u64 v[224:225], s[48:49], 0, v[170:171]
	s_mov_b32 m0, s62
	s_nop 0
	global_load_lds_dwordx4 v[224:225], off
	s_waitcnt vmcnt(8)
	s_waitcnt lgkmcnt(0)
	s_barrier
	s_nop 0
	s_waitcnt lgkmcnt(0)
	v_mfma_f32_16x16x32_bf16 v[124:127], v[128:131], v[160:163], v[124:127]
	v_mfma_f32_16x16x32_bf16 v[120:123], v[136:139], v[160:163], v[120:123]
	v_mfma_f32_16x16x32_bf16 v[108:111], v[128:131], v[180:183], v[108:111]
	v_mfma_f32_16x16x32_bf16 v[104:107], v[136:139], v[180:183], v[104:107]
	v_mfma_f32_16x16x32_bf16 v[92:95], v[128:131], v[188:191], v[92:95]
	v_mfma_f32_16x16x32_bf16 v[88:91], v[136:139], v[188:191], v[88:91]
	v_mfma_f32_16x16x32_bf16 v[76:79], v[128:131], v[208:211], v[76:79]
	v_mfma_f32_16x16x32_bf16 v[72:75], v[136:139], v[208:211], v[72:75]
	v_mfma_f32_16x16x32_bf16 v[124:127], v[132:135], v[164:167], v[124:127]
	v_mfma_f32_16x16x32_bf16 v[120:123], v[140:143], v[164:167], v[120:123]
	v_mfma_f32_16x16x32_bf16 v[108:111], v[132:135], v[184:187], v[108:111]
	v_mfma_f32_16x16x32_bf16 v[104:107], v[140:143], v[184:187], v[104:107]
	v_mfma_f32_16x16x32_bf16 v[92:95], v[132:135], v[192:195], v[92:95]
	v_mfma_f32_16x16x32_bf16 v[88:91], v[140:143], v[192:195], v[88:91]
	v_mfma_f32_16x16x32_bf16 v[76:79], v[132:135], v[216:219], v[76:79]
	v_mfma_f32_16x16x32_bf16 v[72:75], v[140:143], v[216:219], v[72:75]
	s_nop 0
	s_nop 0
	v_mfma_f32_16x16x32_bf16 v[116:119], v[144:147], v[160:163], v[116:119]
	v_mfma_f32_16x16x32_bf16 v[112:115], v[152:155], v[160:163], v[112:115]
	v_mfma_f32_16x16x32_bf16 v[100:103], v[144:147], v[180:183], v[100:103]
	v_mfma_f32_16x16x32_bf16 v[96:99], v[152:155], v[180:183], v[96:99]
	v_mfma_f32_16x16x32_bf16 v[84:87], v[144:147], v[188:191], v[84:87]
	v_mfma_f32_16x16x32_bf16 v[80:83], v[152:155], v[188:191], v[80:83]
	v_mfma_f32_16x16x32_bf16 v[68:71], v[144:147], v[208:211], v[68:71]
	v_mfma_f32_16x16x32_bf16 v[64:67], v[152:155], v[208:211], v[64:67]
	v_mfma_f32_16x16x32_bf16 v[116:119], v[148:151], v[164:167], v[116:119]
	v_mfma_f32_16x16x32_bf16 v[112:115], v[156:159], v[164:167], v[112:115]
	v_mfma_f32_16x16x32_bf16 v[100:103], v[148:151], v[184:187], v[100:103]
	v_mfma_f32_16x16x32_bf16 v[96:99], v[156:159], v[184:187], v[96:99]
	v_mfma_f32_16x16x32_bf16 v[84:87], v[148:151], v[192:195], v[84:87]
	v_mfma_f32_16x16x32_bf16 v[80:83], v[156:159], v[192:195], v[80:83]
	v_mfma_f32_16x16x32_bf16 v[68:71], v[148:151], v[216:219], v[68:71]
	v_mfma_f32_16x16x32_bf16 v[64:67], v[156:159], v[216:219], v[64:67]
	s_nop 0
	s_barrier
; #define PG8_STAGE(bufoff, gbase, voff) do { _Pragma("unroll") for (int _i = 0; _i < 2; ++_i) \
;         __builtin_amdgcn_global_load_lds((const unsigned*)((const char*)(gbase) + (voff)[_i]), (PG8_LAS unsigned*)(lds + (bufoff) + ldsw + _i * 8192), 16, 0, 0); } while (0)
; #define PG8_LDA(dst, b, h) do { _Pragma("unroll") for (int m = 0; m < 4; ++m) _Pragma("unroll") for (int k = 0; k < 2; ++k) dst[m][k] = *(const PG8_LAS bf16x8*)(lds + PG8_SA(b, h) + aoff + m * 2048 + k * 1024); } while (0)
; #define PG8_MMA(ai, bj, At, Bt) do { __builtin_amdgcn_s_setprio(1); _Pragma("unroll") for (int m = 0; m < 4; ++m) _Pragma("unroll") for (int n = 0; n < 2; ++n) _Pragma("unroll") for (int k = 0; k < 2; ++k) \
;         acc[ai][bj][m][n] = __builtin_amdgcn_mfma_f32_16x16x32_bf16(Bt[n][k], At[m][k], acc[ai][bj][m][n], 0, 0, 0); __builtin_amdgcn_s_setprio(0); } while (0)
; #define PG8_WAIT_V(n) asm volatile("s_waitcnt vmcnt(" #n ")" ::: "memory")
; #define PG8_WAIT_L(n) asm volatile("s_waitcnt lgkmcnt(" #n ")" ::: "memory")
; #define PG8_BAR __builtin_amdgcn_s_barrier()
; #define PG8_SCHED __builtin_amdgcn_sched_barrier(0)
; template <class Epi, class Sched>
; __device__ __forceinline__ void gemm_phase(PG8_LAS unsigned char* lds, const Gemm g, const Sched& S, const Epi& E, const int tid) {
;     ...
;             PG8_LDA(At, 1, 1); PG8_STAGE(PG8_SB(1, 0), b3, voffB); PG8_STAGE(PG8_SB(1, 1), b3 + hstepB, voffB); PG8_STAGE(PG8_SA(1, 0), a3, voffA);
;             PG8_WAIT_V(8); PG8_WAIT_L(0); PG8_BAR; PG8_MMA(1, 0, At, B0); PG8_MMA(1, 1, At, B1); PG8_BAR; PG8_SCHED;
;         }
;         if (wr == 0) PG8_BAR;
	s_add_i32 s16, s16, s57
	v_lshl_add_u64 v[196:197], v[196:197], 0, s[10:11]
	s_mov_b32 m0, s16
	ds_read_b128 v[160:163], v206 offset:49152
	ds_read_b128 v[164:167], v206 offset:50176
	ds_read_b128 v[180:183], v206 offset:51200
	ds_read_b128 v[184:187], v206 offset:52224
	ds_read_b128 v[188:191], v206 offset:53248
	ds_read_b128 v[192:195], v206 offset:54272
	ds_read_b128 v[208:211], v206 offset:55296
	ds_read_b128 v[216:219], v206 offset:56320
	global_load_lds_dwordx4 v[196:197], off
	s_add_i32 m0, s16, 0x2000
	s_add_u32 s46, s46, 0x40080
	v_lshl_add_u64 v[196:197], v[202:203], 0, s[10:11]
	s_addc_u32 s47, s47, 0
	s_add_i32 s16, s30, s57
	global_load_lds_dwordx4 v[196:197], off
	v_lshl_add_u64 v[196:197], s[46:47], 0, v[212:213]
	s_mov_b32 m0, s16
	s_nop 0
	global_load_lds_dwordx4 v[196:197], off
	v_lshl_add_u64 v[196:197], s[46:47], 0, v[168:169]
	s_add_i32 m0, s16, 0x2000
	s_nop 0
	global_load_lds_dwordx4 v[196:197], off
	v_lshl_add_u64 v[196:197], v[220:221], 0, s[10:11]
	s_mov_b32 m0, s65
	s_nop 0
	global_load_lds_dwordx4 v[196:197], off
	v_lshl_add_u64 v[196:197], v[222:223], 0, s[10:11]
	s_mov_b32 m0, s66
	s_nop 0
	global_load_lds_dwordx4 v[196:197], off
	s_waitcnt vmcnt(8)
	s_waitcnt lgkmcnt(0)
	s_barrier
	s_nop 0
	s_waitcnt lgkmcnt(0)
	v_mfma_f32_16x16x32_bf16 v[60:63], v[128:131], v[160:163], v[60:63]
	v_mfma_f32_16x16x32_bf16 v[56:59], v[136:139], v[160:163], v[56:59]
	v_mfma_f32_16x16x32_bf16 v[44:47], v[128:131], v[180:183], v[44:47]
	v_mfma_f32_16x16x32_bf16 v[40:43], v[136:139], v[180:183], v[40:43]
	v_mfma_f32_16x16x32_bf16 v[28:31], v[128:131], v[188:191], v[28:31]
	v_mfma_f32_16x16x32_bf16 v[24:27], v[136:139], v[188:191], v[24:27]
	v_mfma_f32_16x16x32_bf16 v[12:15], v[128:131], v[208:211], v[12:15]
	v_mfma_f32_16x16x32_bf16 v[8:11], v[136:139], v[208:211], v[8:11]
	v_mfma_f32_16x16x32_bf16 v[60:63], v[132:135], v[164:167], v[60:63]
	v_mfma_f32_16x16x32_bf16 v[56:59], v[140:143], v[164:167], v[56:59]
	v_mfma_f32_16x16x32_bf16 v[44:47], v[132:135], v[184:187], v[44:47]
	v_mfma_f32_16x16x32_bf16 v[40:43], v[140:143], v[184:187], v[40:43]
	v_mfma_f32_16x16x32_bf16 v[28:31], v[132:135], v[192:195], v[28:31]
	v_mfma_f32_16x16x32_bf16 v[24:27], v[140:143], v[192:195], v[24:27]
	v_mfma_f32_16x16x32_bf16 v[12:15], v[132:135], v[216:219], v[12:15]
	v_mfma_f32_16x16x32_bf16 v[8:11], v[140:143], v[216:219], v[8:11]
	s_nop 0
	s_nop 0
	v_mfma_f32_16x16x32_bf16 v[52:55], v[144:147], v[160:163], v[52:55]
	v_mfma_f32_16x16x32_bf16 v[48:51], v[152:155], v[160:163], v[48:51]
	v_mfma_f32_16x16x32_bf16 v[36:39], v[144:147], v[180:183], v[36:39]
	v_mfma_f32_16x16x32_bf16 v[32:35], v[152:155], v[180:183], v[32:35]
	v_mfma_f32_16x16x32_bf16 v[20:23], v[144:147], v[188:191], v[20:23]
	v_mfma_f32_16x16x32_bf16 v[16:19], v[152:155], v[188:191], v[16:19]
	v_mfma_f32_16x16x32_bf16 v[4:7], v[144:147], v[208:211], v[4:7]
	v_mfma_f32_16x16x32_bf16 v[0:3], v[152:155], v[208:211], v[0:3]
	v_mfma_f32_16x16x32_bf16 v[52:55], v[148:151], v[164:167], v[52:55]
	v_mfma_f32_16x16x32_bf16 v[48:51], v[156:159], v[164:167], v[48:51]
	v_mfma_f32_16x16x32_bf16 v[36:39], v[148:151], v[184:187], v[36:39]
	v_mfma_f32_16x16x32_bf16 v[32:35], v[156:159], v[184:187], v[32:35]
	v_mfma_f32_16x16x32_bf16 v[20:23], v[148:151], v[192:195], v[20:23]
	v_mfma_f32_16x16x32_bf16 v[16:19], v[156:159], v[192:195], v[16:19]
	v_mfma_f32_16x16x32_bf16 v[4:7], v[148:151], v[216:219], v[4:7]
	v_mfma_f32_16x16x32_bf16 v[0:3], v[156:159], v[216:219], v[0:3]
	s_nop 0
	s_barrier
	s_add_i32 s73, s73, 2
	s_add_u32 s44, s44, 0x100
	s_addc_u32 s45, s45, 0
	s_add_u32 s71, s71, 0x100
	s_addc_u32 s72, s72, 0
	s_cmp_gt_u32 s73, 13
	s_cbranch_scc0 .LBB0_1693
	s_and_b64 vcc, exec, s[18:19]
	s_cbranch_vccz .LBB0_1696
	s_barrier

; #define PG8_STAGE(bufoff, gbase, voff) do { _Pragma("unroll") for (int _i = 0; _i < 2; ++_i) \
;         __builtin_amdgcn_global_load_lds((const unsigned*)((const char*)(gbase) + (voff)[_i]), (PG8_LAS unsigned*)(lds + (bufoff) + ldsw + _i * 8192), 16, 0, 0); } while (0)
; #define PG8_LDA(dst, b, h) do { _Pragma("unroll") for (int m = 0; m < 4; ++m) _Pragma("unroll") for (int k = 0; k < 2; ++k) dst[m][k] = *(const PG8_LAS bf16x8*)(lds + PG8_SA(b, h) + aoff + m * 2048 + k * 1024); } while (0)
; #define PG8_LDB(dst, b, h) do { _Pragma("unroll") for (int n = 0; n < 2; ++n) _Pragma("unroll") for (int k = 0; k < 2; ++k) dst[n][k] = *(const PG8_LAS bf16x8*)(lds + PG8_SB(b, h) + boff + n * 2048 + k * 1024); } while (0)
; #define PG8_MMA(ai, bj, At, Bt) do { __builtin_amdgcn_s_setprio(1); _Pragma("unroll") for (int m = 0; m < 4; ++m) _Pragma("unroll") for (int n = 0; n < 2; ++n) _Pragma("unroll") for (int k = 0; k < 2; ++k) \
;         acc[ai][bj][m][n] = __builtin_amdgcn_mfma_f32_16x16x32_bf16(Bt[n][k], At[m][k], acc[ai][bj][m][n], 0, 0, 0); __builtin_amdgcn_s_setprio(0); } while (0)
; #define PG8_WAIT_V(n) asm volatile("s_waitcnt vmcnt(" #n ")" ::: "memory")
; #define PG8_WAIT_L(n) asm volatile("s_waitcnt lgkmcnt(" #n ")" ::: "memory")
; #define PG8_BAR __builtin_amdgcn_s_barrier()
; #define PG8_SCHED __builtin_amdgcn_sched_barrier(0)
; template <class Epi, class Sched>
; __device__ __forceinline__ void gemm_phase(PG8_LAS unsigned char* lds, const Gemm g, const Sched& S, const Epi& E, const int tid) {
;     ...
;         const char* nA = has_next ? (const char*)g.A + (size_t)nxt.pm * tstepA + (size_t)nxt.pn * g.a_pn_off + S.koff(nxt) : cA; const char* nB = has_next ? (const char*)g.Bt + (size_t)nxt.pn * tstepB + S.koff(nxt) : cB;
;         const int ntc = S.nt(cur, nt);
;         for (int t = 0; t < ntc; t += 2) {
;             const bool last = (t == ntc - 2);
;             const char* a1 = cA + (size_t)(t + 1) * kstep;
;             const char* a2 = last ? nA : cA + (size_t)(t + 2) * kstep; const char* b2 = last ? nB : cB + (size_t)(t + 2) * kstep;
;             const char* a3 = a2 + kstep; const char* b3 = b2 + kstep;
;             PG8_LDB(B0, 0, 0); PG8_LDB(B1, 0, 1); PG8_SCHED; PG8_LDA(At, 0, 0); PG8_STAGE(PG8_SA(1, 1), a1 + hstepA, voffA);
;             PG8_WAIT_V(8); PG8_WAIT_L(0); PG8_BAR; PG8_MMA(0, 0, At, B0); PG8_MMA(0, 1, At, B1); PG8_BAR; PG8_SCHED;
.LBB0_1865:
	s_add_u32 s16, s40, 0xfff00080
	s_addc_u32 s30, s41, -1
	s_add_i32 s52, 0, 0x10000
	s_cmp_eq_u32 s59, 60
	s_cselect_b32 s57, s1, s30
	s_cselect_b32 s56, s8, s16
	s_cselect_b32 s49, s25, s58
	s_cselect_b32 s48, s35, s43
	s_add_i32 s16, 0, 0x14000
	v_add_u32_e32 v76, s52, v231
	v_add_u32_e32 v156, s16, v231
	ds_read_b128 v[64:67], v76
	ds_read_b128 v[68:71], v76 offset:1024
	ds_read_b128 v[72:75], v76 offset:2048
	ds_read_b128 v[76:79], v76 offset:3072
	ds_read_b128 v[144:147], v156
	ds_read_b128 v[148:151], v156 offset:1024
	ds_read_b128 v[152:155], v156 offset:2048
	ds_read_b128 v[156:159], v156 offset:3072
	v_lshl_add_u64 v[202:203], s[40:41], 0, v[178:179]
	s_add_i32 m0, s22, 0xc000
	ds_read_b128 v[160:163], v232
	ds_read_b128 v[164:167], v232 offset:1024
	ds_read_b128 v[168:171], v232 offset:2048
	ds_read_b128 v[182:185], v232 offset:3072
	ds_read_b128 v[186:189], v232 offset:4096
	ds_read_b128 v[190:193], v232 offset:5120
	ds_read_b128 v[194:197], v232 offset:6144
	ds_read_b128 v[198:201], v232 offset:7168
	global_load_lds_dwordx4 v[202:203], off
	v_lshl_add_u64 v[202:203], s[40:41], 0, v[180:181]
	s_add_i32 m0, s22, 0xe000
	s_nop 0
	global_load_lds_dwordx4 v[202:203], off
	s_waitcnt vmcnt(8)
	s_waitcnt lgkmcnt(0)
	s_barrier
	s_nop 0
	s_waitcnt lgkmcnt(0)
	v_mfma_f32_16x16x32_bf16 v[140:143], v[64:67], v[160:163], v[140:143]
	v_mfma_f32_16x16x32_bf16 v[136:139], v[72:75], v[160:163], v[136:139]
	v_mfma_f32_16x16x32_bf16 v[124:127], v[64:67], v[168:171], v[124:127]
	v_mfma_f32_16x16x32_bf16 v[120:123], v[72:75], v[168:171], v[120:123]
	v_mfma_f32_16x16x32_bf16 v[108:111], v[64:67], v[186:189], v[108:111]
	v_mfma_f32_16x16x32_bf16 v[104:107], v[72:75], v[186:189], v[104:107]
	v_mfma_f32_16x16x32_bf16 v[92:95], v[64:67], v[194:197], v[92:95]
	v_mfma_f32_16x16x32_bf16 v[88:91], v[72:75], v[194:197], v[88:91]
	v_mfma_f32_16x16x32_bf16 v[140:143], v[68:71], v[164:167], v[140:143]
	v_mfma_f32_16x16x32_bf16 v[136:139], v[76:79], v[164:167], v[136:139]
	v_mfma_f32_16x16x32_bf16 v[124:127], v[68:71], v[182:185], v[124:127]
	v_mfma_f32_16x16x32_bf16 v[120:123], v[76:79], v[182:185], v[120:123]
	v_mfma_f32_16x16x32_bf16 v[108:111], v[68:71], v[190:193], v[108:111]
	v_mfma_f32_16x16x32_bf16 v[104:107], v[76:79], v[190:193], v[104:107]
	v_mfma_f32_16x16x32_bf16 v[92:95], v[68:71], v[198:201], v[92:95]
	v_mfma_f32_16x16x32_bf16 v[88:91], v[76:79], v[198:201], v[88:91]
	s_nop 0
	s_nop 0
	v_mfma_f32_16x16x32_bf16 v[132:135], v[144:147], v[160:163], v[132:135]
	v_mfma_f32_16x16x32_bf16 v[128:131], v[152:155], v[160:163], v[128:131]
	v_mfma_f32_16x16x32_bf16 v[116:119], v[144:147], v[168:171], v[116:119]
	v_mfma_f32_16x16x32_bf16 v[112:115], v[152:155], v[168:171], v[112:115]
	v_mfma_f32_16x16x32_bf16 v[100:103], v[144:147], v[186:189], v[100:103]
	v_mfma_f32_16x16x32_bf16 v[96:99], v[152:155], v[186:189], v[96:99]
	v_mfma_f32_16x16x32_bf16 v[84:87], v[144:147], v[194:197], v[84:87]
	v_mfma_f32_16x16x32_bf16 v[80:83], v[152:155], v[194:197], v[80:83]
	v_mfma_f32_16x16x32_bf16 v[132:135], v[148:151], v[164:167], v[132:135]
	v_mfma_f32_16x16x32_bf16 v[128:131], v[156:159], v[164:167], v[128:131]
	v_mfma_f32_16x16x32_bf16 v[116:119], v[148:151], v[182:185], v[116:119]
	v_mfma_f32_16x16x32_bf16 v[112:115], v[156:159], v[182:185], v[112:115]
	v_mfma_f32_16x16x32_bf16 v[100:103], v[148:151], v[190:193], v[100:103]
	v_mfma_f32_16x16x32_bf16 v[96:99], v[156:159], v[190:193], v[96:99]
	v_mfma_f32_16x16x32_bf16 v[84:87], v[148:151], v[198:201], v[84:87]
	v_mfma_f32_16x16x32_bf16 v[80:83], v[156:159], v[198:201], v[80:83]
	s_nop 0
	s_barrier
	s_add_i32 s30, s52, s21
	v_lshl_add_u64 v[202:203], s[48:49], 0, v[212:213]
	s_mov_b32 m0, s30
	ds_read_b128 v[160:163], v232 offset:16384
	ds_read_b128 v[164:167], v232 offset:17408
	ds_read_b128 v[168:171], v232 offset:18432
	ds_read_b128 v[182:185], v232 offset:19456
	ds_read_b128 v[186:189], v232 offset:20480
	ds_read_b128 v[190:193], v232 offset:21504
	ds_read_b128 v[194:197], v232 offset:22528
	ds_read_b128 v[198:201], v232 offset:23552
	global_load_lds_dwordx4 v[202:203], off
	s_add_i32 m0, s30, 0x2000
	s_add_u32 s52, s48, 0x100000
	v_lshl_add_u64 v[204:205], s[48:49], 0, v[176:177]
	s_addc_u32 s53, s49, 0
	s_add_i32 s16, s16, s21
	global_load_lds_dwordx4 v[204:205], off
	v_lshl_add_u64 v[206:207], s[52:53], 0, v[212:213]
	s_mov_b32 m0, s16
	v_lshl_add_u64 v[208:209], s[56:57], 0, v[174:175]
	global_load_lds_dwordx4 v[206:207], off
	v_lshl_add_u64 v[206:207], s[52:53], 0, v[176:177]
	s_add_i32 m0, s16, 0x2000
	s_nop 0
	global_load_lds_dwordx4 v[206:207], off
	v_lshl_add_u64 v[206:207], s[56:57], 0, v[172:173]
	s_mov_b32 m0, s22
	s_nop 0
	global_load_lds_dwordx4 v[206:207], off
	s_mov_b32 m0, s23
	s_nop 0
	global_load_lds_dwordx4 v[208:209], off
	s_waitcnt vmcnt(8)
	s_waitcnt lgkmcnt(0)
	s_barrier
; #define PG8_STAGE(bufoff, gbase, voff) do { _Pragma("unroll") for (int _i = 0; _i < 2; ++_i) \
;         __builtin_amdgcn_global_load_lds((const unsigned*)((const char*)(gbase) + (voff)[_i]), (PG8_LAS unsigned*)(lds + (bufoff) + ldsw + _i * 8192), 16, 0, 0); } while (0)
; #define PG8_LDA(dst, b, h) do { _Pragma("unroll") for (int m = 0; m < 4; ++m) _Pragma("unroll") for (int k = 0; k < 2; ++k) dst[m][k] = *(const PG8_LAS bf16x8*)(lds + PG8_SA(b, h) + aoff + m * 2048 + k * 1024); } while (0)
; #define PG8_LDB(dst, b, h) do { _Pragma("unroll") for (int n = 0; n < 2; ++n) _Pragma("unroll") for (int k = 0; k < 2; ++k) dst[n][k] = *(const PG8_LAS bf16x8*)(lds + PG8_SB(b, h) + boff + n * 2048 + k * 1024); } while (0)
; #define PG8_MMA(ai, bj, At, Bt) do { __builtin_amdgcn_s_setprio(1); _Pragma("unroll") for (int m = 0; m < 4; ++m) _Pragma("unroll") for (int n = 0; n < 2; ++n) _Pragma("unroll") for (int k = 0; k < 2; ++k) \
;         acc[ai][bj][m][n] = __builtin_amdgcn_mfma_f32_16x16x32_bf16(Bt[n][k], At[m][k], acc[ai][bj][m][n], 0, 0, 0); __builtin_amdgcn_s_setprio(0); } while (0)
; #define PG8_WAIT_V(n) asm volatile("s_waitcnt vmcnt(" #n ")" ::: "memory")
; #define PG8_WAIT_L(n) asm volatile("s_waitcnt lgkmcnt(" #n ")" ::: "memory")
; #define PG8_BAR __builtin_amdgcn_s_barrier()
; #define PG8_SCHED __builtin_amdgcn_sched_barrier(0)
; template <class Epi, class Sched>
; __device__ __forceinline__ void gemm_phase(PG8_LAS unsigned char* lds, const Gemm g, const Sched& S, const Epi& E, const int tid) {
;     ...
;             PG8_LDA(At, 0, 1); PG8_STAGE(PG8_SB(0, 0), b2, voffB); PG8_STAGE(PG8_SB(0, 1), b2 + hstepB, voffB); PG8_STAGE(PG8_SA(0, 0), a2, voffA);
;             PG8_WAIT_V(8); PG8_WAIT_L(0); PG8_BAR; PG8_MMA(1, 0, At, B0); PG8_MMA(1, 1, At, B1); PG8_BAR; PG8_SCHED;
;             PG8_LDB(B0, 1, 0); PG8_LDB(B1, 1, 1); PG8_SCHED; PG8_LDA(At, 1, 0); PG8_STAGE(PG8_SA(0, 1), a2 + hstepA, voffA);
;             PG8_WAIT_V(8); PG8_WAIT_L(0); PG8_BAR; PG8_MMA(0, 0, At, B0); PG8_MMA(0, 1, At, B1); PG8_BAR; PG8_SCHED;
	s_nop 0
	s_waitcnt lgkmcnt(0)
	v_mfma_f32_16x16x32_bf16 v[60:63], v[64:67], v[160:163], v[60:63]
	v_mfma_f32_16x16x32_bf16 v[56:59], v[72:75], v[160:163], v[56:59]
	v_mfma_f32_16x16x32_bf16 v[44:47], v[64:67], v[168:171], v[44:47]
	v_mfma_f32_16x16x32_bf16 v[40:43], v[72:75], v[168:171], v[40:43]
	v_mfma_f32_16x16x32_bf16 v[28:31], v[64:67], v[186:189], v[28:31]
	v_mfma_f32_16x16x32_bf16 v[24:27], v[72:75], v[186:189], v[24:27]
	v_mfma_f32_16x16x32_bf16 v[12:15], v[64:67], v[194:197], v[12:15]
	v_mfma_f32_16x16x32_bf16 v[8:11], v[72:75], v[194:197], v[8:11]
	v_mfma_f32_16x16x32_bf16 v[60:63], v[68:71], v[164:167], v[60:63]
	v_mfma_f32_16x16x32_bf16 v[56:59], v[76:79], v[164:167], v[56:59]
	v_mfma_f32_16x16x32_bf16 v[44:47], v[68:71], v[182:185], v[44:47]
	v_mfma_f32_16x16x32_bf16 v[40:43], v[76:79], v[182:185], v[40:43]
	v_mfma_f32_16x16x32_bf16 v[28:31], v[68:71], v[190:193], v[28:31]
	v_mfma_f32_16x16x32_bf16 v[24:27], v[76:79], v[190:193], v[24:27]
	v_mfma_f32_16x16x32_bf16 v[12:15], v[68:71], v[198:201], v[12:15]
	v_mfma_f32_16x16x32_bf16 v[8:11], v[76:79], v[198:201], v[8:11]
	s_nop 0
	s_nop 0
	v_mfma_f32_16x16x32_bf16 v[52:55], v[144:147], v[160:163], v[52:55]
	v_mfma_f32_16x16x32_bf16 v[48:51], v[152:155], v[160:163], v[48:51]
	v_mfma_f32_16x16x32_bf16 v[36:39], v[144:147], v[168:171], v[36:39]
	v_mfma_f32_16x16x32_bf16 v[32:35], v[152:155], v[168:171], v[32:35]
	v_mfma_f32_16x16x32_bf16 v[20:23], v[144:147], v[186:189], v[20:23]
	v_mfma_f32_16x16x32_bf16 v[16:19], v[152:155], v[186:189], v[16:19]
	v_mfma_f32_16x16x32_bf16 v[4:7], v[144:147], v[194:197], v[4:7]
	v_mfma_f32_16x16x32_bf16 v[0:3], v[152:155], v[194:197], v[0:3]
	v_mfma_f32_16x16x32_bf16 v[52:55], v[148:151], v[164:167], v[52:55]
	v_mfma_f32_16x16x32_bf16 v[48:51], v[156:159], v[164:167], v[48:51]
	v_mfma_f32_16x16x32_bf16 v[36:39], v[148:151], v[182:185], v[36:39]
	v_mfma_f32_16x16x32_bf16 v[32:35], v[156:159], v[182:185], v[32:35]
	v_mfma_f32_16x16x32_bf16 v[20:23], v[148:151], v[190:193], v[20:23]
	v_mfma_f32_16x16x32_bf16 v[16:19], v[156:159], v[190:193], v[16:19]
	v_mfma_f32_16x16x32_bf16 v[4:7], v[148:151], v[198:201], v[4:7]
	v_mfma_f32_16x16x32_bf16 v[0:3], v[156:159], v[198:201], v[0:3]
	s_nop 0
	s_barrier
	s_add_i32 s16, 0, 0x18000
	s_add_i32 s30, 0, 0x1c000
	v_add_u32_e32 v76, s16, v231
	v_add_u32_e32 v156, s30, v231
	ds_read_b128 v[64:67], v76
	ds_read_b128 v[68:71], v76 offset:1024
	ds_read_b128 v[72:75], v76 offset:2048
	ds_read_b128 v[76:79], v76 offset:3072
	ds_read_b128 v[144:147], v156
	ds_read_b128 v[148:151], v156 offset:1024
	ds_read_b128 v[152:155], v156 offset:2048
	ds_read_b128 v[156:159], v156 offset:3072
	s_add_u32 s52, s56, 0x100000
	s_addc_u32 s53, s57, 0
	s_mov_b32 m0, s33
	v_lshl_add_u64 v[210:211], s[52:53], 0, v[172:173]
	ds_read_b128 v[160:163], v232 offset:32768
	ds_read_b128 v[164:167], v232 offset:33792
	ds_read_b128 v[168:171], v232 offset:34816
	ds_read_b128 v[182:185], v232 offset:35840
	ds_read_b128 v[186:189], v232 offset:36864
	ds_read_b128 v[190:193], v232 offset:37888
	ds_read_b128 v[194:197], v232 offset:38912
	ds_read_b128 v[198:201], v232 offset:39936
	global_load_lds_dwordx4 v[210:211], off
	v_lshl_add_u64 v[210:211], s[52:53], 0, v[174:175]
	s_mov_b32 m0, s50
	s_nop 0
	global_load_lds_dwordx4 v[210:211], off
	s_waitcnt vmcnt(8)
	s_waitcnt lgkmcnt(0)
	s_barrier
	s_nop 0
	s_waitcnt lgkmcnt(0)
	v_mfma_f32_16x16x32_bf16 v[140:143], v[64:67], v[160:163], v[140:143]
	v_mfma_f32_16x16x32_bf16 v[136:139], v[72:75], v[160:163], v[136:139]
	v_mfma_f32_16x16x32_bf16 v[124:127], v[64:67], v[168:171], v[124:127]
	v_mfma_f32_16x16x32_bf16 v[120:123], v[72:75], v[168:171], v[120:123]
	v_mfma_f32_16x16x32_bf16 v[108:111], v[64:67], v[186:189], v[108:111]
	v_mfma_f32_16x16x32_bf16 v[104:107], v[72:75], v[186:189], v[104:107]
	v_mfma_f32_16x16x32_bf16 v[92:95], v[64:67], v[194:197], v[92:95]
	v_mfma_f32_16x16x32_bf16 v[88:91], v[72:75], v[194:197], v[88:91]
	v_mfma_f32_16x16x32_bf16 v[140:143], v[68:71], v[164:167], v[140:143]
	v_mfma_f32_16x16x32_bf16 v[136:139], v[76:79], v[164:167], v[136:139]
	v_mfma_f32_16x16x32_bf16 v[124:127], v[68:71], v[182:185], v[124:127]
	v_mfma_f32_16x16x32_bf16 v[120:123], v[76:79], v[182:185], v[120:123]
	v_mfma_f32_16x16x32_bf16 v[108:111], v[68:71], v[190:193], v[108:111]
	v_mfma_f32_16x16x32_bf16 v[104:107], v[76:79], v[190:193], v[104:107]
	v_mfma_f32_16x16x32_bf16 v[92:95], v[68:71], v[198:201], v[92:95]
	v_mfma_f32_16x16x32_bf16 v[88:91], v[76:79], v[198:201], v[88:91]
	s_nop 0
	s_nop 0
	v_mfma_f32_16x16x32_bf16 v[132:135], v[144:147], v[160:163], v[132:135]
	v_mfma_f32_16x16x32_bf16 v[128:131], v[152:155], v[160:163], v[128:131]
	v_mfma_f32_16x16x32_bf16 v[116:119], v[144:147], v[168:171], v[116:119]
	v_mfma_f32_16x16x32_bf16 v[112:115], v[152:155], v[168:171], v[112:115]
	v_mfma_f32_16x16x32_bf16 v[100:103], v[144:147], v[186:189], v[100:103]
	v_mfma_f32_16x16x32_bf16 v[96:99], v[152:155], v[186:189], v[96:99]
	v_mfma_f32_16x16x32_bf16 v[84:87], v[144:147], v[194:197], v[84:87]
	v_mfma_f32_16x16x32_bf16 v[80:83], v[152:155], v[194:197], v[80:83]
	v_mfma_f32_16x16x32_bf16 v[132:135], v[148:151], v[164:167], v[132:135]
	v_mfma_f32_16x16x32_bf16 v[128:131], v[156:159], v[164:167], v[128:131]
	v_mfma_f32_16x16x32_bf16 v[116:119], v[148:151], v[182:185], v[116:119]
	v_mfma_f32_16x16x32_bf16 v[112:115], v[156:159], v[182:185], v[112:115]
	v_mfma_f32_16x16x32_bf16 v[100:103], v[148:151], v[190:193], v[100:103]
	v_mfma_f32_16x16x32_bf16 v[96:99], v[156:159], v[190:193], v[96:99]
	v_mfma_f32_16x16x32_bf16 v[84:87], v[148:151], v[198:201], v[84:87]
	v_mfma_f32_16x16x32_bf16 v[80:83], v[156:159], v[198:201], v[80:83]
	s_nop 0
	s_barrier
; #define PG8_STAGE(bufoff, gbase, voff) do { _Pragma("unroll") for (int _i = 0; _i < 2; ++_i) \
;         __builtin_amdgcn_global_load_lds((const unsigned*)((const char*)(gbase) + (voff)[_i]), (PG8_LAS unsigned*)(lds + (bufoff) + ldsw + _i * 8192), 16, 0, 0); } while (0)
; #define PG8_LDA(dst, b, h) do { _Pragma("unroll") for (int m = 0; m < 4; ++m) _Pragma("unroll") for (int k = 0; k < 2; ++k) dst[m][k] = *(const PG8_LAS bf16x8*)(lds + PG8_SA(b, h) + aoff + m * 2048 + k * 1024); } while (0)
; #define PG8_MMA(ai, bj, At, Bt) do { __builtin_amdgcn_s_setprio(1); _Pragma("unroll") for (int m = 0; m < 4; ++m) _Pragma("unroll") for (int n = 0; n < 2; ++n) _Pragma("unroll") for (int k = 0; k < 2; ++k) \
;         acc[ai][bj][m][n] = __builtin_amdgcn_mfma_f32_16x16x32_bf16(Bt[n][k], At[m][k], acc[ai][bj][m][n], 0, 0, 0); __builtin_amdgcn_s_setprio(0); } while (0)
; #define PG8_WAIT_V(n) asm volatile("s_waitcnt vmcnt(" #n ")" ::: "memory")
; #define PG8_WAIT_L(n) asm volatile("s_waitcnt lgkmcnt(" #n ")" ::: "memory")
; #define PG8_BAR __builtin_amdgcn_s_barrier()
; #define PG8_SCHED __builtin_amdgcn_sched_barrier(0)
; template <class Epi, class Sched>
; __device__ __forceinline__ void gemm_phase(PG8_LAS unsigned char* lds, const Gemm g, const Sched& S, const Epi& E, const int tid) {
;     ...
;             PG8_LDA(At, 1, 1); PG8_STAGE(PG8_SB(1, 0), b3, voffB); PG8_STAGE(PG8_SB(1, 1), b3 + hstepB, voffB); PG8_STAGE(PG8_SA(1, 0), a3, voffA);
;             PG8_WAIT_V(8); PG8_WAIT_L(0); PG8_BAR; PG8_MMA(1, 0, At, B0); PG8_MMA(1, 1, At, B1); PG8_BAR; PG8_SCHED;
;         }
;         if (wr == 0) PG8_BAR;
	s_add_i32 s16, s16, s21
	v_lshl_add_u64 v[202:203], v[202:203], 0, s[10:11]
	s_mov_b32 m0, s16
	ds_read_b128 v[160:163], v232 offset:49152
	ds_read_b128 v[164:167], v232 offset:50176
	ds_read_b128 v[168:171], v232 offset:51200
	ds_read_b128 v[182:185], v232 offset:52224
	ds_read_b128 v[186:189], v232 offset:53248
	ds_read_b128 v[190:193], v232 offset:54272
	ds_read_b128 v[194:197], v232 offset:55296
	ds_read_b128 v[198:201], v232 offset:56320
	global_load_lds_dwordx4 v[202:203], off
	s_add_i32 m0, s16, 0x2000
	s_add_u32 s48, s48, 0x100080
	v_lshl_add_u64 v[202:203], v[204:205], 0, s[10:11]
	s_addc_u32 s49, s49, 0
	s_add_i32 s16, s30, s21
	global_load_lds_dwordx4 v[202:203], off
	v_lshl_add_u64 v[202:203], s[48:49], 0, v[212:213]
	s_mov_b32 m0, s16
	s_nop 0
	global_load_lds_dwordx4 v[202:203], off
	v_lshl_add_u64 v[202:203], s[48:49], 0, v[176:177]
	s_add_i32 m0, s16, 0x2000
	s_nop 0
	global_load_lds_dwordx4 v[202:203], off
	v_lshl_add_u64 v[202:203], v[206:207], 0, s[10:11]
	s_mov_b32 m0, s73
	s_nop 0
	global_load_lds_dwordx4 v[202:203], off
	v_lshl_add_u64 v[202:203], v[208:209], 0, s[10:11]
	s_mov_b32 m0, s75
	s_nop 0
	global_load_lds_dwordx4 v[202:203], off
	s_waitcnt vmcnt(8)
	s_waitcnt lgkmcnt(0)
	s_barrier
	s_nop 0
	s_waitcnt lgkmcnt(0)
	v_mfma_f32_16x16x32_bf16 v[60:63], v[64:67], v[160:163], v[60:63]
	v_mfma_f32_16x16x32_bf16 v[56:59], v[72:75], v[160:163], v[56:59]
	v_mfma_f32_16x16x32_bf16 v[44:47], v[64:67], v[168:171], v[44:47]
	v_mfma_f32_16x16x32_bf16 v[40:43], v[72:75], v[168:171], v[40:43]
	v_mfma_f32_16x16x32_bf16 v[28:31], v[64:67], v[186:189], v[28:31]
	v_mfma_f32_16x16x32_bf16 v[24:27], v[72:75], v[186:189], v[24:27]
	v_mfma_f32_16x16x32_bf16 v[12:15], v[64:67], v[194:197], v[12:15]
	v_mfma_f32_16x16x32_bf16 v[8:11], v[72:75], v[194:197], v[8:11]
	v_mfma_f32_16x16x32_bf16 v[60:63], v[68:71], v[164:167], v[60:63]
	v_mfma_f32_16x16x32_bf16 v[56:59], v[76:79], v[164:167], v[56:59]
	v_mfma_f32_16x16x32_bf16 v[44:47], v[68:71], v[182:185], v[44:47]
	v_mfma_f32_16x16x32_bf16 v[40:43], v[76:79], v[182:185], v[40:43]
	v_mfma_f32_16x16x32_bf16 v[28:31], v[68:71], v[190:193], v[28:31]
	v_mfma_f32_16x16x32_bf16 v[24:27], v[76:79], v[190:193], v[24:27]
	v_mfma_f32_16x16x32_bf16 v[12:15], v[68:71], v[198:201], v[12:15]
	v_mfma_f32_16x16x32_bf16 v[8:11], v[76:79], v[198:201], v[8:11]
	s_nop 0
	s_nop 0
	v_mfma_f32_16x16x32_bf16 v[52:55], v[144:147], v[160:163], v[52:55]
	v_mfma_f32_16x16x32_bf16 v[48:51], v[152:155], v[160:163], v[48:51]
	v_mfma_f32_16x16x32_bf16 v[36:39], v[144:147], v[168:171], v[36:39]
	v_mfma_f32_16x16x32_bf16 v[32:35], v[152:155], v[168:171], v[32:35]
	v_mfma_f32_16x16x32_bf16 v[20:23], v[144:147], v[186:189], v[20:23]
	v_mfma_f32_16x16x32_bf16 v[16:19], v[152:155], v[186:189], v[16:19]
	v_mfma_f32_16x16x32_bf16 v[4:7], v[144:147], v[194:197], v[4:7]
	v_mfma_f32_16x16x32_bf16 v[0:3], v[152:155], v[194:197], v[0:3]
	v_mfma_f32_16x16x32_bf16 v[52:55], v[148:151], v[164:167], v[52:55]
	v_mfma_f32_16x16x32_bf16 v[48:51], v[156:159], v[164:167], v[48:51]
	v_mfma_f32_16x16x32_bf16 v[36:39], v[148:151], v[182:185], v[36:39]
	v_mfma_f32_16x16x32_bf16 v[32:35], v[156:159], v[182:185], v[32:35]
	v_mfma_f32_16x16x32_bf16 v[20:23], v[148:151], v[190:193], v[20:23]
	v_mfma_f32_16x16x32_bf16 v[16:19], v[156:159], v[190:193], v[16:19]
	v_mfma_f32_16x16x32_bf16 v[4:7], v[148:151], v[198:201], v[4:7]
	v_mfma_f32_16x16x32_bf16 v[0:3], v[156:159], v[198:201], v[0:3]
	s_nop 0
	s_barrier
	s_add_i32 s59, s59, 2
	s_add_u32 s40, s40, 0x100
	s_addc_u32 s41, s41, 0
	s_add_u32 s43, s43, 0x100
	s_addc_u32 s58, s58, 0
	s_cmp_gt_u32 s59, 61
	s_cbranch_scc0 .LBB0_1865
	s_and_b64 vcc, exec, s[18:19]
	s_cbranch_vccz .LBB0_1868
	s_barrier

; #define PG8_STAGE(bufoff, gbase, voff) do { _Pragma("unroll") for (int _i = 0; _i < 2; ++_i) \
;         __builtin_amdgcn_global_load_lds((const unsigned*)((const char*)(gbase) + (voff)[_i]), (PG8_LAS unsigned*)(lds + (bufoff) + ldsw + _i * 8192), 16, 0, 0); } while (0)
; #define PG8_LDA(dst, b, h) do { _Pragma("unroll") for (int m = 0; m < 4; ++m) _Pragma("unroll") for (int k = 0; k < 2; ++k) dst[m][k] = *(const PG8_LAS bf16x8*)(lds + PG8_SA(b, h) + aoff + m * 2048 + k * 1024); } while (0)
; #define PG8_LDB(dst, b, h) do { _Pragma("unroll") for (int n = 0; n < 2; ++n) _Pragma("unroll") for (int k = 0; k < 2; ++k) dst[n][k] = *(const PG8_LAS bf16x8*)(lds + PG8_SB(b, h) + boff + n * 2048 + k * 1024); } while (0)
; #define PG8_MMA(ai, bj, At, Bt) do { __builtin_amdgcn_s_setprio(1); _Pragma("unroll") for (int m = 0; m < 4; ++m) _Pragma("unroll") for (int n = 0; n < 2; ++n) _Pragma("unroll") for (int k = 0; k < 2; ++k) \
;         acc[ai][bj][m][n] = __builtin_amdgcn_mfma_f32_16x16x32_bf16(Bt[n][k], At[m][k], acc[ai][bj][m][n], 0, 0, 0); __builtin_amdgcn_s_setprio(0); } while (0)
; #define PG8_WAIT_V(n) asm volatile("s_waitcnt vmcnt(" #n ")" ::: "memory")
; #define PG8_WAIT_L(n) asm volatile("s_waitcnt lgkmcnt(" #n ")" ::: "memory")
; #define PG8_BAR __builtin_amdgcn_s_barrier()
; #define PG8_SCHED __builtin_amdgcn_sched_barrier(0)
; template <class Epi, class Sched>
; __device__ __forceinline__ void gemm_phase(PG8_LAS unsigned char* lds, const Gemm g, const Sched& S, const Epi& E, const int tid) {
;     ...
;         const char* nA = has_next ? (const char*)g.A + (size_t)nxt.pm * tstepA + (size_t)nxt.pn * g.a_pn_off + S.koff(nxt) : cA; const char* nB = has_next ? (const char*)g.Bt + (size_t)nxt.pn * tstepB + S.koff(nxt) : cB;
;         const int ntc = S.nt(cur, nt);
;         for (int t = 0; t < ntc; t += 2) {
;             const bool last = (t == ntc - 2);
;             const char* a1 = cA + (size_t)(t + 1) * kstep;
;             const char* a2 = last ? nA : cA + (size_t)(t + 2) * kstep; const char* b2 = last ? nB : cB + (size_t)(t + 2) * kstep;
;             const char* a3 = a2 + kstep; const char* b3 = b2 + kstep;
;             PG8_LDB(B0, 0, 0); PG8_LDB(B1, 0, 1); PG8_SCHED; PG8_LDA(At, 0, 0); PG8_STAGE(PG8_SA(1, 1), a1 + hstepA, voffA);
;             PG8_WAIT_V(8); PG8_WAIT_L(0); PG8_BAR; PG8_MMA(0, 0, At, B0); PG8_MMA(0, 1, At, B1); PG8_BAR; PG8_SCHED;
.LBB0_1959:
	s_add_i32 s22, s21, 2
	s_add_u32 s16, s56, 0xfff00080
	s_addc_u32 s23, s57, -1
	s_add_i32 s30, 0, 0x10000
	s_cmp_eq_u32 s8, s21
	s_cselect_b32 s65, s47, s23
	s_cselect_b32 s64, s46, s16
	s_cselect_b32 s63, s49, s20
	s_cselect_b32 s62, s48, s17
	s_add_i32 s16, 0, 0x14000
	v_add_u32_e32 v108, s30, v231
	v_add_u32_e32 v156, s16, v231
	ds_read_b128 v[88:91], v108
	ds_read_b128 v[92:95], v108 offset:1024
	ds_read_b128 v[104:107], v108 offset:2048
	ds_read_b128 v[108:111], v108 offset:3072
	ds_read_b128 v[144:147], v156
	ds_read_b128 v[148:151], v156 offset:1024
	ds_read_b128 v[152:155], v156 offset:2048
	ds_read_b128 v[156:159], v156 offset:3072
	v_lshl_add_u64 v[202:203], s[56:57], 0, v[178:179]
	s_add_i32 m0, s68, 0xc000
	ds_read_b128 v[160:163], v232
	ds_read_b128 v[164:167], v232 offset:1024
	ds_read_b128 v[168:171], v232 offset:2048
	ds_read_b128 v[182:185], v232 offset:3072
	ds_read_b128 v[186:189], v232 offset:4096
	ds_read_b128 v[190:193], v232 offset:5120
	ds_read_b128 v[194:197], v232 offset:6144
	ds_read_b128 v[198:201], v232 offset:7168
	global_load_lds_dwordx4 v[202:203], off
	v_lshl_add_u64 v[202:203], s[56:57], 0, v[180:181]
	s_add_i32 m0, s68, 0xe000
	s_nop 0
	global_load_lds_dwordx4 v[202:203], off
	s_waitcnt vmcnt(8)
	s_waitcnt lgkmcnt(0)
	s_barrier
	s_nop 0
	s_waitcnt lgkmcnt(0)
	v_mfma_f32_16x16x32_bf16 v[140:143], v[88:91], v[160:163], v[140:143]
	v_mfma_f32_16x16x32_bf16 v[136:139], v[104:107], v[160:163], v[136:139]
	v_mfma_f32_16x16x32_bf16 v[124:127], v[88:91], v[168:171], v[124:127]
	v_mfma_f32_16x16x32_bf16 v[120:123], v[104:107], v[168:171], v[120:123]
	v_mfma_f32_16x16x32_bf16 v[100:103], v[88:91], v[186:189], v[100:103]
	v_mfma_f32_16x16x32_bf16 v[96:99], v[104:107], v[186:189], v[96:99]
	v_mfma_f32_16x16x32_bf16 v[76:79], v[88:91], v[194:197], v[76:79]
	v_mfma_f32_16x16x32_bf16 v[72:75], v[104:107], v[194:197], v[72:75]
	v_mfma_f32_16x16x32_bf16 v[140:143], v[92:95], v[164:167], v[140:143]
	v_mfma_f32_16x16x32_bf16 v[136:139], v[108:111], v[164:167], v[136:139]
	v_mfma_f32_16x16x32_bf16 v[124:127], v[92:95], v[182:185], v[124:127]
	v_mfma_f32_16x16x32_bf16 v[120:123], v[108:111], v[182:185], v[120:123]
	v_mfma_f32_16x16x32_bf16 v[100:103], v[92:95], v[190:193], v[100:103]
	v_mfma_f32_16x16x32_bf16 v[96:99], v[108:111], v[190:193], v[96:99]
	v_mfma_f32_16x16x32_bf16 v[76:79], v[92:95], v[198:201], v[76:79]
	v_mfma_f32_16x16x32_bf16 v[72:75], v[108:111], v[198:201], v[72:75]
	s_nop 0
	s_nop 0
	v_mfma_f32_16x16x32_bf16 v[132:135], v[144:147], v[160:163], v[132:135]
	v_mfma_f32_16x16x32_bf16 v[128:131], v[152:155], v[160:163], v[128:131]
	v_mfma_f32_16x16x32_bf16 v[116:119], v[144:147], v[168:171], v[116:119]
	v_mfma_f32_16x16x32_bf16 v[112:115], v[152:155], v[168:171], v[112:115]
	v_mfma_f32_16x16x32_bf16 v[84:87], v[144:147], v[186:189], v[84:87]
	v_mfma_f32_16x16x32_bf16 v[80:83], v[152:155], v[186:189], v[80:83]
	v_mfma_f32_16x16x32_bf16 v[68:71], v[144:147], v[194:197], v[68:71]
	v_mfma_f32_16x16x32_bf16 v[64:67], v[152:155], v[194:197], v[64:67]
	v_mfma_f32_16x16x32_bf16 v[132:135], v[148:151], v[164:167], v[132:135]
	v_mfma_f32_16x16x32_bf16 v[128:131], v[156:159], v[164:167], v[128:131]
	v_mfma_f32_16x16x32_bf16 v[116:119], v[148:151], v[182:185], v[116:119]
	v_mfma_f32_16x16x32_bf16 v[112:115], v[156:159], v[182:185], v[112:115]
	v_mfma_f32_16x16x32_bf16 v[84:87], v[148:151], v[190:193], v[84:87]
	v_mfma_f32_16x16x32_bf16 v[80:83], v[156:159], v[190:193], v[80:83]
	v_mfma_f32_16x16x32_bf16 v[68:71], v[148:151], v[198:201], v[68:71]
	v_mfma_f32_16x16x32_bf16 v[64:67], v[156:159], v[198:201], v[64:67]
	s_nop 0
	s_barrier
	s_add_i32 s21, s30, s51
	v_lshl_add_u64 v[202:203], s[62:63], 0, v[212:213]
	s_mov_b32 m0, s21
	ds_read_b128 v[160:163], v232 offset:16384
	ds_read_b128 v[164:167], v232 offset:17408
	ds_read_b128 v[168:171], v232 offset:18432
	ds_read_b128 v[182:185], v232 offset:19456
	ds_read_b128 v[186:189], v232 offset:20480
	ds_read_b128 v[190:193], v232 offset:21504
	ds_read_b128 v[194:197], v232 offset:22528
	ds_read_b128 v[198:201], v232 offset:23552
	global_load_lds_dwordx4 v[202:203], off
	s_add_i32 m0, s21, 0x2000
	s_add_u32 s52, s62, 0x100000
	v_lshl_add_u64 v[204:205], s[62:63], 0, v[176:177]
	s_addc_u32 s53, s63, 0
	s_add_i32 s16, s16, s51
	global_load_lds_dwordx4 v[204:205], off
	v_lshl_add_u64 v[206:207], s[52:53], 0, v[212:213]
	s_mov_b32 m0, s16
	v_lshl_add_u64 v[208:209], s[64:65], 0, v[174:175]
	global_load_lds_dwordx4 v[206:207], off
	v_lshl_add_u64 v[206:207], s[52:53], 0, v[176:177]
	s_add_i32 m0, s16, 0x2000
	s_nop 0
	global_load_lds_dwordx4 v[206:207], off
	v_lshl_add_u64 v[206:207], s[64:65], 0, v[172:173]
	s_mov_b32 m0, s68
	s_nop 0
	global_load_lds_dwordx4 v[206:207], off
	s_mov_b32 m0, s69
	s_nop 0
	global_load_lds_dwordx4 v[208:209], off
	s_waitcnt vmcnt(8)
	s_waitcnt lgkmcnt(0)
	s_barrier
; #define PG8_STAGE(bufoff, gbase, voff) do { _Pragma("unroll") for (int _i = 0; _i < 2; ++_i) \
;         __builtin_amdgcn_global_load_lds((const unsigned*)((const char*)(gbase) + (voff)[_i]), (PG8_LAS unsigned*)(lds + (bufoff) + ldsw + _i * 8192), 16, 0, 0); } while (0)
; #define PG8_LDA(dst, b, h) do { _Pragma("unroll") for (int m = 0; m < 4; ++m) _Pragma("unroll") for (int k = 0; k < 2; ++k) dst[m][k] = *(const PG8_LAS bf16x8*)(lds + PG8_SA(b, h) + aoff + m * 2048 + k * 1024); } while (0)
; #define PG8_LDB(dst, b, h) do { _Pragma("unroll") for (int n = 0; n < 2; ++n) _Pragma("unroll") for (int k = 0; k < 2; ++k) dst[n][k] = *(const PG8_LAS bf16x8*)(lds + PG8_SB(b, h) + boff + n * 2048 + k * 1024); } while (0)
; #define PG8_MMA(ai, bj, At, Bt) do { __builtin_amdgcn_s_setprio(1); _Pragma("unroll") for (int m = 0; m < 4; ++m) _Pragma("unroll") for (int n = 0; n < 2; ++n) _Pragma("unroll") for (int k = 0; k < 2; ++k) \
;         acc[ai][bj][m][n] = __builtin_amdgcn_mfma_f32_16x16x32_bf16(Bt[n][k], At[m][k], acc[ai][bj][m][n], 0, 0, 0); __builtin_amdgcn_s_setprio(0); } while (0)
; #define PG8_WAIT_V(n) asm volatile("s_waitcnt vmcnt(" #n ")" ::: "memory")
; #define PG8_WAIT_L(n) asm volatile("s_waitcnt lgkmcnt(" #n ")" ::: "memory")
; #define PG8_BAR __builtin_amdgcn_s_barrier()
; #define PG8_SCHED __builtin_amdgcn_sched_barrier(0)
; template <class Epi, class Sched>
; __device__ __forceinline__ void gemm_phase(PG8_LAS unsigned char* lds, const Gemm g, const Sched& S, const Epi& E, const int tid) {
;     ...
;             PG8_LDA(At, 0, 1); PG8_STAGE(PG8_SB(0, 0), b2, voffB); PG8_STAGE(PG8_SB(0, 1), b2 + hstepB, voffB); PG8_STAGE(PG8_SA(0, 0), a2, voffA);
;             PG8_WAIT_V(8); PG8_WAIT_L(0); PG8_BAR; PG8_MMA(1, 0, At, B0); PG8_MMA(1, 1, At, B1); PG8_BAR; PG8_SCHED;
;             PG8_LDB(B0, 1, 0); PG8_LDB(B1, 1, 1); PG8_SCHED; PG8_LDA(At, 1, 0); PG8_STAGE(PG8_SA(0, 1), a2 + hstepA, voffA);
;             PG8_WAIT_V(8); PG8_WAIT_L(0); PG8_BAR; PG8_MMA(0, 0, At, B0); PG8_MMA(0, 1, At, B1); PG8_BAR; PG8_SCHED;
	s_nop 0
	s_waitcnt lgkmcnt(0)
	v_mfma_f32_16x16x32_bf16 v[60:63], v[88:91], v[160:163], v[60:63]
	v_mfma_f32_16x16x32_bf16 v[56:59], v[104:107], v[160:163], v[56:59]
	v_mfma_f32_16x16x32_bf16 v[44:47], v[88:91], v[168:171], v[44:47]
	v_mfma_f32_16x16x32_bf16 v[40:43], v[104:107], v[168:171], v[40:43]
	v_mfma_f32_16x16x32_bf16 v[28:31], v[88:91], v[186:189], v[28:31]
	v_mfma_f32_16x16x32_bf16 v[24:27], v[104:107], v[186:189], v[24:27]
	v_mfma_f32_16x16x32_bf16 v[12:15], v[88:91], v[194:197], v[12:15]
	v_mfma_f32_16x16x32_bf16 v[8:11], v[104:107], v[194:197], v[8:11]
	v_mfma_f32_16x16x32_bf16 v[60:63], v[92:95], v[164:167], v[60:63]
	v_mfma_f32_16x16x32_bf16 v[56:59], v[108:111], v[164:167], v[56:59]
	v_mfma_f32_16x16x32_bf16 v[44:47], v[92:95], v[182:185], v[44:47]
	v_mfma_f32_16x16x32_bf16 v[40:43], v[108:111], v[182:185], v[40:43]
	v_mfma_f32_16x16x32_bf16 v[28:31], v[92:95], v[190:193], v[28:31]
	v_mfma_f32_16x16x32_bf16 v[24:27], v[108:111], v[190:193], v[24:27]
	v_mfma_f32_16x16x32_bf16 v[12:15], v[92:95], v[198:201], v[12:15]
	v_mfma_f32_16x16x32_bf16 v[8:11], v[108:111], v[198:201], v[8:11]
	s_nop 0
	s_nop 0
	v_mfma_f32_16x16x32_bf16 v[52:55], v[144:147], v[160:163], v[52:55]
	v_mfma_f32_16x16x32_bf16 v[48:51], v[152:155], v[160:163], v[48:51]
	v_mfma_f32_16x16x32_bf16 v[36:39], v[144:147], v[168:171], v[36:39]
	v_mfma_f32_16x16x32_bf16 v[32:35], v[152:155], v[168:171], v[32:35]
	v_mfma_f32_16x16x32_bf16 v[20:23], v[144:147], v[186:189], v[20:23]
	v_mfma_f32_16x16x32_bf16 v[16:19], v[152:155], v[186:189], v[16:19]
	v_mfma_f32_16x16x32_bf16 v[4:7], v[144:147], v[194:197], v[4:7]
	v_mfma_f32_16x16x32_bf16 v[0:3], v[152:155], v[194:197], v[0:3]
	v_mfma_f32_16x16x32_bf16 v[52:55], v[148:151], v[164:167], v[52:55]
	v_mfma_f32_16x16x32_bf16 v[48:51], v[156:159], v[164:167], v[48:51]
	v_mfma_f32_16x16x32_bf16 v[36:39], v[148:151], v[182:185], v[36:39]
	v_mfma_f32_16x16x32_bf16 v[32:35], v[156:159], v[182:185], v[32:35]
	v_mfma_f32_16x16x32_bf16 v[20:23], v[148:151], v[190:193], v[20:23]
	v_mfma_f32_16x16x32_bf16 v[16:19], v[156:159], v[190:193], v[16:19]
	v_mfma_f32_16x16x32_bf16 v[4:7], v[148:151], v[198:201], v[4:7]
	v_mfma_f32_16x16x32_bf16 v[0:3], v[156:159], v[198:201], v[0:3]
	s_nop 0
	s_barrier
	s_add_i32 s16, 0, 0x18000
	s_add_i32 s21, 0, 0x1c000
	v_add_u32_e32 v108, s16, v231
	v_add_u32_e32 v156, s21, v231
	ds_read_b128 v[88:91], v108
	ds_read_b128 v[92:95], v108 offset:1024
	ds_read_b128 v[104:107], v108 offset:2048
	ds_read_b128 v[108:111], v108 offset:3072
	ds_read_b128 v[144:147], v156
	ds_read_b128 v[148:151], v156 offset:1024
	ds_read_b128 v[152:155], v156 offset:2048
	ds_read_b128 v[156:159], v156 offset:3072
	s_add_u32 s52, s64, 0x100000
	s_addc_u32 s53, s65, 0
	s_mov_b32 m0, s71
	v_lshl_add_u64 v[210:211], s[52:53], 0, v[172:173]
	ds_read_b128 v[160:163], v232 offset:32768
	ds_read_b128 v[164:167], v232 offset:33792
	ds_read_b128 v[168:171], v232 offset:34816
	ds_read_b128 v[182:185], v232 offset:35840
	ds_read_b128 v[186:189], v232 offset:36864
	ds_read_b128 v[190:193], v232 offset:37888
	ds_read_b128 v[194:197], v232 offset:38912
	ds_read_b128 v[198:201], v232 offset:39936
	global_load_lds_dwordx4 v[210:211], off
	v_lshl_add_u64 v[210:211], s[52:53], 0, v[174:175]
	s_mov_b32 m0, s72
	s_nop 0
	global_load_lds_dwordx4 v[210:211], off
	s_waitcnt vmcnt(8)
	s_waitcnt lgkmcnt(0)
	s_barrier
	s_nop 0
	s_waitcnt lgkmcnt(0)
	v_mfma_f32_16x16x32_bf16 v[140:143], v[88:91], v[160:163], v[140:143]
	v_mfma_f32_16x16x32_bf16 v[136:139], v[104:107], v[160:163], v[136:139]
	v_mfma_f32_16x16x32_bf16 v[124:127], v[88:91], v[168:171], v[124:127]
	v_mfma_f32_16x16x32_bf16 v[120:123], v[104:107], v[168:171], v[120:123]
	v_mfma_f32_16x16x32_bf16 v[100:103], v[88:91], v[186:189], v[100:103]
	v_mfma_f32_16x16x32_bf16 v[96:99], v[104:107], v[186:189], v[96:99]
	v_mfma_f32_16x16x32_bf16 v[76:79], v[88:91], v[194:197], v[76:79]
	v_mfma_f32_16x16x32_bf16 v[72:75], v[104:107], v[194:197], v[72:75]
	v_mfma_f32_16x16x32_bf16 v[140:143], v[92:95], v[164:167], v[140:143]
	v_mfma_f32_16x16x32_bf16 v[136:139], v[108:111], v[164:167], v[136:139]
	v_mfma_f32_16x16x32_bf16 v[124:127], v[92:95], v[182:185], v[124:127]
	v_mfma_f32_16x16x32_bf16 v[120:123], v[108:111], v[182:185], v[120:123]
	v_mfma_f32_16x16x32_bf16 v[100:103], v[92:95], v[190:193], v[100:103]
	v_mfma_f32_16x16x32_bf16 v[96:99], v[108:111], v[190:193], v[96:99]
	v_mfma_f32_16x16x32_bf16 v[76:79], v[92:95], v[198:201], v[76:79]
	v_mfma_f32_16x16x32_bf16 v[72:75], v[108:111], v[198:201], v[72:75]
	s_nop 0
	s_nop 0
	v_mfma_f32_16x16x32_bf16 v[132:135], v[144:147], v[160:163], v[132:135]
	v_mfma_f32_16x16x32_bf16 v[128:131], v[152:155], v[160:163], v[128:131]
	v_mfma_f32_16x16x32_bf16 v[116:119], v[144:147], v[168:171], v[116:119]
	v_mfma_f32_16x16x32_bf16 v[112:115], v[152:155], v[168:171], v[112:115]
	v_mfma_f32_16x16x32_bf16 v[84:87], v[144:147], v[186:189], v[84:87]
	v_mfma_f32_16x16x32_bf16 v[80:83], v[152:155], v[186:189], v[80:83]
	v_mfma_f32_16x16x32_bf16 v[68:71], v[144:147], v[194:197], v[68:71]
	v_mfma_f32_16x16x32_bf16 v[64:67], v[152:155], v[194:197], v[64:67]
	v_mfma_f32_16x16x32_bf16 v[132:135], v[148:151], v[164:167], v[132:135]
	v_mfma_f32_16x16x32_bf16 v[128:131], v[156:159], v[164:167], v[128:131]
	v_mfma_f32_16x16x32_bf16 v[116:119], v[148:151], v[182:185], v[116:119]
	v_mfma_f32_16x16x32_bf16 v[112:115], v[156:159], v[182:185], v[112:115]
	v_mfma_f32_16x16x32_bf16 v[84:87], v[148:151], v[190:193], v[84:87]
	v_mfma_f32_16x16x32_bf16 v[80:83], v[156:159], v[190:193], v[80:83]
	v_mfma_f32_16x16x32_bf16 v[68:71], v[148:151], v[198:201], v[68:71]
	v_mfma_f32_16x16x32_bf16 v[64:67], v[156:159], v[198:201], v[64:67]
	s_nop 0
	s_barrier
; #define PG8_STAGE(bufoff, gbase, voff) do { _Pragma("unroll") for (int _i = 0; _i < 2; ++_i) \
;         __builtin_amdgcn_global_load_lds((const unsigned*)((const char*)(gbase) + (voff)[_i]), (PG8_LAS unsigned*)(lds + (bufoff) + ldsw + _i * 8192), 16, 0, 0); } while (0)
; #define PG8_LDA(dst, b, h) do { _Pragma("unroll") for (int m = 0; m < 4; ++m) _Pragma("unroll") for (int k = 0; k < 2; ++k) dst[m][k] = *(const PG8_LAS bf16x8*)(lds + PG8_SA(b, h) + aoff + m * 2048 + k * 1024); } while (0)
; #define PG8_MMA(ai, bj, At, Bt) do { __builtin_amdgcn_s_setprio(1); _Pragma("unroll") for (int m = 0; m < 4; ++m) _Pragma("unroll") for (int n = 0; n < 2; ++n) _Pragma("unroll") for (int k = 0; k < 2; ++k) \
;         acc[ai][bj][m][n] = __builtin_amdgcn_mfma_f32_16x16x32_bf16(Bt[n][k], At[m][k], acc[ai][bj][m][n], 0, 0, 0); __builtin_amdgcn_s_setprio(0); } while (0)
; #define PG8_WAIT_V(n) asm volatile("s_waitcnt vmcnt(" #n ")" ::: "memory")
; #define PG8_WAIT_L(n) asm volatile("s_waitcnt lgkmcnt(" #n ")" ::: "memory")
; #define PG8_BAR __builtin_amdgcn_s_barrier()
; #define PG8_SCHED __builtin_amdgcn_sched_barrier(0)
; template <class Epi, class Sched>
; __device__ __forceinline__ void gemm_phase(PG8_LAS unsigned char* lds, const Gemm g, const Sched& S, const Epi& E, const int tid) {
;     ...
;             PG8_LDA(At, 1, 1); PG8_STAGE(PG8_SB(1, 0), b3, voffB); PG8_STAGE(PG8_SB(1, 1), b3 + hstepB, voffB); PG8_STAGE(PG8_SA(1, 0), a3, voffA);
;             PG8_WAIT_V(8); PG8_WAIT_L(0); PG8_BAR; PG8_MMA(1, 0, At, B0); PG8_MMA(1, 1, At, B1); PG8_BAR; PG8_SCHED;
;         }
;         if (wr == 0) PG8_BAR;
;         E(acc, cur, wr, wc, fr, fq);
	s_add_i32 s16, s16, s51
	v_lshl_add_u64 v[202:203], v[202:203], 0, s[10:11]
	s_mov_b32 m0, s16
	ds_read_b128 v[160:163], v232 offset:49152
	ds_read_b128 v[164:167], v232 offset:50176
	ds_read_b128 v[168:171], v232 offset:51200
	ds_read_b128 v[182:185], v232 offset:52224
	ds_read_b128 v[186:189], v232 offset:53248
	ds_read_b128 v[190:193], v232 offset:54272
	ds_read_b128 v[194:197], v232 offset:55296
	ds_read_b128 v[198:201], v232 offset:56320
	global_load_lds_dwordx4 v[202:203], off
	s_add_i32 m0, s16, 0x2000
	s_add_u32 s52, s62, 0x100080
	v_lshl_add_u64 v[202:203], v[204:205], 0, s[10:11]
	s_addc_u32 s53, s63, 0
	s_add_i32 s16, s21, s51
	global_load_lds_dwordx4 v[202:203], off
	v_lshl_add_u64 v[202:203], s[52:53], 0, v[212:213]
	s_mov_b32 m0, s16
	s_nop 0
	global_load_lds_dwordx4 v[202:203], off
	v_lshl_add_u64 v[202:203], s[52:53], 0, v[176:177]
	s_add_i32 m0, s16, 0x2000
	s_nop 0
	global_load_lds_dwordx4 v[202:203], off
	v_lshl_add_u64 v[202:203], v[206:207], 0, s[10:11]
	s_mov_b32 m0, s89
	s_nop 0
	global_load_lds_dwordx4 v[202:203], off
	v_lshl_add_u64 v[202:203], v[208:209], 0, s[10:11]
	s_mov_b32 m0, s90
	s_nop 0
	global_load_lds_dwordx4 v[202:203], off
	s_waitcnt vmcnt(8)
	s_waitcnt lgkmcnt(0)
	s_barrier
	s_nop 0
	s_waitcnt lgkmcnt(0)
	v_mfma_f32_16x16x32_bf16 v[60:63], v[88:91], v[160:163], v[60:63]
	v_mfma_f32_16x16x32_bf16 v[56:59], v[104:107], v[160:163], v[56:59]
	v_mfma_f32_16x16x32_bf16 v[44:47], v[88:91], v[168:171], v[44:47]
	v_mfma_f32_16x16x32_bf16 v[40:43], v[104:107], v[168:171], v[40:43]
	v_mfma_f32_16x16x32_bf16 v[28:31], v[88:91], v[186:189], v[28:31]
	v_mfma_f32_16x16x32_bf16 v[24:27], v[104:107], v[186:189], v[24:27]
	v_mfma_f32_16x16x32_bf16 v[12:15], v[88:91], v[194:197], v[12:15]
	v_mfma_f32_16x16x32_bf16 v[8:11], v[104:107], v[194:197], v[8:11]
	v_mfma_f32_16x16x32_bf16 v[60:63], v[92:95], v[164:167], v[60:63]
	v_mfma_f32_16x16x32_bf16 v[56:59], v[108:111], v[164:167], v[56:59]
	v_mfma_f32_16x16x32_bf16 v[44:47], v[92:95], v[182:185], v[44:47]
	v_mfma_f32_16x16x32_bf16 v[40:43], v[108:111], v[182:185], v[40:43]
	v_mfma_f32_16x16x32_bf16 v[28:31], v[92:95], v[190:193], v[28:31]
	v_mfma_f32_16x16x32_bf16 v[24:27], v[108:111], v[190:193], v[24:27]
	v_mfma_f32_16x16x32_bf16 v[12:15], v[92:95], v[198:201], v[12:15]
	v_mfma_f32_16x16x32_bf16 v[8:11], v[108:111], v[198:201], v[8:11]
	s_nop 0
	s_nop 0
	v_mfma_f32_16x16x32_bf16 v[52:55], v[144:147], v[160:163], v[52:55]
	v_mfma_f32_16x16x32_bf16 v[48:51], v[152:155], v[160:163], v[48:51]
	v_mfma_f32_16x16x32_bf16 v[36:39], v[144:147], v[168:171], v[36:39]
	v_mfma_f32_16x16x32_bf16 v[32:35], v[152:155], v[168:171], v[32:35]
	v_mfma_f32_16x16x32_bf16 v[20:23], v[144:147], v[186:189], v[20:23]
	v_mfma_f32_16x16x32_bf16 v[16:19], v[152:155], v[186:189], v[16:19]
	v_mfma_f32_16x16x32_bf16 v[4:7], v[144:147], v[194:197], v[4:7]
	v_mfma_f32_16x16x32_bf16 v[0:3], v[152:155], v[194:197], v[0:3]
	v_mfma_f32_16x16x32_bf16 v[52:55], v[148:151], v[164:167], v[52:55]
	v_mfma_f32_16x16x32_bf16 v[48:51], v[156:159], v[164:167], v[48:51]
	v_mfma_f32_16x16x32_bf16 v[36:39], v[148:151], v[182:185], v[36:39]
	v_mfma_f32_16x16x32_bf16 v[32:35], v[156:159], v[182:185], v[32:35]
	v_mfma_f32_16x16x32_bf16 v[20:23], v[148:151], v[190:193], v[20:23]
	v_mfma_f32_16x16x32_bf16 v[16:19], v[156:159], v[190:193], v[16:19]
	v_mfma_f32_16x16x32_bf16 v[4:7], v[148:151], v[198:201], v[4:7]
	v_mfma_f32_16x16x32_bf16 v[0:3], v[156:159], v[198:201], v[0:3]
	s_nop 0
	s_barrier
	s_add_u32 s56, s56, 0x100
	s_addc_u32 s57, s57, 0
	s_add_u32 s17, s17, 0x100
	s_addc_u32 s20, s20, 0
	s_cmp_ge_u32 s22, s3
	s_mov_b32 s21, s22
	s_cbranch_scc0 .LBB0_1959
	s_and_b64 vcc, exec, s[18:19]
	s_cbranch_vccz .LBB0_1980
	s_barrier
	s_lshl_b32 s56, s40, 8
	s_mov_b64 s[62:63], -1
	s_and_b64 vcc, exec, s[60:61]
	s_cbranch_vccnz .LBB0_1981
